# adds FFT filter-row batched loads, 16-row XOR swizzle for attention K/Q LDS tiles (diff+NA), FFT packed-f32 de-pack with dead halves dropped, wave-uniform T5 bias class branches
# speedup vs baseline: 1.0156x; 1.0156x over previous
; #define AIN(i) ((const float*)ldarg(i))
; #define G lgrid()
; #define bx lbid()
; __global__ void __launch_bounds__(NTHR, 2) mega_fwd(Args a_unused) {
;     ...
;     const size_t ZS = (size_t)T_TOK * 1024;
;     const bf16 *QA = Z, *KA = Z + ZS, *VA = Z + 2 * ZS, *QB = Z + 3 * ZS, *KB = Z + 4 * ZS, *VB = Z + 5 * ZS;
;     bf16* O = (bf16*)AOUT;
;     const int vcu = (G % 8 == 0) ? (bx % 8) * (G / 8) + bx / 8 : bx;
;     float lam;
;     { const float* lv = AIN(11); const float s1 = wave_sum(lv[lane] * lv[64 + lane]), s2 = wave_sum(lv[128 + lane] * lv[192 + lane]); lam = expf(s1) - expf(s2) + 0.2f; }
;     ...
; #pragma unroll 1
;     for (int u = vcu; u < 1536; u += G) {
;       int s, h, qb, L;
;       if (u < 1024) { qb = u & 15; const int bh = u >> 4; h = bh & 7; s = 8 + (bh >> 3); L = 4096; }
;       else { const int v = u - 1024; qb = v & 7; const int bh = v >> 3; h = bh & 7; s = bh >> 3; L = 2048; }
;       const size_t mbase = s < 8 ? (size_t)s * 2048 : (size_t)TP + (size_t)(s - 8) * 4096;
;       att::attn_unit<true>(QA + (mbase + 256 * qb) * 1024 + 128 * h, KA + mbase * 1024 + 128 * h, VA + mbase * 1024 + 128 * h,
;                            O + (mbase + 256 * qb) * 2048 + 128 * h, 0, L / 64, 256 * qb, 0, lam, AIN(4), h, AIN(12), (char*)lds);
.LBB0_258:
	s_mov_b64 s[6:7], s[0:1]
	s_load_dwordx2 s[6:7], s[6:7], 0x58
	v_mov_b32_e32 v0, v208
	v_mov_b32_e32 v1, v208
	v_and_b32_e32 v0, 63, v0
	v_lshlrev_b32_e32 v0, 2, v0
	s_waitcnt lgkmcnt(0)
	global_load_dword v0, v0, s[6:7]
	v_mov_b32_e32 v2, v208
	v_and_b32_e32 v1, 63, v1
	v_lshlrev_b32_e32 v1, 2, v1
	global_load_dword v1, v1, s[6:7] offset:256
	v_mov_b32_e32 v3, v208
	v_and_b32_e32 v2, 63, v2
	v_lshlrev_b32_e32 v2, 2, v2
	global_load_dword v2, v2, s[6:7] offset:512
	v_mbcnt_lo_u32_b32 v4, -1, 0
	v_and_b32_e32 v3, 63, v3
	v_lshlrev_b32_e32 v3, 2, v3
	global_load_dword v3, v3, s[6:7] offset:768
	v_mbcnt_hi_u32_b32 v4, -1, v4
	v_and_b32_e32 v5, 64, v4
	v_xor_b32_e32 v6, 1, v4
	v_add_u32_e32 v5, 64, v5
	v_cmp_lt_i32_e32 vcc, v6, v5
	v_xor_b32_e32 v7, 2, v4
	v_xor_b32_e32 v8, 4, v4
	v_cndmask_b32_e32 v6, v4, v6, vcc
	v_lshlrev_b32_e32 v154, 2, v6
	v_cmp_lt_i32_e32 vcc, v7, v5
	v_xor_b32_e32 v9, 8, v4
	v_xor_b32_e32 v10, 16, v4
	v_cndmask_b32_e32 v7, v4, v7, vcc
	v_lshlrev_b32_e32 v155, 2, v7
	v_cmp_lt_i32_e32 vcc, v8, v5
	s_cmpk_gt_i32 s33, 0x5ff
	s_mov_b32 s19, 0
	v_cndmask_b32_e32 v7, v4, v8, vcc
	v_lshlrev_b32_e32 v156, 2, v7
	v_cmp_lt_i32_e32 vcc, v9, v5
	s_waitcnt vmcnt(2)
	v_mul_f32_e32 v6, v0, v1
	ds_bpermute_b32 v6, v154, v6
	s_waitcnt lgkmcnt(0)
	v_fmac_f32_e32 v6, v0, v1
	ds_bpermute_b32 v1, v155, v6
	s_waitcnt vmcnt(0)
	v_mul_f32_e32 v0, v2, v3
	ds_bpermute_b32 v0, v154, v0
	s_waitcnt lgkmcnt(1)
	v_add_f32_e32 v1, v6, v1
	v_cndmask_b32_e32 v6, v4, v9, vcc
	v_lshlrev_b32_e32 v157, 2, v6
	v_cmp_lt_i32_e32 vcc, v10, v5
	s_waitcnt lgkmcnt(0)
	v_fmac_f32_e32 v0, v2, v3
	ds_bpermute_b32 v3, v155, v0
	ds_bpermute_b32 v2, v156, v1
	v_cndmask_b32_e32 v6, v4, v10, vcc
	v_lshlrev_b32_e32 v158, 2, v6
	v_xor_b32_e32 v6, 32, v4
	s_waitcnt lgkmcnt(1)
	v_add_f32_e32 v0, v0, v3
	s_waitcnt lgkmcnt(0)
	v_add_f32_e32 v1, v1, v2
	ds_bpermute_b32 v3, v156, v0
	ds_bpermute_b32 v2, v157, v1
	v_cmp_lt_i32_e32 vcc, v6, v5
	s_waitcnt lgkmcnt(1)
	v_add_f32_e32 v0, v0, v3
	s_waitcnt lgkmcnt(0)
	v_add_f32_e32 v1, v1, v2
	ds_bpermute_b32 v3, v157, v0
	ds_bpermute_b32 v2, v158, v1
	s_waitcnt lgkmcnt(1)
	v_add_f32_e32 v0, v0, v3
	s_waitcnt lgkmcnt(0)
	v_add_f32_e32 v2, v1, v2
	ds_bpermute_b32 v1, v158, v0
	v_cndmask_b32_e32 v3, v4, v6, vcc
	v_lshlrev_b32_e32 v4, 2, v3
	ds_bpermute_b32 v3, v4, v2
	s_waitcnt lgkmcnt(1)
	v_add_f32_e32 v0, v0, v1
	ds_bpermute_b32 v1, v4, v0
	s_cbranch_scc1 .LBB0_448
	s_waitcnt lgkmcnt(1)
	v_add_f32_e32 v2, v2, v3
	s_mov_b32 s2, 0x3fb8aa3b
	v_mul_f32_e32 v3, 0x3fb8aa3b, v2
	v_fma_f32 v4, v2, s2, -v3
	v_rndne_f32_e32 v5, v3
	v_fmac_f32_e32 v4, 0x32a5705f, v2
	v_sub_f32_e32 v3, v3, v5
	v_add_f32_e32 v3, v3, v4
	v_exp_f32_e32 v3, v3
	v_cvt_i32_f32_e32 v4, v5
	s_waitcnt lgkmcnt(0)
	v_add_f32_e32 v0, v0, v1
	v_mul_f32_e32 v1, 0x3fb8aa3b, v0
	v_rndne_f32_e32 v5, v1
	v_ldexp_f32 v3, v3, v4
	v_fma_f32 v4, v0, s2, -v1
	v_fmac_f32_e32 v4, 0x32a5705f, v0
	v_sub_f32_e32 v1, v1, v5
	v_add_f32_e32 v1, v1, v4
	v_exp_f32_e32 v1, v1
	v_cvt_i32_f32_e32 v4, v5
	s_add_u32 s23, s4, 0x19a00000
	s_mov_b32 s4, 0xc2ce8ed0
	s_addc_u32 s25, s5, 0
	v_cmp_ngt_f32_e32 vcc, s4, v2
	s_mov_b32 s5, 0x42b17218
	v_mov_b32_e32 v5, 0x7f800000
	v_cndmask_b32_e32 v3, 0, v3, vcc
	v_cmp_nlt_f32_e32 vcc, s5, v2
	v_ldexp_f32 v1, v1, v4
	s_add_u32 s40, s8, 0x1fa00000
	v_cndmask_b32_e32 v2, v5, v3, vcc
	v_cmp_ngt_f32_e32 vcc, s4, v0
	s_addc_u32 s41, s9, 0
	s_add_u32 s44, s10, 0x25a00000
	v_cndmask_b32_e32 v1, 0, v1, vcc
	v_cmp_nlt_f32_e32 vcc, s5, v0
	s_addc_u32 s45, s11, 0
	s_add_u32 s20, s8, 0x1fa20000
	v_cndmask_b32_e32 v0, v5, v1, vcc
	v_sub_f32_e32 v0, v2, v0
	v_add_f32_e32 v159, 0x3e4ccccd, v0
	v_cmp_gt_f32_e32 vcc, 0, v159
	s_addc_u32 s21, s9, 0
	s_add_i32 s2, 0, 0x8000
	v_cndmask_b32_e64 v144, -1.0, 1.0, vcc
	s_mov_b32 s46, 0x7f800000
	v_mov_b32_e32 v145, v144
	s_movk_i32 s52, 0x101
	s_movk_i32 s53, 0x1ff
	s_mov_b32 s54, 0x8000
	v_writelane_b32 v255, s2, 1
	s_movk_i32 s55, 0x80
	s_mov_b32 s22, 0x3e000000
	s_mov_b32 s56, 0x800000
	s_mov_b32 s57, 0x3f317217
	s_mov_b32 s58, 0x40317218
	s_mov_b32 s24, 0x41000000
	s_movk_i32 s59, 0x1000
	s_movk_i32 s60, 0xff00
	v_mov_b32_e32 v147, 0
	s_movk_i32 s61, 0xf0
	s_movk_i32 s62, 0x60
	s_movk_i32 s63, 0xa0
	s_movk_i32 s64, 0xc0
	s_movk_i32 s65, 0xe0
	s_mov_b32 s66, 0x10000
	s_movk_i32 s67, 0x9f
	s_movk_i32 s68, 0xff41
	s_mov_b64 s[26:27], 0x20000
	s_mov_b32 s69, 0xbe38aa3b
	s_add_i32 s90, 0, 0x4000
	s_mov_b32 s70, 0x1fa20000
	s_mov_b32 s71, 0x1fa30000
	s_mov_b32 s72, 0x25a20000
	s_mov_b32 s73, 0x25a30000
	v_mov_b32_e32 v160, 0x358637bd
	s_mov_b32 s74, 0xf800000
	v_mov_b32_e32 v161, 0x260
	s_movk_i32 s75, 0x7fff
	s_movk_i32 s76, 0x2000
	s_movk_i32 s77, 0x3000
	s_mov_b32 s78, 0x9000
	s_mov_b32 s79, 0xa000
	s_mov_b32 s80, 0xb000
	s_mov_b32 s81, 0x11000
	s_mov_b32 s82, 0x12000
	s_mov_b32 s83, 0x13000
	s_mov_b32 s84, 0x18000
	s_mov_b32 s85, 0x19000
	s_mov_b32 s86, 0x1a000
	s_mov_b32 s87, 0x1b000
	v_mov_b32_e32 v162, 0x41b17218
	v_mov_b32_e32 v163, 0x100
	s_mov_b32 s88, s33
	s_branch .LBB0_261

; __device__ __forceinline__ int v_st(int k, int c) { const int kk = (k & ~0xC) | ((k & 4) << 1) | ((k & 8) >> 1); return ((kk >> 3) * 4 + (c >> 5)) * 512 + ((kk & 7) * 32 + (c & 31)) * 2; }
; __device__ __forceinline__ int v_rd_base(int lane) { return ((lane & 3) << 3) | (((lane >> 2) & 3) << 6) | (((lane >> 4) & 1) << 5) | (((lane >> 5) & 1) << 8); }
; #define tid ltid()
; template <bool DIFF> ...
;   int tid = threadIdx.x; asm volatile("" : "+v"(tid)); const int wid = tid >> 6, lane = tid & 63, r32 = lane & 31, hi = lane >> 5;
;   char* K_lds = lds; char* V_lds = lds + 16384; float* tab = (float*)(lds + 32768);
;   constexpr float SCALE = DIFF ? 0.125f : 0.08838834764831845f;
;   constexpr float C = SCALE * 1.4426950408889634f;
;   __syncthreads();
;   if (DIFF) { for (int i = tid; i < 257; i += 512) tab[i] = tabg[t5_bucket(i - 128) * 8 + head] * 8.0f; }
;   else      { for (int i = tid; i < 465; i += 512) tab[i] = tabg[head * 465 + i] * 11.313708498984761f; }
;   char* Q_lds = lds + 36864 + wid * 8192;
;   { const bf16* Qw = Qb + (size_t)(wid * 32 + r32) * 1024 + hi * 8;
; #pragma unroll
;     for (int d0 = 0; d0 < 8; ++d0) *reinterpret_cast<bf16x8*>(Q_lds + KSWZ(r32, (d0 * 16 + hi * 8) * 2)) = *reinterpret_cast<const bf16x8*>(Qw + d0 * 16); }
;   const int sr = tid >> 4, sc = (tid & 15) * 8;
;   const int vst0 = v_st(sr, sc), vst1 = v_st(32 + sr, sc), kst0 = KSWZ(sr, sc * 2), kst1 = KSWZ(32 + sr, sc * 2);
;   const int vb0 = (int)(uintptr_t)V_lds + v_rd_base(lane);
;   int rw = 0, rstart = 0;
;   if (!DIFF) { rw = q0 + (wid >> 1); rstart = rw - 4; rstart = rstart < 0 ? 0 : rstart; rstart = rstart > rows - 8 ? rows - 8 : rstart; }
;   const int qbase = q0 + wid * 32;
;   float m1 = -1e30f, l1 = 0.f, m2 = -1e30f, l2 = 0.f;
;   bf16x8 ks0, ks1, vs0, vs1;
.LBB0_274:
	s_or_b64 exec, exec, s[6:7]
	s_lshl_b32 s36, s2, 8
	s_waitcnt lgkmcnt(0)
	s_add_u32 s30, s34, s36
	s_addc_u32 s31, s35, 0
	s_lshl_b64 s[4:5], s[30:31], 11
	v_ashrrev_i32_e32 v1, 6, v0
	s_add_u32 s2, s23, s4
	v_and_b32_e32 v164, 31, v0
	v_lshlrev_b32_e32 v148, 5, v1
	s_addc_u32 s5, s25, s5
	s_lshl_b32 s38, s18, 7
	s_lshl_b32 s37, s18, 8
	v_or_b32_e32 v2, v148, v164
	s_add_u32 s4, s2, s37
	v_ashrrev_i32_e32 v3, 31, v2
	s_addc_u32 s5, s5, 0
	v_lshlrev_b64 v[2:3], 11, v[2:3]
	v_lshl_add_u64 v[2:3], s[4:5], 0, v[2:3]
	s_lshl_b64 s[6:7], s[34:35], 10
	s_lshl_b64 s[4:5], s[34:35], 11
	s_add_u32 s2, s40, s4
	v_ashrrev_i32_e32 v80, 4, v0
	s_addc_u32 s18, s41, s5
	v_lshlrev_b32_e32 v34, 3, v0
	v_ashrrev_i32_e32 v81, 31, v80
	s_add_u32 s34, s2, s37
	v_and_b32_e32 v72, 0x78, v34
	v_lshlrev_b64 v[34:35], 11, v[80:81]
	s_addc_u32 s35, s18, 0
	v_bfe_u32 v165, v0, 5, 1
	v_mov_b32_e32 v75, v147
	v_lshlrev_b32_e32 v74, 1, v72
	v_lshl_add_u64 v[36:37], s[34:35], 0, v[34:35]
	v_lshlrev_b32_e32 v146, 4, v165
	v_lshl_add_u64 v[36:37], v[36:37], 0, v[74:75]
	v_lshl_add_u64 v[30:31], v[2:3], 0, v[146:147]
	v_add_co_u32_e32 v38, vcc, s66, v36
	global_load_dwordx4 v[2:5], v[30:31], off
	global_load_dwordx4 v[6:9], v[30:31], off offset:32
	global_load_dwordx4 v[10:13], v[30:31], off offset:64
	global_load_dwordx4 v[14:17], v[30:31], off offset:96
	global_load_dwordx4 v[18:21], v[30:31], off offset:128
	global_load_dwordx4 v[22:25], v[30:31], off offset:160
	global_load_dwordx4 v[26:29], v[30:31], off offset:192
	s_nop 0
	global_load_dwordx4 v[30:33], v[30:31], off offset:224
	v_addc_co_u32_e32 v39, vcc, 0, v37, vcc
	global_load_dwordx4 v[128:131], v[36:37], off
	global_load_dwordx4 v[132:135], v[38:39], off
	v_lshlrev_b32_e32 v36, 4, v0
	v_lshl_add_u32 v1, v1, 13, 0
	v_lshlrev_b32_e32 v38, 8, v164
	v_and_b32_e32 v75, 63, v0
	v_and_b32_e32 v37, 0xf0, v0
	v_and_b32_e32 v39, 0xf0, v36
	v_bitop3_b32 v40, v165, v0, 15 bitop3:0x78
	v_add_u32_e32 v42, v1, v38
	v_and_b32_e32 v0, 15, v0
	v_add_u32_e32 v86, 32, v80
	v_bitop3_b32 v90, v146, v39, 32 bitop3:0x36
	v_bitop3_b32 v91, v146, v39, 64 bitop3:0x36
	v_bitop3_b32 v92, v146, v39, s62 bitop3:0x36
	v_bitop3_b32 v93, v146, v39, s55 bitop3:0x36
	v_bitop3_b32 v94, v146, v39, s63 bitop3:0x36
	v_bitop3_b32 v95, v146, v39, s64 bitop3:0x36
	v_bitop3_b32 v96, v146, v39, s65 bitop3:0x36
	v_add_u32_e32 v89, s36, v148
	v_bitop3_b32 v98, v146, v36, s61 bitop3:0x78
	v_lshl_add_u32 v36, v40, 4, v42
	v_lshl_add_u64 v[78:79], s[4:5], 0, v[34:35]
	v_lshlrev_b32_e32 v0, 4, v0
	v_lshlrev_b32_e32 v41, 8, v80
	v_lshlrev_b32_e32 v39, 8, v86
	v_add_u32_e32 v40, v42, v90
	v_add_u32_e32 v43, v42, v91
	v_add_u32_e32 v44, v42, v92
	v_add_u32_e32 v45, v42, v93
	v_add_u32_e32 v46, v42, v94
	v_add_u32_e32 v47, v42, v95
	v_add_u32_e32 v42, v42, v96
	v_xad_u32 v37, v74, v37, 0
	v_add_u32_e32 v48, v1, v98
	v_add_u32_e32 v49, v1, v93
	v_lshlrev_b32_e32 v73, 2, v165
	s_lshl_b32 s18, s48, 6
	v_or3_b32 v78, v78, s37, v0
	v_mov_b32_e32 v82, 0
	s_mov_b32 s2, 0
	v_lshlrev_b64 v[76:77], 10, v[80:81]
	v_add_u32_e32 v97, 0, v38
	s_add_i32 s18, s18, 64
	v_sub_u32_e32 v173, 0, v89
	v_lshl_add_u64 v[84:85], s[20:21], 0, v[78:79]
	v_mov_b32_e32 v81, 0xf149f2ca
	v_add_u32_e32 v174, v37, v41
	v_add_u32_e32 v175, v37, v39
	v_readfirstlane_b32 s91, v173
	v_add_u32_e32 v172, v48, v38
	v_add_u32_e32 v171, v49, v38
	s_waitcnt vmcnt(9)
	ds_write_b128 v36, v[2:5] offset:36864
	s_waitcnt vmcnt(8)
	ds_write_b128 v40, v[6:9] offset:36864
	s_waitcnt vmcnt(7)
	ds_write_b128 v43, v[10:13] offset:36864
	s_waitcnt vmcnt(6)
	ds_write_b128 v44, v[14:17] offset:36864
	s_waitcnt vmcnt(5)
	ds_write_b128 v45, v[18:21] offset:36864
	s_waitcnt vmcnt(4)
	ds_write_b128 v46, v[22:25] offset:36864
	s_waitcnt vmcnt(3)
	ds_write_b128 v47, v[26:29] offset:36864
	s_waitcnt vmcnt(2)
	ds_write_b128 v42, v[30:33] offset:36864
	v_add_u32_e32 v2, v1, v90
	v_add_u32_e32 v3, v1, v94
	v_add_u32_e32 v4, v1, v91
	v_add_u32_e32 v5, v1, v95
	v_add_u32_e32 v6, v1, v92
	v_add_u32_e32 v1, v1, v96
	v_or_b32_e32 v7, v89, v164
	s_waitcnt vmcnt(1)
	v_mov_b64_e32 v[64:65], v[128:129]
	s_waitcnt vmcnt(0)
	v_mov_b64_e32 v[68:69], v[132:133]
	v_sub_u32_e32 v88, v73, v7
	v_add_u32_e32 v170, v2, v38
	v_add_u32_e32 v169, v3, v38
	v_add_u32_e32 v168, v4, v38
	v_add_u32_e32 v167, v5, v38
	v_add_u32_e32 v166, v6, v38
	v_add_u32_e32 v149, v1, v38
	v_mov_b64_e32 v[66:67], v[130:131]
	v_mov_b64_e32 v[70:71], v[134:135]
	v_mov_b32_e32 v87, 0xf149f2ca
	v_mov_b32_e32 v83, v82
	s_waitcnt lgkmcnt(0)
	s_barrier
	ds_read_b32 v252, v147 offset:32768
	ds_read_b32 v253, v147 offset:33792
	s_waitcnt lgkmcnt(0)
	s_branch .LBB0_276
; #define SBAR() __builtin_amdgcn_sched_barrier(0)
; __device__ __forceinline__ void stat_upd(const f32x16& p0, float& m, float& l, const float C, const float cb) {
;   float mx = p0[0];
; #pragma unroll
;   for (int r = 1; r < 16; ++r) mx = fmaxf(mx, p0[r]);
;   { auto rr = __builtin_amdgcn_permlane32_swap(__float_as_uint(mx), __float_as_uint(mx), false, false);
;     mx = fmaxf(__uint_as_float(rr[0]), __uint_as_float(rr[1])); }
;   mx += cb;
;   const float mn = fmaxf(m, mx), alpha = __builtin_amdgcn_exp2f((m - mn) * C), mnC = (cb - mn) * C; float s = 0.f;
; #pragma unroll
;   for (int r = 0; r < 16; ++r) s += __builtin_amdgcn_exp2f(fmaf(p0[r], C, mnC));
;   l = l * alpha + s; m = mn;
; }
; template <bool DIFF> ...
;     ...
;       BIAS_APPLY(t, 0, a0, b0, cb0);
;       stat_upd(a0, m1, l1, C, cb0);
;       if (DIFF) stat_upd(b0, m2, l2, C, cb0);
;       SBAR();
;       BIAS_APPLY(t, 1, a1, b1, cb1);
;       stat_upd(a1, m1, l1, C, cb1);
;       if (DIFF) stat_upd(b1, m2, l2, C, cb1);
.LBB0_275:
	v_max_f32_e32 v102, v103, v103
	v_max_f32_e32 v103, v104, v104
	v_max_f32_e32 v102, v102, v103
	s_waitcnt lgkmcnt(0)
	v_add_f32_e32 v102, v99, v102
	v_max_f32_e32 v103, v87, v87
	v_max_f32_e32 v104, v103, v102
	v_sub_f32_e32 v102, v99, v104
	v_mul_f32_e32 v102, 0x3e38aa3b, v102
	v_fmamk_f32 v48, v48, 0x3e38aa3b, v102
	v_exp_f32_e32 v48, v48
	v_fmamk_f32 v49, v49, 0x3e38aa3b, v102
	v_exp_f32_e32 v49, v49
	v_fmamk_f32 v50, v50, 0x3e38aa3b, v102
	v_exp_f32_e32 v50, v50
	v_fmamk_f32 v51, v51, 0x3e38aa3b, v102
	v_exp_f32_e32 v51, v51
	v_add_f32_e32 v48, 0, v48
	v_add_f32_e32 v48, v49, v48
	v_fmamk_f32 v49, v52, 0x3e38aa3b, v102
	v_add_f32_e32 v48, v50, v48
	v_exp_f32_e32 v49, v49
	v_fmamk_f32 v50, v53, 0x3e38aa3b, v102
	v_add_f32_e32 v48, v51, v48
	v_exp_f32_e32 v50, v50
	v_fmamk_f32 v51, v54, 0x3e38aa3b, v102
	v_exp_f32_e32 v51, v51
	v_fmamk_f32 v52, v55, 0x3e38aa3b, v102
	v_exp_f32_e32 v52, v52
	v_add_f32_e32 v48, v49, v48
	v_add_f32_e32 v48, v50, v48
	v_add_f32_e32 v48, v51, v48
	v_add_f32_e32 v49, v52, v48
	v_fmamk_f32 v48, v56, 0x3e38aa3b, v102
	v_exp_f32_e32 v51, v48
	v_fmamk_f32 v48, v57, 0x3e38aa3b, v102
	v_exp_f32_e32 v53, v48
	v_fmamk_f32 v48, v58, 0x3e38aa3b, v102
	v_exp_f32_e32 v55, v48
	v_fmamk_f32 v48, v59, 0x3e38aa3b, v102
	v_exp_f32_e32 v57, v48
	v_fmamk_f32 v48, v60, 0x3e38aa3b, v102
	v_exp_f32_e32 v59, v48
	v_fmamk_f32 v48, v61, 0x3e38aa3b, v102
	v_exp_f32_e32 v61, v48
	v_fmamk_f32 v48, v62, 0x3e38aa3b, v102
	v_exp_f32_e32 v103, v48
	v_sub_f32_e32 v48, v87, v104
	v_mul_f32_e32 v48, 0x3e38aa3b, v48
	v_exp_f32_e32 v107, v48
	v_max_f32_e32 v48, v100, v100
	v_max_f32_e32 v50, v101, v101
	v_max_f32_e32 v48, v48, v50
	v_add_f32_e32 v48, v99, v48
	v_max_f32_e32 v50, v81, v81
	v_max_f32_e32 v100, v50, v48
	v_sub_f32_e32 v48, v99, v100
	v_mul_f32_e32 v62, 0x3e38aa3b, v48
	v_fmamk_f32 v32, v32, 0x3e38aa3b, v62
	v_exp_f32_e32 v32, v32
	v_fmamk_f32 v33, v33, 0x3e38aa3b, v62
	v_exp_f32_e32 v33, v33
	v_fmamk_f32 v34, v34, 0x3e38aa3b, v62
	v_exp_f32_e32 v34, v34
	v_fmamk_f32 v35, v35, 0x3e38aa3b, v62
	v_exp_f32_e32 v35, v35
	v_add_f32_e32 v32, 0, v32
	v_add_f32_e32 v32, v33, v32
	v_fmamk_f32 v33, v36, 0x3e38aa3b, v62
	v_add_f32_e32 v32, v34, v32
	v_exp_f32_e32 v33, v33
	v_fmamk_f32 v34, v37, 0x3e38aa3b, v62
	v_add_f32_e32 v32, v35, v32
	v_exp_f32_e32 v34, v34
	v_fmamk_f32 v35, v38, 0x3e38aa3b, v62
	v_exp_f32_e32 v35, v35
	v_add_f32_e32 v32, v33, v32
	v_add_f32_e32 v32, v34, v32
	v_max_f32_e32 v34, v17, v17
	v_add_f32_e32 v32, v35, v32
	v_max_f32_e32 v35, v16, v16
	v_fmamk_f32 v36, v39, 0x3e38aa3b, v62
	v_max_f32_e32 v34, v35, v34
	v_exp_f32_e32 v36, v36
	v_max3_f32 v34, v34, v18, v19
	v_max3_f32 v34, v34, v20, v21
	v_max3_f32 v34, v34, v22, v23
	v_max3_f32 v34, v34, v24, v25
	v_add_f32_e32 v48, v36, v32
	v_fmamk_f32 v32, v40, 0x3e38aa3b, v62
	v_max3_f32 v34, v34, v26, v27
	v_exp_f32_e32 v50, v32
	v_fmamk_f32 v32, v41, 0x3e38aa3b, v62
	v_max3_f32 v34, v34, v28, v29
	v_exp_f32_e32 v52, v32
	v_fmamk_f32 v32, v42, 0x3e38aa3b, v62
	v_max3_f32 v34, v34, v30, v31
	v_exp_f32_e32 v54, v32
	v_fmamk_f32 v32, v43, 0x3e38aa3b, v62
	v_mov_b32_e32 v35, v34
	v_exp_f32_e32 v56, v32
	v_fmamk_f32 v32, v44, 0x3e38aa3b, v62
	v_permlane32_swap_b32_e32 v34, v35
	v_exp_f32_e32 v58, v32
	v_fmamk_f32 v32, v45, 0x3e38aa3b, v62
	v_max_f32_e32 v35, v35, v35
	v_max_f32_e32 v34, v34, v34
	v_fmac_f32_e32 v102, 0x3e38aa3b, v63
	v_exp_f32_e32 v60, v32
	v_fmamk_f32 v32, v46, 0x3e38aa3b, v62
	v_max_f32_e32 v34, v34, v35
	v_exp_f32_e32 v63, v102
	v_exp_f32_e32 v102, v32
	v_sub_f32_e32 v32, v81, v100
	v_add_f32_e32 v34, v105, v34
	v_mul_f32_e32 v32, 0x3e38aa3b, v32
	v_max_f32_e32 v87, v104, v34
	v_exp_f32_e32 v106, v32
	v_pk_add_f32 v[32:33], v[50:51], v[48:49]
	v_sub_f32_e32 v34, v105, v87
	v_pk_add_f32 v[32:33], v[52:53], v[32:33]
	v_mul_f32_e32 v34, 0x3e38aa3b, v34
	v_fmac_f32_e32 v62, 0x3e38aa3b, v47
	v_pk_add_f32 v[32:33], v[54:55], v[32:33]
	v_fmamk_f32 v16, v16, 0x3e38aa3b, v34
	v_exp_f32_e32 v62, v62
	v_pk_add_f32 v[32:33], v[56:57], v[32:33]
	v_exp_f32_e32 v35, v16
	v_fmamk_f32 v16, v17, 0x3e38aa3b, v34
	v_pk_add_f32 v[32:33], v[58:59], v[32:33]
	v_exp_f32_e32 v36, v16
	v_fmamk_f32 v18, v18, 0x3e38aa3b, v34
	v_pk_add_f32 v[32:33], v[60:61], v[32:33]
	v_exp_f32_e32 v18, v18
	v_fmamk_f32 v19, v19, 0x3e38aa3b, v34
	v_pk_add_f32 v[32:33], v[102:103], v[32:33]
	v_exp_f32_e32 v19, v19
	v_fmamk_f32 v20, v20, 0x3e38aa3b, v34
	v_pk_add_f32 v[16:17], v[62:63], v[32:33]
	v_add_f32_e32 v32, 0, v35
	v_exp_f32_e32 v20, v20
	v_fmamk_f32 v21, v21, 0x3e38aa3b, v34
	v_add_f32_e32 v32, v36, v32
	v_exp_f32_e32 v21, v21
	v_add_f32_e32 v18, v18, v32
	v_add_f32_e32 v18, v19, v18
	v_add_f32_e32 v18, v20, v18
	v_add_f32_e32 v19, v21, v18
	v_fmamk_f32 v18, v22, 0x3e38aa3b, v34
	v_max_f32_e32 v20, v1, v1
	v_max_f32_e32 v22, v0, v0
	v_max_f32_e32 v20, v22, v20
	v_max3_f32 v20, v20, v2, v3
	v_max3_f32 v20, v20, v4, v5
	v_max3_f32 v20, v20, v6, v7
	v_max3_f32 v20, v20, v8, v9
	v_max3_f32 v20, v20, v10, v11
	v_max3_f32 v20, v20, v12, v13
	v_max3_f32 v20, v20, v14, v15
	v_exp_f32_e32 v21, v18
	v_fmamk_f32 v18, v23, 0x3e38aa3b, v34
	v_mov_b32_e32 v22, v20
	v_exp_f32_e32 v23, v18
	v_fmamk_f32 v18, v24, 0x3e38aa3b, v34
	v_permlane32_swap_b32_e32 v20, v22
	v_exp_f32_e32 v33, v18
	v_fmamk_f32 v18, v25, 0x3e38aa3b, v34
	v_max_f32_e32 v22, v22, v22
	v_max_f32_e32 v20, v20, v20
	v_exp_f32_e32 v25, v18
	v_fmamk_f32 v18, v26, 0x3e38aa3b, v34
	v_max_f32_e32 v20, v20, v22
	v_exp_f32_e32 v35, v18
	v_fmamk_f32 v18, v27, 0x3e38aa3b, v34
	v_add_f32_e32 v20, v105, v20
	v_exp_f32_e32 v27, v18
	v_fmamk_f32 v18, v28, 0x3e38aa3b, v34
	v_max_f32_e32 v81, v100, v20
	v_exp_f32_e32 v37, v18
; #define SBAR() __builtin_amdgcn_sched_barrier(0)
; #define KLOAD(t) do { const bf16* kp_ = Kb + (size_t)((t) * 64 + sr) * 1024 + sc; ks0 = *reinterpret_cast<const bf16x8*>(kp_); ks1 = *reinterpret_cast<const bf16x8*>(kp_ + 32 * 1024); } while (0)
; #define KWRITE() do { *reinterpret_cast<bf16x8*>(K_lds + kst0) = ks0; *reinterpret_cast<bf16x8*>(K_lds + kst1) = ks1; } while (0)
; template <bool DIFF>
; __device__ __forceinline__ void qkt(f32x16& a, f32x16& b, const char* Ks, const char* Qs, int krow, int r32, int hi) {
;   a = f32x16{}; b = f32x16{};
; #pragma unroll
;   for (int d = 0; d < 4; ++d) {
;     const int cb0 = (d * 16 + hi * 8) * 2, cb1 = ((d + 4) * 16 + hi * 8) * 2;
;     const bf16x8 k0 = *reinterpret_cast<const bf16x8*>(Ks + KSWZ(krow, cb0)), q0 = *reinterpret_cast<const bf16x8*>(Qs + KSWZ(r32, cb0));
;     const bf16x8 k1 = *reinterpret_cast<const bf16x8*>(Ks + KSWZ(krow, cb1)), q1 = *reinterpret_cast<const bf16x8*>(Qs + KSWZ(r32, cb1));
;     a = __builtin_amdgcn_mfma_f32_32x32x16_bf16(k0, q0, a, 0, 0, 0);
;     b = __builtin_amdgcn_mfma_f32_32x32x16_bf16(k1, q1, b, 0, 0, 0); }
; template <bool DIFF> ...
;     ...
;   for (int t = t_lo; t < t_hi; ++t) {
;     __syncthreads();
;     KWRITE();
;     __syncthreads();
;     if (t + 1 < t_hi) KLOAD(t + 1);
;     const bool active = DIFF || (t >= rstart && t < rstart + 8);
;     if (active) {
;       f32x16 a0, b0, a1, b1;
;       qkt<DIFF>(a0, b0, K_lds, Q_lds, r32, r32, hi);
;       qkt<DIFF>(a1, b1, K_lds, Q_lds, r32 + 32, r32, hi);
;       SBAR();
;       float cb0, cb1;
;       BIAS_APPLY(t, 0, a0, b0, cb0);
	v_fmamk_f32 v18, v29, 0x3e38aa3b, v34
	v_sub_f32_e32 v20, v105, v81
	v_exp_f32_e32 v29, v18
	v_fmamk_f32 v18, v30, 0x3e38aa3b, v34
	v_mul_f32_e32 v30, 0x3e38aa3b, v20
	v_fmamk_f32 v0, v0, 0x3e38aa3b, v30
	v_exp_f32_e32 v0, v0
	v_fmamk_f32 v1, v1, 0x3e38aa3b, v30
	v_exp_f32_e32 v20, v1
	v_fmamk_f32 v2, v2, 0x3e38aa3b, v30
	v_exp_f32_e32 v2, v2
	v_fmamk_f32 v3, v3, 0x3e38aa3b, v30
	v_exp_f32_e32 v3, v3
	v_fmamk_f32 v4, v4, 0x3e38aa3b, v30
	v_add_f32_e32 v0, 0, v0
	v_exp_f32_e32 v4, v4
	v_fmamk_f32 v5, v5, 0x3e38aa3b, v30
	v_add_f32_e32 v0, v20, v0
	v_exp_f32_e32 v5, v5
	v_add_f32_e32 v0, v2, v0
	v_add_f32_e32 v0, v3, v0
	v_exp_f32_e32 v39, v18
	v_sub_f32_e32 v18, v104, v87
	v_add_f32_e32 v0, v4, v0
	v_mul_f32_e32 v1, 0x3e38aa3b, v18
	v_add_f32_e32 v18, v5, v0
	v_fmamk_f32 v0, v6, 0x3e38aa3b, v30
	v_exp_f32_e32 v20, v0
	v_fmamk_f32 v0, v7, 0x3e38aa3b, v30
	v_exp_f32_e32 v22, v0
	v_fmamk_f32 v0, v8, 0x3e38aa3b, v30
	v_exp_f32_e32 v32, v0
	v_fmamk_f32 v0, v9, 0x3e38aa3b, v30
	v_fmac_f32_e32 v34, 0x3e38aa3b, v31
	v_exp_f32_e32 v24, v0
	v_fmamk_f32 v0, v10, 0x3e38aa3b, v30
	v_exp_f32_e32 v31, v34
	v_exp_f32_e32 v34, v0
	v_fmamk_f32 v0, v11, 0x3e38aa3b, v30
	v_pk_add_f32 v[2:3], v[20:21], v[18:19]
	v_exp_f32_e32 v26, v0
	v_fmamk_f32 v0, v12, 0x3e38aa3b, v30
	v_pk_add_f32 v[2:3], v[22:23], v[2:3]
	v_exp_f32_e32 v36, v0
	v_fmamk_f32 v0, v13, 0x3e38aa3b, v30
	v_pk_add_f32 v[2:3], v[32:33], v[2:3]
	v_exp_f32_e32 v28, v0
	v_fmamk_f32 v0, v14, 0x3e38aa3b, v30
	v_pk_add_f32 v[2:3], v[24:25], v[2:3]
	v_exp_f32_e32 v38, v0
	v_fmac_f32_e32 v30, 0x3e38aa3b, v15
	v_sub_f32_e32 v0, v100, v81
	v_pk_add_f32 v[2:3], v[34:35], v[2:3]
	v_exp_f32_e32 v30, v30
	v_mul_f32_e32 v0, 0x3e38aa3b, v0
	v_pk_add_f32 v[2:3], v[26:27], v[2:3]
	v_exp_f32_e32 v1, v1
	v_exp_f32_e32 v0, v0
	v_pk_add_f32 v[2:3], v[36:37], v[2:3]
	v_pk_fma_f32 v[16:17], v[82:83], v[106:107], v[16:17]
	v_pk_add_f32 v[2:3], v[28:29], v[2:3]
	s_add_i32 s2, s2, 64
	v_pk_add_f32 v[2:3], v[38:39], v[2:3]
	s_cmp_eq_u32 s18, s2
	v_pk_add_f32 v[2:3], v[30:31], v[2:3]
	v_lshl_add_u64 v[84:85], v[84:85], 0, s[26:27]
	v_pk_fma_f32 v[82:83], v[16:17], v[0:1], v[2:3]
	s_cbranch_scc1 .LBB0_292
.LBB0_276:
	v_add_u32_e32 v176, v97, v98
	s_waitcnt lgkmcnt(0)
	s_barrier
	s_waitcnt vmcnt(0)
	ds_write_b128 v174, v[64:67]
	ds_write_b128 v175, v[68:71]
	s_waitcnt lgkmcnt(0)
	s_barrier
	ds_read_b128 v[0:3], v176
	ds_read_b128 v[4:7], v172 offset:36864
	v_add_u32_e32 v177, v97, v93
	ds_read_b128 v[8:11], v177
	ds_read_b128 v[12:15], v176 offset:8192
	s_waitcnt lgkmcnt(2)
	v_mfma_f32_32x32x16_bf16 v[48:63], v[0:3], v[4:7], 0
	ds_read_b128 v[0:3], v171 offset:36864
	ds_read_b128 v[64:67], v177 offset:8192
	v_add_u32_e32 v178, v97, v90
	v_add_u32_e32 v179, v97, v94
	v_add_u32_e32 v180, v97, v91
	v_add_u32_e32 v181, v97, v95
	v_add_u32_e32 v182, v97, v92
	v_add_u32_e32 v183, v97, v96
	s_waitcnt lgkmcnt(1)
	v_mfma_f32_32x32x16_bf16 v[32:47], v[8:11], v[0:3], 0
	ds_read_b128 v[8:11], v178
	ds_read_b128 v[68:71], v170 offset:36864
	ds_read_b128 v[16:19], v179
	ds_read_b128 v[100:103], v178 offset:8192
	ds_read_b128 v[104:107], v169 offset:36864
	ds_read_b128 v[108:111], v179 offset:8192
	s_waitcnt lgkmcnt(1)
	v_mfma_f32_32x32x16_bf16 v[32:47], v[16:19], v[104:107], v[32:47]
	v_mfma_f32_32x32x16_bf16 v[48:63], v[8:11], v[68:71], v[48:63]
	ds_read_b128 v[8:11], v180
	ds_read_b128 v[112:115], v168 offset:36864
	ds_read_b128 v[16:19], v181
	ds_read_b128 v[116:119], v180 offset:8192
	ds_read_b128 v[120:123], v167 offset:36864
	ds_read_b128 v[124:127], v181 offset:8192
	s_waitcnt lgkmcnt(1)
	v_mfma_f32_32x32x16_bf16 v[32:47], v[16:19], v[120:123], v[32:47]
	v_mfma_f32_32x32x16_bf16 v[48:63], v[8:11], v[112:115], v[48:63]
	ds_read_b128 v[8:11], v182
	ds_read_b128 v[136:139], v166 offset:36864
	ds_read_b128 v[16:19], v183
	ds_read_b128 v[140:143], v182 offset:8192
	ds_read_b128 v[150:153], v149 offset:36864
	ds_read_b128 v[184:187], v183 offset:8192
	s_waitcnt lgkmcnt(1)
	v_mfma_f32_32x32x16_bf16 v[32:47], v[16:19], v[150:153], v[32:47]
	v_mfma_f32_32x32x16_bf16 v[16:31], v[12:15], v[4:7], 0
	v_mfma_f32_32x32x16_bf16 v[16:31], v[100:103], v[68:71], v[16:31]
	v_add_co_u32_e32 v68, vcc, s66, v84
	s_nop 1
	v_addc_co_u32_e32 v69, vcc, 0, v85, vcc
	global_load_dwordx4 v[68:71], v[68:69], off
	v_mfma_f32_32x32x16_bf16 v[48:63], v[8:11], v[136:139], v[48:63]
	v_mfma_f32_32x32x16_bf16 v[0:15], v[64:67], v[0:3], 0
	global_load_dwordx4 v[64:67], v[84:85], off
	v_mfma_f32_32x32x16_bf16 v[0:15], v[108:111], v[104:107], v[0:15]
	v_mfma_f32_32x32x16_bf16 v[16:31], v[116:119], v[112:115], v[16:31]
	v_mfma_f32_32x32x16_bf16 v[0:15], v[124:127], v[120:123], v[0:15]
	v_mfma_f32_32x32x16_bf16 v[16:31], v[140:143], v[136:139], v[16:31]
	s_waitcnt lgkmcnt(0)
	v_mfma_f32_32x32x16_bf16 v[0:15], v[184:187], v[150:153], v[0:15]
	s_add_i32 s92, s2, s91
	s_cmpk_ge_i32 s92, 0x9f
	s_cbranch_scc1 .Lb1a_hi
	s_cmpk_le_i32 s92, 0xff41
	s_cbranch_scc1 .Lb1a_lo
	v_add_u32_e32 v99, s2, v88
	v_add_u32_e32 v99, 0x80, v99
	v_med3_i32 v100, v99, 0, v163
	v_lshl_add_u32 v103, v100, 2, 0
	v_max_i32_e32 v100, -1, v99
	v_add_u32_e32 v100, 1, v100
	v_min_u32_e32 v100, 0x100, v100
	v_lshl_add_u32 v111, v100, 2, 0
	v_max_i32_e32 v100, -2, v99
	v_add_u32_e32 v100, 2, v100
	v_min_u32_e32 v100, 0x100, v100
	v_lshl_add_u32 v112, v100, 2, 0
	v_max_i32_e32 v100, -3, v99
	v_add_u32_e32 v100, 3, v100
	v_min_u32_e32 v100, 0x100, v100
	v_lshl_add_u32 v113, v100, 2, 0
	v_max_i32_e32 v100, -8, v99
	v_add_u32_e32 v100, 8, v100
	v_min_u32_e32 v100, 0x100, v100
	v_lshl_add_u32 v114, v100, 2, 0
	v_max_i32_e32 v100, -9, v99
	v_add_u32_e32 v100, 9, v100
	v_min_u32_e32 v100, 0x100, v100
	v_lshl_add_u32 v115, v100, 2, 0
	v_max_i32_e32 v100, -10, v99
	v_add_u32_e32 v100, 10, v100
	v_min_u32_e32 v100, 0x100, v100
	v_lshl_add_u32 v116, v100, 2, 0
	v_max_i32_e32 v100, -11, v99
	v_add_u32_e32 v100, 11, v100
	v_min_u32_e32 v100, 0x100, v100
	v_lshl_add_u32 v117, v100, 2, 0
	v_max_i32_e32 v100, -16, v99
	v_max_i32_e32 v101, 0xffffffef, v99
	v_max_i32_e32 v104, 0xffffffee, v99
	v_max_i32_e32 v105, 0xffffffed, v99
	v_max_i32_e32 v106, 0xffffffe8, v99
	v_max_i32_e32 v107, 0xffffffe7, v99
	v_max_i32_e32 v108, 0xffffffe6, v99
	v_add_u32_e32 v100, 16, v100
	v_add_u32_e32 v101, 17, v101
	v_add_u32_e32 v104, 18, v104
	v_add_u32_e32 v105, 19, v105
	v_add_u32_e32 v106, 24, v106
	v_add_u32_e32 v107, 25, v107
	v_add_u32_e32 v108, 26, v108
	v_max_i32_e32 v99, 0xffffffe5, v99
	v_min_u32_e32 v100, 0x100, v100
	v_min_u32_e32 v101, 0x100, v101
	v_min_u32_e32 v104, 0x100, v104
	v_min_u32_e32 v105, 0x100, v105
	v_min_u32_e32 v106, 0x100, v106
	v_min_u32_e32 v107, 0x100, v107
	v_min_u32_e32 v108, 0x100, v108
	v_add_u32_e32 v99, 27, v99
	v_lshl_add_u32 v100, v100, 2, 0
	v_lshl_add_u32 v101, v101, 2, 0
	v_lshl_add_u32 v104, v104, 2, 0
	v_lshl_add_u32 v105, v105, 2, 0
	v_lshl_add_u32 v106, v106, 2, 0
	v_lshl_add_u32 v107, v107, 2, 0
	v_lshl_add_u32 v108, v108, 2, 0
	v_min_u32_e32 v99, 0x100, v99
	v_lshl_add_u32 v99, v99, 2, 0
	ds_read_b32 v100, v100 offset:32768
	ds_read_b32 v101, v101 offset:32768
	ds_read_b32 v104, v104 offset:32768
	ds_read_b32 v105, v105 offset:32768
	ds_read_b32 v106, v106 offset:32768
	ds_read_b32 v107, v107 offset:32768
	ds_read_b32 v108, v108 offset:32768
	ds_read_b32 v109, v99 offset:32768
	ds_read_b32 v110, v103 offset:32768
	ds_read_b32 v111, v111 offset:32768
	ds_read_b32 v112, v112 offset:32768
	ds_read_b32 v113, v113 offset:32768
	ds_read_b32 v114, v114 offset:32768
	ds_read_b32 v115, v115 offset:32768
	ds_read_b32 v116, v116 offset:32768
	ds_read_b32 v117, v117 offset:32768
	s_waitcnt lgkmcnt(8)
	v_pk_add_f32 v[62:63], v[62:63], v[108:109]
	v_pk_add_f32 v[60:61], v[60:61], v[106:107]
	v_pk_add_f32 v[58:59], v[58:59], v[104:105]
	v_pk_add_f32 v[56:57], v[56:57], v[100:101]
	s_waitcnt lgkmcnt(0)
	v_pk_add_f32 v[54:55], v[54:55], v[116:117]
	v_pk_add_f32 v[52:53], v[52:53], v[114:115]
	v_pk_add_f32 v[50:51], v[50:51], v[112:113]
	v_pk_add_f32 v[48:49], v[48:49], v[110:111]
	v_pk_add_f32 v[46:47], v[46:47], v[108:109]
	v_pk_add_f32 v[44:45], v[44:45], v[106:107]
	v_pk_add_f32 v[42:43], v[42:43], v[104:105]
	v_pk_add_f32 v[40:41], v[40:41], v[100:101]
	v_pk_add_f32 v[38:39], v[38:39], v[116:117]
	v_pk_add_f32 v[36:37], v[36:37], v[114:115]
	v_pk_add_f32 v[34:35], v[34:35], v[112:113]
	v_pk_add_f32 v[32:33], v[32:33], v[110:111]
	v_mov_b32_e32 v99, 0
	s_branch .LBB0_284
.Lb1a_hi:
	v_mov_b32_e32 v99, v253
	s_branch .LBB0_284
.Lb1a_lo:
	v_mov_b32_e32 v99, v252
; __device__ __forceinline__ void stat_upd(const f32x16& p0, float& m, float& l, const float C, const float cb) {
;   float mx = p0[0];
; #pragma unroll
;   for (int r = 1; r < 16; ++r) mx = fmaxf(mx, p0[r]);
;   { auto rr = __builtin_amdgcn_permlane32_swap(__float_as_uint(mx), __float_as_uint(mx), false, false);
;     mx = fmaxf(__uint_as_float(rr[0]), __uint_as_float(rr[1])); }
.LBB0_284:
	v_max_f32_e32 v100, v49, v49
	v_max_f32_e32 v101, v48, v48
	v_max_f32_e32 v100, v101, v100
	v_max3_f32 v100, v100, v50, v51
	v_max3_f32 v100, v100, v52, v53
	v_max3_f32 v100, v100, v54, v55
	v_max3_f32 v100, v100, v56, v57
	v_max3_f32 v100, v100, v58, v59
	v_max3_f32 v100, v100, v60, v61
	v_max3_f32 v103, v100, v62, v63
	v_max_f32_e32 v100, v33, v33
	v_max_f32_e32 v101, v32, v32
	v_max_f32_e32 v100, v101, v100
	v_max3_f32 v100, v100, v34, v35
	v_max3_f32 v100, v100, v36, v37
	v_max3_f32 v100, v100, v38, v39
	v_max3_f32 v100, v100, v40, v41
	v_max3_f32 v100, v100, v42, v43
	v_max3_f32 v100, v100, v44, v45
	v_max3_f32 v100, v100, v46, v47
	v_mov_b32_e32 v104, v103
	v_mov_b32_e32 v101, v100
	s_nop 0
	v_permlane32_swap_b32_e32 v103, v104
	v_permlane32_swap_b32_e32 v100, v101
	s_cmpk_ge_i32 s92, 0x9f
	s_cbranch_scc1 .Lb1b_hi
	s_cmpk_le_i32 s92, 0xff41
	s_cbranch_scc1 .Lb1b_lo
	v_add_u32_e32 v102, s2, v88
	v_add_u32_e32 v102, 0xa0, v102
	v_max_i32_e32 v106, -1, v102
	v_add_u32_e32 v106, 1, v106
	v_min_u32_e32 v106, 0x100, v106
	v_lshl_add_u32 v115, v106, 2, 0
	v_max_i32_e32 v106, -2, v102
	v_add_u32_e32 v106, 2, v106
	v_min_u32_e32 v106, 0x100, v106
	v_lshl_add_u32 v116, v106, 2, 0
	v_max_i32_e32 v106, -3, v102
	v_add_u32_e32 v106, 3, v106
	v_min_u32_e32 v106, 0x100, v106
	v_lshl_add_u32 v117, v106, 2, 0
	v_max_i32_e32 v106, -8, v102
	v_add_u32_e32 v106, 8, v106
	v_min_u32_e32 v106, 0x100, v106
	v_lshl_add_u32 v118, v106, 2, 0
	v_max_i32_e32 v106, -9, v102
	v_add_u32_e32 v106, 9, v106
	v_min_u32_e32 v106, 0x100, v106
	v_lshl_add_u32 v119, v106, 2, 0
	v_max_i32_e32 v106, -10, v102
	v_add_u32_e32 v106, 10, v106
	v_min_u32_e32 v106, 0x100, v106
	v_lshl_add_u32 v120, v106, 2, 0
	v_max_i32_e32 v106, -11, v102
	v_add_u32_e32 v106, 11, v106
	v_min_u32_e32 v106, 0x100, v106
	v_lshl_add_u32 v121, v106, 2, 0
	v_max_i32_e32 v106, -16, v102
	v_max_i32_e32 v107, 0xffffffef, v102
	v_max_i32_e32 v108, 0xffffffee, v102
	v_max_i32_e32 v109, 0xffffffed, v102
	v_max_i32_e32 v110, 0xffffffe8, v102
	v_max_i32_e32 v111, 0xffffffe7, v102
	v_max_i32_e32 v112, 0xffffffe6, v102
	v_med3_i32 v105, v102, 0, v163
	v_add_u32_e32 v106, 16, v106
	v_add_u32_e32 v107, 17, v107
	v_add_u32_e32 v108, 18, v108
	v_add_u32_e32 v109, 19, v109
	v_add_u32_e32 v110, 24, v110
	v_add_u32_e32 v111, 25, v111
	v_add_u32_e32 v112, 26, v112
	v_max_i32_e32 v102, 0xffffffe5, v102
	v_min_u32_e32 v106, 0x100, v106
	v_min_u32_e32 v107, 0x100, v107
	v_min_u32_e32 v108, 0x100, v108
	v_min_u32_e32 v109, 0x100, v109
	v_min_u32_e32 v110, 0x100, v110
	v_min_u32_e32 v111, 0x100, v111
	v_min_u32_e32 v112, 0x100, v112
	v_add_u32_e32 v102, 27, v102
	v_lshl_add_u32 v106, v106, 2, 0
	v_lshl_add_u32 v107, v107, 2, 0
	v_lshl_add_u32 v108, v108, 2, 0
	v_lshl_add_u32 v109, v109, 2, 0
	v_lshl_add_u32 v110, v110, 2, 0
	v_lshl_add_u32 v111, v111, 2, 0
	v_lshl_add_u32 v112, v112, 2, 0
	v_min_u32_e32 v102, 0x100, v102
	v_lshl_add_u32 v105, v105, 2, 0
	v_lshl_add_u32 v102, v102, 2, 0
	ds_read_b32 v106, v106 offset:32768
	ds_read_b32 v107, v107 offset:32768
	ds_read_b32 v108, v108 offset:32768
	ds_read_b32 v109, v109 offset:32768
	ds_read_b32 v110, v110 offset:32768
	ds_read_b32 v111, v111 offset:32768
	ds_read_b32 v112, v112 offset:32768
	ds_read_b32 v113, v102 offset:32768
	ds_read_b32 v114, v105 offset:32768
	ds_read_b32 v115, v115 offset:32768
	ds_read_b32 v116, v116 offset:32768
	ds_read_b32 v117, v117 offset:32768
	ds_read_b32 v118, v118 offset:32768
	ds_read_b32 v119, v119 offset:32768
	ds_read_b32 v120, v120 offset:32768
	ds_read_b32 v121, v121 offset:32768
	s_waitcnt lgkmcnt(8)
	v_pk_add_f32 v[30:31], v[30:31], v[112:113]
	v_pk_add_f32 v[28:29], v[28:29], v[110:111]
	v_pk_add_f32 v[26:27], v[26:27], v[108:109]
	v_pk_add_f32 v[24:25], v[24:25], v[106:107]
	s_waitcnt lgkmcnt(0)
	v_pk_add_f32 v[22:23], v[22:23], v[120:121]
	v_pk_add_f32 v[20:21], v[20:21], v[118:119]
	v_pk_add_f32 v[18:19], v[18:19], v[116:117]
	v_pk_add_f32 v[16:17], v[16:17], v[114:115]
	v_pk_add_f32 v[14:15], v[14:15], v[112:113]
	v_pk_add_f32 v[12:13], v[12:13], v[110:111]
	v_pk_add_f32 v[10:11], v[10:11], v[108:109]
	v_pk_add_f32 v[8:9], v[8:9], v[106:107]
	v_pk_add_f32 v[6:7], v[6:7], v[120:121]
	v_pk_add_f32 v[4:5], v[4:5], v[118:119]
	v_pk_add_f32 v[2:3], v[2:3], v[116:117]
	v_pk_add_f32 v[0:1], v[0:1], v[114:115]
	v_mov_b32_e32 v105, 0
	s_branch .LBB0_275
.Lb1b_hi:
	v_mov_b32_e32 v105, v253
	s_branch .LBB0_275
.Lb1b_lo:
	v_mov_b32_e32 v105, v252
	s_branch .LBB0_275

; #define SBAR() __builtin_amdgcn_sched_barrier(0)
; __device__ __forceinline__ void stat_upd(const f32x16& p0, float& m, float& l, const float C, const float cb) {
;   float mx = p0[0];
; #pragma unroll
;   for (int r = 1; r < 16; ++r) mx = fmaxf(mx, p0[r]);
;   { auto rr = __builtin_amdgcn_permlane32_swap(__float_as_uint(mx), __float_as_uint(mx), false, false);
;     mx = fmaxf(__uint_as_float(rr[0]), __uint_as_float(rr[1])); }
;   mx += cb;
;   const float mn = fmaxf(m, mx), alpha = __builtin_amdgcn_exp2f((m - mn) * C), mnC = (cb - mn) * C; float s = 0.f;
; #pragma unroll
;   for (int r = 0; r < 16; ++r) s += __builtin_amdgcn_exp2f(fmaf(p0[r], C, mnC));
;   l = l * alpha + s; m = mn;
; }
; template <bool DIFF> ...
;     ...
;       stat_upd(a0, m1, l1, C, cb0);
;       if (DIFF) stat_upd(b0, m2, l2, C, cb0);
;       SBAR();
;       BIAS_APPLY(t, 1, a1, b1, cb1);
;       stat_upd(a1, m1, l1, C, cb1);
;       if (DIFF) stat_upd(b1, m2, l2, C, cb1);
;     }
;   }
;   { auto rr = __builtin_amdgcn_permlane32_swap(__float_as_uint(l1), __float_as_uint(l1), false, false); l1 = __uint_as_float(rr[0]) + __uint_as_float(rr[1]); }
.LBB0_308:
	s_or_b64 exec, exec, s[34:35]
	v_max_f32_e32 v0, v0, v0
	v_max_f32_e32 v69, v69, v69
	v_max_f32_e32 v0, v0, v69
	s_waitcnt lgkmcnt(0)
	v_add_f32_e32 v0, v1, v0
	v_max_f32_e32 v69, v87, v87
	v_max_f32_e32 v69, v69, v0
	v_sub_f32_e32 v0, v1, v69
	v_mul_f32_e32 v70, 0x3e38aa3b, v0
	v_fmamk_f32 v0, v50, 0x3e38aa3b, v70
	v_exp_f32_e32 v50, v0
	v_fmamk_f32 v0, v51, 0x3e38aa3b, v70
	v_exp_f32_e32 v51, v0
	s_lshl_b64 s[6:7], s[6:7], 1
	v_add_f32_e32 v50, 0, v50
	s_add_u32 s2, s44, s6
	v_add_f32_e32 v50, v51, v50
	v_fmamk_f32 v51, v52, 0x3e38aa3b, v70
	v_exp_f32_e32 v51, v51
	v_fmamk_f32 v52, v53, 0x3e38aa3b, v70
	v_exp_f32_e32 v52, v52
	v_fmamk_f32 v53, v54, 0x3e38aa3b, v70
	v_exp_f32_e32 v53, v53
	v_fmamk_f32 v54, v55, 0x3e38aa3b, v70
	v_exp_f32_e32 v54, v54
	v_add_f32_e32 v50, v51, v50
	v_fmamk_f32 v51, v56, 0x3e38aa3b, v70
	v_add_f32_e32 v50, v52, v50
	v_exp_f32_e32 v51, v51
	v_fmamk_f32 v52, v57, 0x3e38aa3b, v70
	v_add_f32_e32 v50, v53, v50
	v_exp_f32_e32 v52, v52
	v_fmamk_f32 v53, v58, 0x3e38aa3b, v70
	v_add_f32_e32 v50, v54, v50
	v_exp_f32_e32 v53, v53
	v_fmamk_f32 v54, v59, 0x3e38aa3b, v70
	v_exp_f32_e32 v54, v54
	v_add_f32_e32 v50, v51, v50
	v_fmamk_f32 v51, v60, 0x3e38aa3b, v70
	v_add_f32_e32 v50, v52, v50
	v_exp_f32_e32 v51, v51
	v_fmamk_f32 v52, v61, 0x3e38aa3b, v70
	v_add_f32_e32 v50, v53, v50
	v_exp_f32_e32 v52, v52
	v_fmamk_f32 v53, v62, 0x3e38aa3b, v70
	v_add_f32_e32 v50, v54, v50
	v_exp_f32_e32 v53, v53
	v_fmamk_f32 v54, v63, 0x3e38aa3b, v70
	v_exp_f32_e32 v54, v54
	v_add_f32_e32 v50, v51, v50
	v_add_f32_e32 v50, v52, v50
	v_add_f32_e32 v50, v53, v50
	v_add_f32_e32 v50, v54, v50
	v_max_f32_e32 v54, v66, v66
	v_max_f32_e32 v55, v67, v67
	v_max_f32_e32 v54, v54, v55
	v_add_f32_e32 v54, v1, v54
	v_max_f32_e32 v55, v81, v81
	v_max_f32_e32 v54, v55, v54
	v_sub_f32_e32 v1, v1, v54
	v_mul_f32_e32 v1, 0x3e38aa3b, v1
	v_fmamk_f32 v34, v34, 0x3e38aa3b, v1
	v_exp_f32_e32 v34, v34
	v_fmamk_f32 v35, v35, 0x3e38aa3b, v1
	v_exp_f32_e32 v35, v35
	v_fmamk_f32 v36, v36, 0x3e38aa3b, v1
	v_exp_f32_e32 v36, v36
	v_fmamk_f32 v37, v37, 0x3e38aa3b, v1
	v_add_f32_e32 v34, 0, v34
	v_exp_f32_e32 v37, v37
	v_fmamk_f32 v38, v38, 0x3e38aa3b, v1
	v_exp_f32_e32 v38, v38
	v_add_f32_e32 v34, v35, v34
	v_fmamk_f32 v35, v39, 0x3e38aa3b, v1
	v_add_f32_e32 v34, v36, v34
	v_exp_f32_e32 v35, v35
	v_fmamk_f32 v36, v40, 0x3e38aa3b, v1
	v_exp_f32_e32 v36, v36
	v_add_f32_e32 v34, v37, v34
	v_fmamk_f32 v37, v41, 0x3e38aa3b, v1
	v_add_f32_e32 v34, v38, v34
	v_exp_f32_e32 v37, v37
	v_fmamk_f32 v38, v42, 0x3e38aa3b, v1
	v_exp_f32_e32 v38, v38
	v_add_f32_e32 v34, v35, v34
	v_fmamk_f32 v35, v43, 0x3e38aa3b, v1
	v_add_f32_e32 v34, v36, v34
	v_exp_f32_e32 v35, v35
	v_fmamk_f32 v36, v44, 0x3e38aa3b, v1
	v_exp_f32_e32 v36, v36
	v_add_f32_e32 v34, v37, v34
	v_fmamk_f32 v37, v45, 0x3e38aa3b, v1
	v_add_f32_e32 v34, v38, v34
	v_exp_f32_e32 v37, v37
	v_fmamk_f32 v38, v46, 0x3e38aa3b, v1
	v_exp_f32_e32 v38, v38
	v_add_f32_e32 v34, v35, v34
	v_fmamk_f32 v35, v47, 0x3e38aa3b, v1
	v_add_f32_e32 v34, v36, v34
	v_exp_f32_e32 v35, v35
	v_fmamk_f32 v36, v48, 0x3e38aa3b, v1
	v_exp_f32_e32 v36, v36
	v_fmac_f32_e32 v1, 0x3e38aa3b, v49
	v_add_f32_e32 v34, v37, v34
	v_exp_f32_e32 v1, v1
	v_sub_f32_e32 v37, v81, v54
	v_add_f32_e32 v34, v38, v34
	v_mul_f32_e32 v37, 0x3e38aa3b, v37
	v_exp_f32_e32 v37, v37
	v_add_f32_e32 v34, v35, v34
	v_add_f32_e32 v34, v36, v34
	v_add_f32_e32 v1, v1, v34
	v_lshlrev_b32_e32 v34, 1, v80
	v_and_b32_e32 v38, 0xfffff0, v86
	v_lshlrev_b32_e32 v39, 1, v86
	v_and_b32_e32 v43, 0xfffff0, v80
	v_and_or_b32 v38, v39, 8, v38
	v_lshlrev_b32_e32 v40, 4, v75
	v_and_or_b32 v34, v34, 8, v43
	v_fmac_f32_e32 v1, v82, v37
	v_lshrrev_b32_e32 v35, 1, v80
	v_lshrrev_b32_e32 v36, 5, v72
	v_and_b32_e32 v37, 3, v80
	v_lshrrev_b32_e32 v38, 1, v38
	v_lshlrev_b32_e32 v39, 3, v75
	v_and_b32_e32 v40, 0xc0, v40
	v_lshrrev_b32_e32 v34, 1, v34
	v_and_b32_e32 v42, 0x100, v39
	v_or_b32_e32 v34, v34, v36
	v_and_or_b32 v35, v35, 4, v37
	v_or_b32_e32 v36, v38, v36
	v_and_or_b32 v37, v39, 24, v40
	v_max_f32_e32 v38, v19, v19
	v_max_f32_e32 v39, v18, v18
	v_max_f32_e32 v38, v39, v38
	v_max3_f32 v38, v38, v20, v21
	v_max3_f32 v38, v38, v22, v23
	v_max3_f32 v38, v38, v24, v25
	v_max3_f32 v38, v38, v26, v27
	v_max3_f32 v38, v38, v28, v29
	v_max3_f32 v38, v38, v30, v31
	v_max3_f32 v38, v38, v32, v33
	v_mov_b32_e32 v39, v38
	s_nop 1
	v_permlane32_swap_b32_e32 v38, v39
	v_max_f32_e32 v39, v39, v39
	v_max_f32_e32 v38, v38, v38
	v_max_f32_e32 v38, v38, v39
	v_add_f32_e32 v38, v68, v38
	v_max_f32_e32 v38, v69, v38
	v_sub_f32_e32 v39, v68, v38
	v_mul_f32_e32 v39, 0x3e38aa3b, v39
	v_fmamk_f32 v18, v18, 0x3e38aa3b, v39
	v_exp_f32_e32 v18, v18
	v_fmamk_f32 v19, v19, 0x3e38aa3b, v39
	v_exp_f32_e32 v19, v19
	v_fmamk_f32 v51, v64, 0x3e38aa3b, v70
	v_add_f32_e32 v18, 0, v18
	v_exp_f32_e32 v51, v51
	v_add_f32_e32 v18, v19, v18
	v_fmamk_f32 v19, v20, 0x3e38aa3b, v39
	v_exp_f32_e32 v19, v19
	v_fmamk_f32 v20, v21, 0x3e38aa3b, v39
	v_exp_f32_e32 v20, v20
	v_fmamk_f32 v21, v22, 0x3e38aa3b, v39
	v_exp_f32_e32 v21, v21
	v_fmamk_f32 v22, v23, 0x3e38aa3b, v39
	v_exp_f32_e32 v22, v22
	v_add_f32_e32 v18, v19, v18
	v_fmamk_f32 v19, v24, 0x3e38aa3b, v39
	v_add_f32_e32 v18, v20, v18
	v_exp_f32_e32 v19, v19
	v_fmamk_f32 v20, v25, 0x3e38aa3b, v39
	v_add_f32_e32 v18, v21, v18
	v_exp_f32_e32 v20, v20
	v_fmamk_f32 v21, v26, 0x3e38aa3b, v39
	v_add_f32_e32 v18, v22, v18
	v_exp_f32_e32 v21, v21
	v_fmamk_f32 v22, v27, 0x3e38aa3b, v39
	v_exp_f32_e32 v22, v22
	v_add_f32_e32 v18, v19, v18
	v_fmamk_f32 v19, v28, 0x3e38aa3b, v39
	v_add_f32_e32 v18, v20, v18
	v_exp_f32_e32 v19, v19
	v_fmamk_f32 v20, v29, 0x3e38aa3b, v39
	v_add_f32_e32 v18, v21, v18
; #define KLOAD(t) do { const bf16* kp_ = Kb + (size_t)((t) * 64 + sr) * 1024 + sc; ks0 = *reinterpret_cast<const bf16x8*>(kp_); ks1 = *reinterpret_cast<const bf16x8*>(kp_ + 32 * 1024); } while (0)
; #define VLOAD(t) do { const bf16* vp_ = Vb + (size_t)((t) * 64 + sr) * 1024 + sc; vs0 = *reinterpret_cast<const bf16x8*>(vp_); vs1 = *reinterpret_cast<const bf16x8*>(vp_ + 32 * 1024); } while (0)
; template <bool DIFF> ...
;     ...
;   { auto rr = __builtin_amdgcn_permlane32_swap(__float_as_uint(l1), __float_as_uint(l1), false, false); l1 = __uint_as_float(rr[0]) + __uint_as_float(rr[1]); }
;   }
;   if (DIFF) { auto rr = __builtin_amdgcn_permlane32_swap(__float_as_uint(l2), __float_as_uint(l2), false, false); l2 = __uint_as_float(rr[0]) + __uint_as_float(rr[1]); }
;   float* const wsc = (float*)(lds + 34816) + wid * 64;
;   const float e1 = DIFF ? -m1 * C - __builtin_amdgcn_logf(l1) : 0.f, e2 = DIFF ? -m2 * C + __builtin_amdgcn_logf(fabsf(lam) / l2) : 0.f, nsg = lam < 0.f ? 1.f : -1.f;
;   f32x16 o[4];
; #pragma unroll
;   for (int d = 0; d < 4; ++d) o[d] = f32x16{};
;   KLOAD(t_lo); VLOAD(t_lo);
	v_exp_f32_e32 v20, v20
	v_fmamk_f32 v21, v30, 0x3e38aa3b, v39
	v_add_f32_e32 v18, v22, v18
	v_exp_f32_e32 v21, v21
	v_fmamk_f32 v22, v31, 0x3e38aa3b, v39
	v_exp_f32_e32 v22, v22
	v_add_f32_e32 v18, v19, v18
	v_add_f32_e32 v18, v20, v18
	v_add_f32_e32 v18, v21, v18
	v_add_f32_e32 v18, v22, v18
	v_max_f32_e32 v22, v3, v3
	v_max_f32_e32 v23, v2, v2
	v_max_f32_e32 v22, v23, v22
	v_max3_f32 v22, v22, v4, v5
	v_max3_f32 v22, v22, v6, v7
	v_max3_f32 v22, v22, v8, v9
	v_max3_f32 v22, v22, v10, v11
	v_max3_f32 v22, v22, v12, v13
	v_max3_f32 v22, v22, v14, v15
	v_max3_f32 v22, v22, v16, v17
	v_mov_b32_e32 v23, v22
	s_nop 1
	v_permlane32_swap_b32_e32 v22, v23
	v_max_f32_e32 v23, v23, v23
	v_max_f32_e32 v22, v22, v22
	v_max_f32_e32 v22, v22, v23
	v_add_f32_e32 v22, v68, v22
	v_max_f32_e32 v22, v54, v22
	v_sub_f32_e32 v23, v68, v22
	v_mul_f32_e32 v23, 0x3e38aa3b, v23
	v_fmamk_f32 v2, v2, 0x3e38aa3b, v23
	v_exp_f32_e32 v2, v2
	v_fmamk_f32 v3, v3, 0x3e38aa3b, v23
	v_exp_f32_e32 v3, v3
	v_fmamk_f32 v4, v4, 0x3e38aa3b, v23
	v_exp_f32_e32 v4, v4
	v_fmamk_f32 v5, v5, 0x3e38aa3b, v23
	v_exp_f32_e32 v5, v5
	v_fmamk_f32 v6, v6, 0x3e38aa3b, v23
	v_add_f32_e32 v2, 0, v2
	v_exp_f32_e32 v6, v6
	v_add_f32_e32 v2, v3, v2
	v_fmamk_f32 v3, v7, 0x3e38aa3b, v23
	v_add_f32_e32 v2, v4, v2
	v_exp_f32_e32 v3, v3
	v_fmamk_f32 v4, v8, 0x3e38aa3b, v23
	v_add_f32_e32 v2, v5, v2
	v_exp_f32_e32 v4, v4
	v_fmamk_f32 v5, v9, 0x3e38aa3b, v23
	v_add_f32_e32 v2, v6, v2
	v_exp_f32_e32 v5, v5
	v_fmamk_f32 v6, v10, 0x3e38aa3b, v23
	v_exp_f32_e32 v6, v6
	v_add_f32_e32 v2, v3, v2
	v_fmamk_f32 v3, v11, 0x3e38aa3b, v23
	v_add_f32_e32 v2, v4, v2
	v_exp_f32_e32 v3, v3
	v_fmamk_f32 v4, v12, 0x3e38aa3b, v23
	v_add_f32_e32 v2, v5, v2
	v_exp_f32_e32 v4, v4
	v_fmamk_f32 v5, v13, 0x3e38aa3b, v23
	v_add_f32_e32 v2, v6, v2
	v_exp_f32_e32 v5, v5
	v_fmamk_f32 v6, v14, 0x3e38aa3b, v23
	v_exp_f32_e32 v6, v6
	v_add_f32_e32 v2, v3, v2
	v_add_f32_e32 v2, v4, v2
	v_fmamk_f32 v3, v15, 0x3e38aa3b, v23
	v_add_f32_e32 v2, v5, v2
	v_exp_f32_e32 v3, v3
	v_fmamk_f32 v4, v16, 0x3e38aa3b, v23
	v_fmac_f32_e32 v70, 0x3e38aa3b, v65
	v_sub_f32_e32 v53, v87, v69
	v_fmamk_f32 v19, v32, 0x3e38aa3b, v39
	v_add_f32_e32 v2, v6, v2
	v_exp_f32_e32 v4, v4
	v_fmac_f32_e32 v23, 0x3e38aa3b, v17
	v_sub_f32_e32 v6, v54, v22
	v_exp_f32_e32 v52, v70
	v_mul_f32_e32 v53, 0x3e38aa3b, v53
	v_exp_f32_e32 v19, v19
	v_fmac_f32_e32 v39, 0x3e38aa3b, v33
	v_sub_f32_e32 v21, v69, v38
	v_exp_f32_e32 v5, v23
	v_mul_f32_e32 v6, 0x3e38aa3b, v6
	v_exp_f32_e32 v53, v53
	v_exp_f32_e32 v20, v39
	v_mul_f32_e32 v21, 0x3e38aa3b, v21
	v_exp_f32_e32 v6, v6
	v_exp_f32_e32 v21, v21
	v_add_f32_e32 v2, v3, v2
	v_add_f32_e32 v50, v51, v50
	v_add_f32_e32 v2, v4, v2
	v_add_f32_e32 v50, v52, v50
	v_add_f32_e32 v18, v19, v18
	v_add_f32_e32 v2, v5, v2
	v_fmac_f32_e32 v50, v83, v53
	v_add_f32_e32 v18, v20, v18
	v_fmac_f32_e32 v2, v1, v6
	v_fmac_f32_e32 v18, v50, v21
	v_mov_b32_e32 v3, v2
	v_mov_b32_e32 v1, v18
	s_nop 0
	v_permlane32_swap_b32_e32 v2, v3
	v_permlane32_swap_b32_e32 v18, v1
	v_add_f32_e32 v2, v2, v3
	v_and_b32_e32 v3, 0x7fffffff, v159
	v_add_f32_e32 v1, v18, v1
	v_div_scale_f32 v4, s[34:35], v2, v2, v3
	v_log_f32_e32 v1, v1
	v_rcp_f32_e32 v5, v4
	s_addc_u32 s7, s45, s7
	s_lshl_b32 s38, s38, 1
	v_fma_f32 v188, v38, s69, -v1
	v_fma_f32 v1, -v4, v5, 1.0
	v_fmac_f32_e32 v5, v1, v5
	v_div_scale_f32 v1, vcc, v3, v2, v3
	v_mul_f32_e32 v3, v1, v5
	v_fma_f32 v7, -v4, v3, v1
	v_fmac_f32_e32 v3, v7, v5
	s_add_u32 s6, s2, s38
	v_fma_f32 v1, -v4, v3, v1
	s_addc_u32 s7, s7, 0
	v_div_fmas_f32 v1, v1, v5, v3
	v_div_fixup_f32 v1, v1, v2, |v159|
	v_lshl_add_u64 v[2:3], v[76:77], 1, s[6:7]
	v_lshlrev_b32_e32 v146, 1, v72
	v_lshl_add_u64 v[2:3], v[2:3], 0, v[146:147]
	v_add_co_u32_e32 v4, vcc, s66, v2
	v_lshlrev_b32_e32 v41, 1, v75
	s_nop 0
	v_addc_co_u32_e32 v5, vcc, 0, v3, vcc
	global_load_dwordx4 v[136:139], v[2:3], off
	global_load_dwordx4 v[140:143], v[4:5], off
	v_log_f32_e32 v187, v1
	v_and_b32_e32 v41, 32, v41
	s_cmp_lg_u32 s90, -1
	v_or3_b32 v37, v37, v41, v42
	s_cselect_b32 s2, s90, 0
	v_lshl_add_u32 v1, v35, 6, 0
	v_mov_b32_e32 v0, 0
	v_and_b32_e32 v6, 48, v74
	v_add_u32_e32 v146, s2, v37
	v_lshl_add_u32 v2, v34, 9, v1
	v_lshl_add_u32 v1, v36, 9, v1
	s_lshl_b32 s2, s48, 17
	v_fmac_f32_e32 v187, 0xbe38aa3b, v22
	s_add_u32 s2, s2, 0x20000
	v_sub_u32_e32 v191, v73, v164
	v_lshl_add_u64 v[150:151], s[8:9], 0, v[78:79]
	v_lshl_add_u64 v[152:153], s[10:11], 0, v[78:79]
	s_mov_b64 s[34:35], 0
	v_add_u32_e32 v189, v2, v6
	v_add_u32_e32 v190, v1, v6
	v_mov_b32_e32 v1, v0
	v_mov_b32_e32 v2, v0
	v_mov_b32_e32 v3, v0
	v_mov_b32_e32 v4, v0
	v_mov_b32_e32 v5, v0
	v_mov_b32_e32 v6, v0
	v_mov_b32_e32 v7, v0
	v_mov_b32_e32 v8, v0
	v_mov_b32_e32 v9, v0
	v_mov_b32_e32 v10, v0
	v_mov_b32_e32 v11, v0
	v_mov_b32_e32 v12, v0
	v_mov_b32_e32 v13, v0
	v_mov_b32_e32 v14, v0
	v_mov_b32_e32 v15, v0
	v_mov_b32_e32 v16, v0
	v_mov_b32_e32 v17, v0
	v_mov_b32_e32 v18, v0
	v_mov_b32_e32 v19, v0
	v_mov_b32_e32 v20, v0
	v_mov_b32_e32 v21, v0
	v_mov_b32_e32 v22, v0
	v_mov_b32_e32 v23, v0
	v_mov_b32_e32 v24, v0
	v_mov_b32_e32 v25, v0
	v_mov_b32_e32 v26, v0
	v_mov_b32_e32 v27, v0
	v_mov_b32_e32 v28, v0
	v_mov_b32_e32 v29, v0
	v_mov_b32_e32 v30, v0
	v_mov_b32_e32 v31, v0
	v_mov_b32_e32 v32, v0
	v_mov_b32_e32 v33, v0
	v_mov_b32_e32 v34, v0
	v_mov_b32_e32 v35, v0
	v_mov_b32_e32 v36, v0
	v_mov_b32_e32 v37, v0
	v_mov_b32_e32 v38, v0
	v_mov_b32_e32 v39, v0
	v_mov_b32_e32 v40, v0
	v_mov_b32_e32 v41, v0
	v_mov_b32_e32 v42, v0
	v_mov_b32_e32 v43, v0
	v_mov_b32_e32 v44, v0
	v_mov_b32_e32 v45, v0
	v_mov_b32_e32 v46, v0
	v_mov_b32_e32 v47, v0
	v_mov_b32_e32 v48, v0
	v_mov_b32_e32 v49, v0
	v_mov_b32_e32 v50, v0
	v_mov_b32_e32 v51, v0
	v_mov_b32_e32 v52, v0
	v_mov_b32_e32 v53, v0
	v_mov_b32_e32 v54, v0
	v_mov_b32_e32 v55, v0
	v_mov_b32_e32 v56, v0
	v_mov_b32_e32 v57, v0
	v_mov_b32_e32 v58, v0
	v_mov_b32_e32 v59, v0
	v_mov_b32_e32 v60, v0
	v_mov_b32_e32 v61, v0
	v_mov_b32_e32 v62, v0
	v_mov_b32_e32 v63, v0
	s_mov_b32 s93, s91
	s_branch .LBB0_310
; #define SBAR() __builtin_amdgcn_sched_barrier(0)
; template <int KS> __device__ __forceinline__ void pv_step(f32x16* o, int vb, bf16x8 pa) {
;   const s16x4 l0 = tr_read<v_rd_off(0, KS, 0)>(vb), h0 = tr_read<v_rd_off(0, KS, 1)>(vb), l1 = tr_read<v_rd_off(1, KS, 0)>(vb), h1 = tr_read<v_rd_off(1, KS, 1)>(vb);
;   const s16x4 l2 = tr_read<v_rd_off(2, KS, 0)>(vb), h2 = tr_read<v_rd_off(2, KS, 1)>(vb), l3 = tr_read<v_rd_off(3, KS, 0)>(vb), h3 = tr_read<v_rd_off(3, KS, 1)>(vb);
;   asm volatile("s_waitcnt lgkmcnt(0)" ::: "memory"); SBAR();
;     ...
;   o[0] = __builtin_amdgcn_mfma_f32_32x32x16_bf16(pa, PK(l0, h0), o[0], 0, 0, 0);
;   o[1] = __builtin_amdgcn_mfma_f32_32x32x16_bf16(pa, PK(l1, h1), o[1], 0, 0, 0);
;   o[2] = __builtin_amdgcn_mfma_f32_32x32x16_bf16(pa, PK(l2, h2), o[2], 0, 0, 0);
;   o[3] = __builtin_amdgcn_mfma_f32_32x32x16_bf16(pa, PK(l3, h3), o[3], 0, 0, 0);
; template <bool DIFF> ...
;     ...
;       BIAS_APPLY(t, 1, a1, b1, cb1);
;       { const float x1 = fmaf(cb1, C, e1), x2 = fmaf(cb1, C, e2);
; #pragma unroll
;       for (int r = 0; r < 16; ++r) a1[r] = __builtin_amdgcn_exp2f(fmaf(a1[r], C, x1));
;       if (DIFF) {
; #pragma unroll
;         for (int r = 0; r < 16; ++r) a1[r] = fmaf(nsg, __builtin_amdgcn_exp2f(fmaf(b1[r], C, x2)), a1[r]);
;       } }
;       PK4(a1, 0, pa2); PK4(a1, 8, pa3);
;       SBAR();
;       pv_step<2>(o, vb0, pa2); pv_step<3>(o, vb0, pa3);
.LBB0_309:
	s_waitcnt lgkmcnt(0)
	v_fmamk_f32 v97, v96, 0x3e38aa3b, v188
	v_fmamk_f32 v96, v96, 0x3e38aa3b, v187
	v_fmamk_f32 v80, v80, 0x3e38aa3b, v97
	v_fmamk_f32 v81, v81, 0x3e38aa3b, v97
	v_fmamk_f32 v82, v82, 0x3e38aa3b, v97
	v_fmamk_f32 v83, v83, 0x3e38aa3b, v97
	v_fmamk_f32 v84, v84, 0x3e38aa3b, v97
	v_fmamk_f32 v85, v85, 0x3e38aa3b, v97
	v_fmamk_f32 v86, v86, 0x3e38aa3b, v97
	v_fmamk_f32 v87, v87, 0x3e38aa3b, v97
	v_fmamk_f32 v88, v88, 0x3e38aa3b, v97
	v_fmamk_f32 v89, v89, 0x3e38aa3b, v97
	v_fmamk_f32 v90, v90, 0x3e38aa3b, v97
	v_fmamk_f32 v91, v91, 0x3e38aa3b, v97
	v_fmamk_f32 v92, v92, 0x3e38aa3b, v97
	v_fmamk_f32 v93, v93, 0x3e38aa3b, v97
	v_fmamk_f32 v94, v94, 0x3e38aa3b, v97
	v_fmac_f32_e32 v97, 0x3e38aa3b, v95
	v_fmamk_f32 v64, v64, 0x3e38aa3b, v96
	v_fmamk_f32 v65, v65, 0x3e38aa3b, v96
	v_fmamk_f32 v66, v66, 0x3e38aa3b, v96
	v_fmamk_f32 v67, v67, 0x3e38aa3b, v96
	v_fmamk_f32 v68, v68, 0x3e38aa3b, v96
	v_fmamk_f32 v69, v69, 0x3e38aa3b, v96
	v_fmamk_f32 v70, v70, 0x3e38aa3b, v96
	v_fmamk_f32 v71, v71, 0x3e38aa3b, v96
	v_fmamk_f32 v72, v72, 0x3e38aa3b, v96
	v_fmamk_f32 v73, v73, 0x3e38aa3b, v96
	v_fmamk_f32 v74, v74, 0x3e38aa3b, v96
	v_fmamk_f32 v75, v75, 0x3e38aa3b, v96
	v_fmamk_f32 v76, v76, 0x3e38aa3b, v96
	v_fmamk_f32 v77, v77, 0x3e38aa3b, v96
	v_fmamk_f32 v78, v78, 0x3e38aa3b, v96
	v_fmac_f32_e32 v96, 0x3e38aa3b, v79
	v_exp_f32_e32 v80, v80
	v_exp_f32_e32 v81, v81
	v_exp_f32_e32 v82, v82
	v_exp_f32_e32 v83, v83
	v_exp_f32_e32 v84, v84
	v_exp_f32_e32 v85, v85
	v_exp_f32_e32 v86, v86
	v_exp_f32_e32 v87, v87
	v_exp_f32_e32 v88, v88
	v_exp_f32_e32 v89, v89
	v_exp_f32_e32 v90, v90
	v_exp_f32_e32 v91, v91
	v_exp_f32_e32 v92, v92
	v_exp_f32_e32 v93, v93
	v_exp_f32_e32 v94, v94
	v_exp_f32_e32 v95, v97
	v_exp_f32_e32 v64, v64
	v_exp_f32_e32 v65, v65
	v_exp_f32_e32 v66, v66
	v_exp_f32_e32 v67, v67
	v_exp_f32_e32 v68, v68
	v_exp_f32_e32 v69, v69
	v_exp_f32_e32 v70, v70
	v_exp_f32_e32 v71, v71
	v_exp_f32_e32 v72, v72
	v_exp_f32_e32 v73, v73
	v_exp_f32_e32 v74, v74
	v_exp_f32_e32 v75, v75
	v_exp_f32_e32 v76, v76
	v_exp_f32_e32 v77, v77
	v_exp_f32_e32 v78, v78
	v_exp_f32_e32 v79, v96
	v_pk_fma_f32 v[64:65], v[144:145], v[64:65], v[80:81]
	v_pk_fma_f32 v[66:67], v[144:145], v[66:67], v[82:83]
	v_pk_fma_f32 v[68:69], v[144:145], v[68:69], v[84:85]
	v_pk_fma_f32 v[70:71], v[144:145], v[70:71], v[86:87]
	v_pk_fma_f32 v[72:73], v[144:145], v[72:73], v[88:89]
	v_pk_fma_f32 v[74:75], v[144:145], v[74:75], v[90:91]
	v_pk_fma_f32 v[76:77], v[144:145], v[76:77], v[92:93]
	v_pk_fma_f32 v[78:79], v[144:145], v[78:79], v[94:95]
	v_cvt_pk_bf16_f32 v64, v64, v65
	v_cvt_pk_bf16_f32 v65, v66, v67
	v_cvt_pk_bf16_f32 v66, v68, v69
	v_cvt_pk_bf16_f32 v67, v70, v71
	v_cvt_pk_bf16_f32 v68, v72, v73
	v_cvt_pk_bf16_f32 v69, v74, v75
	v_cvt_pk_bf16_f32 v70, v76, v77
	v_cvt_pk_bf16_f32 v71, v78, v79
	v_permlane32_swap_b32_e32 v64, v66
	v_permlane32_swap_b32_e32 v65, v67
	v_permlane32_swap_b32_e32 v68, v70
	v_permlane32_swap_b32_e32 v69, v71
	ds_read_b64_tr_b16 v[72:73], v146 offset:0x2000
	ds_read_b64_tr_b16 v[74:75], v146 offset:0x2800
	ds_read_b64_tr_b16 v[76:77], v146 offset:0x2200
	ds_read_b64_tr_b16 v[78:79], v146 offset:0x2a00
	ds_read_b64_tr_b16 v[80:81], v146 offset:0x2400
	ds_read_b64_tr_b16 v[82:83], v146 offset:0x2c00
	ds_read_b64_tr_b16 v[84:85], v146 offset:0x2600
	ds_read_b64_tr_b16 v[86:87], v146 offset:0x2e00
	s_waitcnt lgkmcnt(0)
	s_nop 0
	v_mfma_f32_32x32x16_bf16 v[0:15], v[64:67], v[72:75], v[0:15]
	ds_read_b64_tr_b16 v[72:73], v146 offset:0x3000
	ds_read_b64_tr_b16 v[74:75], v146 offset:0x3800
	v_mfma_f32_32x32x16_bf16 v[16:31], v[64:67], v[76:79], v[16:31]
	ds_read_b64_tr_b16 v[76:77], v146 offset:0x3200
	ds_read_b64_tr_b16 v[78:79], v146 offset:0x3a00
	v_mfma_f32_32x32x16_bf16 v[32:47], v[64:67], v[80:83], v[32:47]
	ds_read_b64_tr_b16 v[80:81], v146 offset:0x3400
	ds_read_b64_tr_b16 v[82:83], v146 offset:0x3c00
	ds_read_b64_tr_b16 v[88:89], v146 offset:0x3600
	ds_read_b64_tr_b16 v[90:91], v146 offset:0x3e00
	s_waitcnt lgkmcnt(0)
	v_mfma_f32_32x32x16_bf16 v[48:63], v[64:67], v[84:87], v[48:63]
	v_mfma_f32_32x32x16_bf16 v[0:15], v[68:71], v[72:75], v[0:15]
	s_add_u32 s34, s34, 0x20000
	s_addc_u32 s35, s35, 0
	v_add_u32_e32 v173, 64, v173
	s_add_i32 s93, s93, 64
	s_cmp_eq_u32 s2, s34
	v_mfma_f32_32x32x16_bf16 v[16:31], v[68:71], v[76:79], v[16:31]
	v_mfma_f32_32x32x16_bf16 v[32:47], v[68:71], v[80:83], v[32:47]
	v_mfma_f32_32x32x16_bf16 v[48:63], v[68:71], v[88:91], v[48:63]
	s_cbranch_scc1 .LBB0_326
; #define KLOAD(t) do { const bf16* kp_ = Kb + (size_t)((t) * 64 + sr) * 1024 + sc; ks0 = *reinterpret_cast<const bf16x8*>(kp_); ks1 = *reinterpret_cast<const bf16x8*>(kp_ + 32 * 1024); } while (0)
; #define VLOAD(t) do { const bf16* vp_ = Vb + (size_t)((t) * 64 + sr) * 1024 + sc; vs0 = *reinterpret_cast<const bf16x8*>(vp_); vs1 = *reinterpret_cast<const bf16x8*>(vp_ + 32 * 1024); } while (0)
; #define KWRITE() do { *reinterpret_cast<bf16x8*>(K_lds + kst0) = ks0; *reinterpret_cast<bf16x8*>(K_lds + kst1) = ks1; } while (0)
; #define VWRITE() do { *reinterpret_cast<bf16x8*>(V_lds + vst0) = vs0; *reinterpret_cast<bf16x8*>(V_lds + vst1) = vs1; } while (0)
; template <bool DIFF> ...
;     ...
;   for (int t = t_lo; t < t_hi; ++t) {
;     __syncthreads();
;     KWRITE(); VWRITE();
;     __syncthreads();
;     if (t + 1 < t_hi) { KLOAD(t + 1); VLOAD(t + 1); }
;     const bool active = DIFF || (t >= rstart && t < rstart + 8);
;     if (active) {
;       bf16x8 pa0, pa1, pa2, pa3;
;     ...
;       f32x16 a0, b0, a1, b1;
;       qkt<DIFF>(a0, b0, K_lds, Q_lds, r32, r32, hi);
;       qkt<DIFF>(a1, b1, K_lds, Q_lds, r32 + 32, r32, hi);
.LBB0_310:
	s_barrier
	s_waitcnt vmcnt(3)
	ds_write_b128 v174, v[128:131]
	s_waitcnt vmcnt(2)
	ds_write_b128 v175, v[132:135]
	s_waitcnt vmcnt(1)
	ds_write_b128 v189, v[136:139] offset:16384
	s_waitcnt vmcnt(0)
	ds_write_b128 v190, v[140:143] offset:16384
	s_waitcnt lgkmcnt(0)
	s_barrier
	ds_read_b128 v[64:67], v176
	ds_read_b128 v[68:71], v172 offset:36864
	ds_read_b128 v[72:75], v177
	ds_read_b128 v[76:79], v176 offset:8192
	s_waitcnt lgkmcnt(2)
	v_mfma_f32_32x32x16_bf16 v[112:127], v[64:67], v[68:71], 0
	ds_read_b128 v[64:67], v171 offset:36864
	ds_read_b128 v[128:131], v177 offset:8192
	s_waitcnt lgkmcnt(1)
	v_mfma_f32_32x32x16_bf16 v[96:111], v[72:75], v[64:67], 0
	ds_read_b128 v[72:75], v178
	ds_read_b128 v[132:135], v170 offset:36864
	ds_read_b128 v[80:83], v179
	ds_read_b128 v[136:139], v178 offset:8192
	ds_read_b128 v[140:143], v169 offset:36864
	ds_read_b128 v[192:195], v179 offset:8192
	s_waitcnt lgkmcnt(1)
	v_mfma_f32_32x32x16_bf16 v[96:111], v[80:83], v[140:143], v[96:111]
	v_mfma_f32_32x32x16_bf16 v[112:127], v[72:75], v[132:135], v[112:127]
	ds_read_b128 v[72:75], v180
	ds_read_b128 v[196:199], v168 offset:36864
	ds_read_b128 v[80:83], v181
	ds_read_b128 v[200:203], v180 offset:8192
	ds_read_b128 v[204:207], v167 offset:36864
	ds_read_b128 v[210:213], v181 offset:8192
	s_waitcnt lgkmcnt(1)
	v_mfma_f32_32x32x16_bf16 v[96:111], v[80:83], v[204:207], v[96:111]
	v_mfma_f32_32x32x16_bf16 v[112:127], v[72:75], v[196:199], v[112:127]
	ds_read_b128 v[72:75], v182
	ds_read_b128 v[214:217], v166 offset:36864
	ds_read_b128 v[80:83], v183
	ds_read_b128 v[218:221], v182 offset:8192
	ds_read_b128 v[222:225], v149 offset:36864
	ds_read_b128 v[226:229], v183 offset:8192
	s_waitcnt lgkmcnt(1)
	v_mfma_f32_32x32x16_bf16 v[96:111], v[80:83], v[222:225], v[96:111]
	v_mfma_f32_32x32x16_bf16 v[80:95], v[76:79], v[68:71], 0
	v_mfma_f32_32x32x16_bf16 v[112:127], v[72:75], v[214:217], v[112:127]
	v_mfma_f32_32x32x16_bf16 v[64:79], v[128:131], v[64:67], 0
	v_lshl_add_u64 v[128:129], v[150:151], 0, s[34:35]
	v_add_co_u32_e32 v130, vcc, s70, v128
	s_nop 1
	v_addc_co_u32_e32 v131, vcc, 0, v129, vcc
	v_mfma_f32_32x32x16_bf16 v[80:95], v[136:139], v[132:135], v[80:95]
	v_add_co_u32_e32 v132, vcc, s71, v128
	v_lshl_add_u64 v[136:137], v[152:153], 0, s[34:35]
	s_nop 0
	v_addc_co_u32_e32 v133, vcc, 0, v129, vcc
	v_add_co_u32_e32 v138, vcc, s72, v136
	v_mfma_f32_32x32x16_bf16 v[64:79], v[192:195], v[140:143], v[64:79]
	s_nop 0
	v_addc_co_u32_e32 v139, vcc, 0, v137, vcc
	v_add_co_u32_e32 v140, vcc, s73, v136
	global_load_dwordx4 v[128:131], v[130:131], off
	s_nop 0
	global_load_dwordx4 v[132:135], v[132:133], off
	v_addc_co_u32_e32 v141, vcc, 0, v137, vcc
	global_load_dwordx4 v[136:139], v[138:139], off
	s_nop 0
	global_load_dwordx4 v[140:143], v[140:141], off
	v_mfma_f32_32x32x16_bf16 v[80:95], v[200:203], v[196:199], v[80:95]
	v_mfma_f32_32x32x16_bf16 v[64:79], v[210:213], v[204:207], v[64:79]
	v_mfma_f32_32x32x16_bf16 v[80:95], v[218:221], v[214:217], v[80:95]
	s_waitcnt lgkmcnt(0)
	v_mfma_f32_32x32x16_bf16 v[64:79], v[226:229], v[222:225], v[64:79]
	s_cmpk_ge_i32 s93, 0x9f
	s_cbranch_scc1 .Lb2a_hi
	s_cmpk_le_i32 s93, 0xff41
	s_cbranch_scc1 .Lb2a_lo
	v_add3_u32 v192, v191, v173, s55
	v_med3_i32 v193, v192, 0, v163
	v_lshl_add_u32 v200, v193, 2, 0
	v_max_i32_e32 v193, -1, v192
	v_add_u32_e32 v193, 1, v193
	v_min_u32_e32 v193, 0x100, v193
	v_lshl_add_u32 v201, v193, 2, 0
	v_max_i32_e32 v193, -2, v192
	v_add_u32_e32 v193, 2, v193
	v_min_u32_e32 v193, 0x100, v193
	v_lshl_add_u32 v202, v193, 2, 0
	v_max_i32_e32 v193, -3, v192
	v_add_u32_e32 v193, 3, v193
	v_min_u32_e32 v193, 0x100, v193
	v_lshl_add_u32 v203, v193, 2, 0
	v_max_i32_e32 v193, -8, v192
	v_add_u32_e32 v193, 8, v193
	v_min_u32_e32 v193, 0x100, v193
	v_lshl_add_u32 v204, v193, 2, 0
	v_max_i32_e32 v193, -9, v192
	v_add_u32_e32 v193, 9, v193
	v_min_u32_e32 v193, 0x100, v193
	v_lshl_add_u32 v205, v193, 2, 0
	v_max_i32_e32 v193, -10, v192
	v_add_u32_e32 v193, 10, v193
	v_min_u32_e32 v193, 0x100, v193
	v_lshl_add_u32 v206, v193, 2, 0
	v_max_i32_e32 v193, -11, v192
	v_add_u32_e32 v193, 11, v193
	v_min_u32_e32 v193, 0x100, v193
	v_lshl_add_u32 v207, v193, 2, 0
	v_max_i32_e32 v193, -16, v192
	v_max_i32_e32 v194, 0xffffffef, v192
	v_max_i32_e32 v195, 0xffffffee, v192
	v_max_i32_e32 v196, 0xffffffed, v192
	v_max_i32_e32 v197, 0xffffffe8, v192
	v_max_i32_e32 v198, 0xffffffe7, v192
	v_max_i32_e32 v199, 0xffffffe6, v192
	v_add_u32_e32 v193, 16, v193
	v_add_u32_e32 v194, 17, v194
	v_add_u32_e32 v195, 18, v195
	v_add_u32_e32 v196, 19, v196
	v_add_u32_e32 v197, 24, v197
	v_add_u32_e32 v198, 25, v198
	v_add_u32_e32 v199, 26, v199
	v_max_i32_e32 v192, 0xffffffe5, v192
	v_min_u32_e32 v193, 0x100, v193
	v_min_u32_e32 v194, 0x100, v194
	v_min_u32_e32 v195, 0x100, v195
	v_min_u32_e32 v196, 0x100, v196
	v_min_u32_e32 v197, 0x100, v197
	v_min_u32_e32 v198, 0x100, v198
	v_min_u32_e32 v199, 0x100, v199
	v_add_u32_e32 v192, 27, v192
	v_lshl_add_u32 v193, v193, 2, 0
	v_lshl_add_u32 v194, v194, 2, 0
	v_lshl_add_u32 v195, v195, 2, 0
	v_lshl_add_u32 v196, v196, 2, 0
	v_lshl_add_u32 v197, v197, 2, 0
	v_lshl_add_u32 v198, v198, 2, 0
	v_lshl_add_u32 v199, v199, 2, 0
	v_min_u32_e32 v192, 0x100, v192
	v_lshl_add_u32 v209, v192, 2, 0
	ds_read_b32 v192, v193 offset:32768
	ds_read_b32 v193, v194 offset:32768
	ds_read_b32 v194, v195 offset:32768
	ds_read_b32 v195, v196 offset:32768
	ds_read_b32 v196, v197 offset:32768
	ds_read_b32 v197, v198 offset:32768
	ds_read_b32 v198, v199 offset:32768
	ds_read_b32 v199, v209 offset:32768
	ds_read_b32 v200, v200 offset:32768
	ds_read_b32 v201, v201 offset:32768
	ds_read_b32 v202, v202 offset:32768
	ds_read_b32 v203, v203 offset:32768
	ds_read_b32 v204, v204 offset:32768
	ds_read_b32 v205, v205 offset:32768
	ds_read_b32 v206, v206 offset:32768
	ds_read_b32 v207, v207 offset:32768
	s_waitcnt lgkmcnt(8)
	v_pk_add_f32 v[126:127], v[126:127], v[198:199]
	v_pk_add_f32 v[124:125], v[124:125], v[196:197]
	v_pk_add_f32 v[122:123], v[122:123], v[194:195]
	v_pk_add_f32 v[120:121], v[120:121], v[192:193]
	s_waitcnt lgkmcnt(0)
	v_pk_add_f32 v[118:119], v[118:119], v[206:207]
	v_pk_add_f32 v[116:117], v[116:117], v[204:205]
	v_pk_add_f32 v[114:115], v[114:115], v[202:203]
	v_pk_add_f32 v[112:113], v[112:113], v[200:201]
	v_pk_add_f32 v[110:111], v[110:111], v[198:199]
	v_pk_add_f32 v[108:109], v[108:109], v[196:197]
	v_pk_add_f32 v[106:107], v[106:107], v[194:195]
	v_pk_add_f32 v[104:105], v[104:105], v[192:193]
	v_pk_add_f32 v[102:103], v[102:103], v[206:207]
	v_pk_add_f32 v[100:101], v[100:101], v[204:205]
	v_pk_add_f32 v[98:99], v[98:99], v[202:203]
	v_pk_add_f32 v[96:97], v[96:97], v[200:201]
	v_mov_b32_e32 v192, 0
	s_branch .LBB0_318
; #define SBAR() __builtin_amdgcn_sched_barrier(0)
; template <bool DIFF> ...
;     ...
;       BIAS_APPLY(t, 0, a0, b0, cb0);
;       { const float x1 = fmaf(cb0, C, e1), x2 = fmaf(cb0, C, e2);
; #pragma unroll
;       for (int r = 0; r < 16; ++r) a0[r] = __builtin_amdgcn_exp2f(fmaf(a0[r], C, x1));
;       if (DIFF) {
; #pragma unroll
;         for (int r = 0; r < 16; ++r) a0[r] = fmaf(nsg, __builtin_amdgcn_exp2f(fmaf(b0[r], C, x2)), a0[r]);
;       } }
;       PK4(a0, 0, pa0); PK4(a0, 8, pa1);
;       SBAR();
;       pv_step<0>(o, vb0, pa0); pv_step<1>(o, vb0, pa1);
;       SBAR();
;       BIAS_APPLY(t, 1, a1, b1, cb1);
.Lb2a_hi:
	v_mov_b32_e32 v192, v253
	s_branch .LBB0_318
.Lb2a_lo:
	v_mov_b32_e32 v192, v252
.LBB0_318:
	s_waitcnt lgkmcnt(0)
	v_fmamk_f32 v193, v192, 0x3e38aa3b, v188
	v_fmamk_f32 v192, v192, 0x3e38aa3b, v187
	v_fmamk_f32 v112, v112, 0x3e38aa3b, v193
	v_fmamk_f32 v113, v113, 0x3e38aa3b, v193
	v_fmamk_f32 v114, v114, 0x3e38aa3b, v193
	v_fmamk_f32 v115, v115, 0x3e38aa3b, v193
	v_fmamk_f32 v116, v116, 0x3e38aa3b, v193
	v_fmamk_f32 v117, v117, 0x3e38aa3b, v193
	v_fmamk_f32 v96, v96, 0x3e38aa3b, v192
	v_fmamk_f32 v97, v97, 0x3e38aa3b, v192
	v_fmamk_f32 v98, v98, 0x3e38aa3b, v192
	v_fmamk_f32 v99, v99, 0x3e38aa3b, v192
	v_fmamk_f32 v100, v100, 0x3e38aa3b, v192
	v_fmamk_f32 v101, v101, 0x3e38aa3b, v192
	v_exp_f32_e32 v112, v112
	v_exp_f32_e32 v113, v113
	v_exp_f32_e32 v114, v114
	v_exp_f32_e32 v115, v115
	v_exp_f32_e32 v116, v116
	v_exp_f32_e32 v117, v117
	v_fmamk_f32 v118, v118, 0x3e38aa3b, v193
	v_fmamk_f32 v119, v119, 0x3e38aa3b, v193
	v_fmamk_f32 v120, v120, 0x3e38aa3b, v193
	v_fmamk_f32 v121, v121, 0x3e38aa3b, v193
	v_fmamk_f32 v122, v122, 0x3e38aa3b, v193
	v_fmamk_f32 v123, v123, 0x3e38aa3b, v193
	v_fmamk_f32 v124, v124, 0x3e38aa3b, v193
	v_fmamk_f32 v125, v125, 0x3e38aa3b, v193
	v_fmamk_f32 v126, v126, 0x3e38aa3b, v193
	v_fmac_f32_e32 v193, 0x3e38aa3b, v127
	v_exp_f32_e32 v96, v96
	v_exp_f32_e32 v97, v97
	v_exp_f32_e32 v98, v98
	v_exp_f32_e32 v99, v99
	v_exp_f32_e32 v100, v100
	v_exp_f32_e32 v101, v101
	v_fmamk_f32 v102, v102, 0x3e38aa3b, v192
	v_fmamk_f32 v103, v103, 0x3e38aa3b, v192
	v_fmamk_f32 v104, v104, 0x3e38aa3b, v192
	v_fmamk_f32 v105, v105, 0x3e38aa3b, v192
	v_fmamk_f32 v106, v106, 0x3e38aa3b, v192
	v_fmamk_f32 v107, v107, 0x3e38aa3b, v192
	v_fmamk_f32 v108, v108, 0x3e38aa3b, v192
	v_fmamk_f32 v109, v109, 0x3e38aa3b, v192
	v_fmamk_f32 v110, v110, 0x3e38aa3b, v192
	v_fmac_f32_e32 v192, 0x3e38aa3b, v111
	v_exp_f32_e32 v118, v118
	v_exp_f32_e32 v119, v119
	v_exp_f32_e32 v120, v120
	v_exp_f32_e32 v121, v121
	v_exp_f32_e32 v122, v122
	v_exp_f32_e32 v123, v123
	v_exp_f32_e32 v124, v124
	v_exp_f32_e32 v125, v125
	v_exp_f32_e32 v126, v126
	v_exp_f32_e32 v127, v193
	v_exp_f32_e32 v102, v102
	v_exp_f32_e32 v103, v103
	v_exp_f32_e32 v104, v104
	v_exp_f32_e32 v105, v105
	v_exp_f32_e32 v106, v106
	v_exp_f32_e32 v107, v107
	v_exp_f32_e32 v108, v108
	v_exp_f32_e32 v109, v109
	v_exp_f32_e32 v110, v110
	v_exp_f32_e32 v111, v192
	v_pk_fma_f32 v[96:97], v[144:145], v[96:97], v[112:113]
	v_pk_fma_f32 v[98:99], v[144:145], v[98:99], v[114:115]
	v_pk_fma_f32 v[100:101], v[144:145], v[100:101], v[116:117]
	v_pk_fma_f32 v[102:103], v[144:145], v[102:103], v[118:119]
	v_pk_fma_f32 v[104:105], v[144:145], v[104:105], v[120:121]
	v_pk_fma_f32 v[106:107], v[144:145], v[106:107], v[122:123]
	v_pk_fma_f32 v[108:109], v[144:145], v[108:109], v[124:125]
	v_pk_fma_f32 v[110:111], v[144:145], v[110:111], v[126:127]
	v_cvt_pk_bf16_f32 v96, v96, v97
	v_cvt_pk_bf16_f32 v97, v98, v99
	v_cvt_pk_bf16_f32 v98, v100, v101
	v_cvt_pk_bf16_f32 v99, v102, v103
	s_nop 0
	v_permlane32_swap_b32_e32 v96, v98
	v_cvt_pk_bf16_f32 v100, v104, v105
	v_cvt_pk_bf16_f32 v101, v106, v107
	v_cvt_pk_bf16_f32 v102, v108, v109
	v_cvt_pk_bf16_f32 v103, v110, v111
	v_permlane32_swap_b32_e32 v97, v99
	v_permlane32_swap_b32_e32 v100, v102
	v_permlane32_swap_b32_e32 v101, v103
	ds_read_b64_tr_b16 v[104:105], v146 offset:0
	ds_read_b64_tr_b16 v[106:107], v146 offset:0x800
	ds_read_b64_tr_b16 v[108:109], v146 offset:0x200
	ds_read_b64_tr_b16 v[110:111], v146 offset:0xa00
	ds_read_b64_tr_b16 v[112:113], v146 offset:0x400
	ds_read_b64_tr_b16 v[114:115], v146 offset:0xc00
	ds_read_b64_tr_b16 v[116:117], v146 offset:0x600
	ds_read_b64_tr_b16 v[118:119], v146 offset:0xe00
	s_waitcnt lgkmcnt(0)
	s_nop 0
	v_mfma_f32_32x32x16_bf16 v[0:15], v[96:99], v[104:107], v[0:15]
	ds_read_b64_tr_b16 v[104:105], v146 offset:0x1000
	ds_read_b64_tr_b16 v[106:107], v146 offset:0x1800
	v_mfma_f32_32x32x16_bf16 v[16:31], v[96:99], v[108:111], v[16:31]
	ds_read_b64_tr_b16 v[108:109], v146 offset:0x1200
	ds_read_b64_tr_b16 v[110:111], v146 offset:0x1a00
	v_mfma_f32_32x32x16_bf16 v[32:47], v[96:99], v[112:115], v[32:47]
	ds_read_b64_tr_b16 v[112:113], v146 offset:0x1400
	ds_read_b64_tr_b16 v[114:115], v146 offset:0x1c00
	ds_read_b64_tr_b16 v[120:121], v146 offset:0x1600
	ds_read_b64_tr_b16 v[122:123], v146 offset:0x1e00
	s_waitcnt lgkmcnt(0)
	v_mfma_f32_32x32x16_bf16 v[48:63], v[96:99], v[116:119], v[48:63]
	v_mfma_f32_32x32x16_bf16 v[0:15], v[100:103], v[104:107], v[0:15]
	v_mfma_f32_32x32x16_bf16 v[16:31], v[100:103], v[108:111], v[16:31]
	v_mfma_f32_32x32x16_bf16 v[32:47], v[100:103], v[112:115], v[32:47]
	v_mfma_f32_32x32x16_bf16 v[48:63], v[100:103], v[120:123], v[48:63]
	s_cmpk_ge_i32 s93, 0x9f
	s_cbranch_scc1 .Lb2b_hi
	s_cmpk_le_i32 s93, 0xff41
	s_cbranch_scc1 .Lb2b_lo
	v_add3_u32 v96, v191, v173, s63
	v_med3_i32 v97, v96, 0, v163
	v_lshl_add_u32 v104, v97, 2, 0
	v_max_i32_e32 v97, -1, v96
	v_add_u32_e32 v97, 1, v97
	v_min_u32_e32 v97, 0x100, v97
	v_lshl_add_u32 v105, v97, 2, 0
	v_max_i32_e32 v97, -2, v96
	v_add_u32_e32 v97, 2, v97
	v_min_u32_e32 v97, 0x100, v97
	v_lshl_add_u32 v106, v97, 2, 0
	v_max_i32_e32 v97, -3, v96
	v_add_u32_e32 v97, 3, v97
	v_min_u32_e32 v97, 0x100, v97
	v_lshl_add_u32 v107, v97, 2, 0
	v_max_i32_e32 v97, -8, v96
	v_add_u32_e32 v97, 8, v97
	v_min_u32_e32 v97, 0x100, v97
	v_lshl_add_u32 v108, v97, 2, 0
	v_max_i32_e32 v97, -9, v96
	v_add_u32_e32 v97, 9, v97
	v_min_u32_e32 v97, 0x100, v97
	v_lshl_add_u32 v109, v97, 2, 0
	v_max_i32_e32 v97, -10, v96
	v_add_u32_e32 v97, 10, v97
	v_min_u32_e32 v97, 0x100, v97
	v_lshl_add_u32 v110, v97, 2, 0
	v_max_i32_e32 v97, -11, v96
	v_add_u32_e32 v97, 11, v97
	v_min_u32_e32 v97, 0x100, v97
	v_lshl_add_u32 v111, v97, 2, 0
	v_max_i32_e32 v97, -16, v96
	v_max_i32_e32 v98, 0xffffffef, v96
	v_max_i32_e32 v99, 0xffffffee, v96
	v_max_i32_e32 v100, 0xffffffed, v96
	v_max_i32_e32 v101, 0xffffffe8, v96
	v_max_i32_e32 v102, 0xffffffe7, v96
	v_max_i32_e32 v103, 0xffffffe6, v96
	v_add_u32_e32 v97, 16, v97
	v_add_u32_e32 v98, 17, v98
	v_add_u32_e32 v99, 18, v99
	v_add_u32_e32 v100, 19, v100
	v_add_u32_e32 v101, 24, v101
	v_add_u32_e32 v102, 25, v102
	v_add_u32_e32 v103, 26, v103
	v_max_i32_e32 v96, 0xffffffe5, v96
	v_min_u32_e32 v97, 0x100, v97
	v_min_u32_e32 v98, 0x100, v98
	v_min_u32_e32 v99, 0x100, v99
	v_min_u32_e32 v100, 0x100, v100
	v_min_u32_e32 v101, 0x100, v101
	v_min_u32_e32 v102, 0x100, v102
	v_min_u32_e32 v103, 0x100, v103
	v_add_u32_e32 v96, 27, v96
	v_lshl_add_u32 v97, v97, 2, 0
	v_lshl_add_u32 v98, v98, 2, 0
	v_lshl_add_u32 v99, v99, 2, 0
	v_lshl_add_u32 v100, v100, 2, 0
	v_lshl_add_u32 v101, v101, 2, 0
	v_lshl_add_u32 v102, v102, 2, 0
	v_lshl_add_u32 v103, v103, 2, 0
	v_min_u32_e32 v96, 0x100, v96
	v_lshl_add_u32 v112, v96, 2, 0
	ds_read_b32 v96, v97 offset:32768
	ds_read_b32 v97, v98 offset:32768
	ds_read_b32 v98, v99 offset:32768
	ds_read_b32 v99, v100 offset:32768
	ds_read_b32 v100, v101 offset:32768
	ds_read_b32 v101, v102 offset:32768
	ds_read_b32 v102, v103 offset:32768
	ds_read_b32 v103, v112 offset:32768
	ds_read_b32 v104, v104 offset:32768
	ds_read_b32 v105, v105 offset:32768
	ds_read_b32 v106, v106 offset:32768
	ds_read_b32 v107, v107 offset:32768
	ds_read_b32 v108, v108 offset:32768
	ds_read_b32 v109, v109 offset:32768
	ds_read_b32 v110, v110 offset:32768
	ds_read_b32 v111, v111 offset:32768
	s_waitcnt lgkmcnt(8)
	v_pk_add_f32 v[94:95], v[94:95], v[102:103]
	v_pk_add_f32 v[92:93], v[92:93], v[100:101]
	v_pk_add_f32 v[90:91], v[90:91], v[98:99]
	v_pk_add_f32 v[88:89], v[88:89], v[96:97]
	s_waitcnt lgkmcnt(0)
	v_pk_add_f32 v[86:87], v[86:87], v[110:111]
	v_pk_add_f32 v[84:85], v[84:85], v[108:109]
	v_pk_add_f32 v[82:83], v[82:83], v[106:107]
	v_pk_add_f32 v[80:81], v[80:81], v[104:105]
	v_pk_add_f32 v[78:79], v[78:79], v[102:103]
	v_pk_add_f32 v[76:77], v[76:77], v[100:101]
	v_pk_add_f32 v[74:75], v[74:75], v[98:99]
	v_pk_add_f32 v[72:73], v[72:73], v[96:97]
	v_pk_add_f32 v[70:71], v[70:71], v[110:111]
	v_pk_add_f32 v[68:69], v[68:69], v[108:109]
	v_pk_add_f32 v[66:67], v[66:67], v[106:107]
	v_pk_add_f32 v[64:65], v[64:65], v[104:105]
	v_mov_b32_e32 v96, 0
	s_branch .LBB0_309
.Lb2b_hi:
	v_mov_b32_e32 v96, v253
	s_branch .LBB0_309
.Lb2b_lo:
	v_mov_b32_e32 v96, v252
	s_branch .LBB0_309

; #define AIN(i) ((const float*)ldarg(i))
; #define G lgrid()
; __global__ void __launch_bounds__(NTHR, 2) mega_fwd(Args a_unused) {
;     ...
; #pragma unroll 1
;     for (int v = vcu; v < 1536; v += G) {
;       int s, h, rb, rows;
;       if (v < 1024) { rb = v & 15; const int bh = v >> 4; h = bh & 7; s = 8 + (bh >> 3); rows = 64; }
;       else { const int w = v - 1024; rb = w & 7; const int bh = w >> 3; h = bh & 7; s = bh >> 3; rows = 32; }
;       const size_t mbase = s < 8 ? (size_t)s * 2048 : (size_t)TP + (size_t)(s - 8) * 4096;
;       int tl = 4 * rb - 4; tl = tl < 0 ? 0 : (tl > rows - 8 ? rows - 8 : tl);
;       int th = 4 * rb + 3 - 4; th = th < 0 ? 0 : (th > rows - 8 ? rows - 8 : th); th += 8;
;       att::attn_unit<false>(QB + (mbase + 256 * rb) * 1024 + 128 * h, KB + mbase * 1024 + 128 * h, VB + mbase * 1024 + 128 * h,
;                             O + (mbase + 256 * rb) * 2048 + 1024 + 128 * h, tl, th, 4 * rb, rows, 0.f, AIN(13), h, nullptr, (char*)lds);
.LBB0_345:
	s_add_u32 s48, s12, 0x2ba00000
	s_addc_u32 s49, s13, 0
	s_load_dwordx2 s[56:57], s[0:1], 0x100
	s_add_u32 s91, s14, 0x31a00000
	s_addc_u32 s92, s15, 0
	s_add_u32 s93, s16, 0x37a00000
	s_addc_u32 s94, s17, 0
	s_mov_b32 s45, 0
	s_mov_b32 s46, 0x413504f3
	v_mov_b32_e32 v1, 0
	s_movk_i32 s95, 0xf0
	s_mov_b32 s96, 0x10000
	s_movk_i32 s97, 0x7fff
	v_readlane_b32 s54, v255, 0
	s_branch .LBB0_347

; __device__ __forceinline__ int v_st(int k, int c) { const int kk = (k & ~0xC) | ((k & 4) << 1) | ((k & 8) >> 1); return ((kk >> 3) * 4 + (c >> 5)) * 512 + ((kk & 7) * 32 + (c & 31)) * 2; }
; __device__ __forceinline__ int v_rd_base(int lane) { return ((lane & 3) << 3) | (((lane >> 2) & 3) << 6) | (((lane >> 4) & 1) << 5) | (((lane >> 5) & 1) << 8); }
; #define tid ltid()
; template <bool DIFF> ...
;   int tid = threadIdx.x; asm volatile("" : "+v"(tid)); const int wid = tid >> 6, lane = tid & 63, r32 = lane & 31, hi = lane >> 5;
;   char* K_lds = lds; char* V_lds = lds + 16384; float* tab = (float*)(lds + 32768);
;   constexpr float SCALE = DIFF ? 0.125f : 0.08838834764831845f;
;   constexpr float C = SCALE * 1.4426950408889634f;
;   __syncthreads();
;   if (DIFF) { for (int i = tid; i < 257; i += 512) tab[i] = tabg[t5_bucket(i - 128) * 8 + head] * 8.0f; }
;   else      { for (int i = tid; i < 465; i += 512) tab[i] = tabg[head * 465 + i] * 11.313708498984761f; }
;   char* Q_lds = lds + 36864 + wid * 8192;
;   { const bf16* Qw = Qb + (size_t)(wid * 32 + r32) * 1024 + hi * 8;
; #pragma unroll
;     for (int d0 = 0; d0 < 8; ++d0) *reinterpret_cast<bf16x8*>(Q_lds + KSWZ(r32, (d0 * 16 + hi * 8) * 2)) = *reinterpret_cast<const bf16x8*>(Qw + d0 * 16); }
;   const int sr = tid >> 4, sc = (tid & 15) * 8;
;   const int vst0 = v_st(sr, sc), vst1 = v_st(32 + sr, sc), kst0 = KSWZ(sr, sc * 2), kst1 = KSWZ(32 + sr, sc * 2);
;   const int vb0 = (int)(uintptr_t)V_lds + v_rd_base(lane);
;   int rw = 0, rstart = 0;
;   if (!DIFF) { rw = q0 + (wid >> 1); rstart = rw - 4; rstart = rstart < 0 ? 0 : rstart; rstart = rstart > rows - 8 ? rows - 8 : rstart; }
;   const int qbase = q0 + wid * 32;
;   float m1 = -1e30f, l1 = 0.f, m2 = -1e30f, l2 = 0.f;
;   bf16x8 ks0, ks1, vs0, vs1;
; __global__ void __launch_bounds__(NTHR, 2) mega_fwd(Args a_unused) {
;     ...
;       if (v < 1024) { rb = v & 15; const int bh = v >> 4; h = bh & 7; s = 8 + (bh >> 3); rows = 64; }
;       else { const int w = v - 1024; rb = w & 7; const int bh = w >> 3; h = bh & 7; s = bh >> 3; rows = 32; }
;       const size_t mbase = s < 8 ? (size_t)s * 2048 : (size_t)TP + (size_t)(s - 8) * 4096;
;       int tl = 4 * rb - 4; tl = tl < 0 ? 0 : (tl > rows - 8 ? rows - 8 : tl);
;       int th = 4 * rb + 3 - 4; th = th < 0 ? 0 : (th > rows - 8 ? rows - 8 : th); th += 8;
.LBB0_365:
	s_or_b64 exec, exec, s[6:7]
	s_lshl_b32 s41, s17, 2
	s_add_i32 s6, s41, -1
	s_add_i32 s2, s41, -4
	s_min_i32 s6, s6, s16
	s_min_i32 s2, s2, s16
	s_add_i32 s6, s6, 8
	s_cmp_eq_u32 s17, 0
	s_cselect_b32 s40, 0, s2
	s_cselect_b32 s2, 8, s6
	s_lshl_b32 s6, s17, 8
	s_add_u32 s52, s4, s6
	s_addc_u32 s53, s5, 0
	s_lshl_b64 s[6:7], s[52:53], 11
	v_ashrrev_i32_e32 v3, 6, v2
	s_add_u32 s6, s48, s6
	v_and_b32_e32 v155, 31, v2
	v_lshlrev_b32_e32 v146, 5, v3
	s_addc_u32 s7, s49, s7
	s_lshl_b32 s44, s18, 7
	s_waitcnt lgkmcnt(0)
	s_lshl_b32 s8, s18, 8
	v_or_b32_e32 v4, v146, v155
	s_add_u32 s6, s6, s8
	v_ashrrev_i32_e32 v5, 31, v4
	s_addc_u32 s7, s7, 0
	v_bfe_u32 v154, v2, 5, 1
	v_lshlrev_b64 v[4:5], 11, v[4:5]
	v_lshl_add_u64 v[4:5], s[6:7], 0, v[4:5]
	v_lshlrev_b32_e32 v0, 4, v154
	v_lshl_add_u64 v[4:5], v[4:5], 0, v[0:1]
	global_load_dwordx4 v[12:15], v[4:5], off
	global_load_dwordx4 v[20:23], v[4:5], off offset:32
	global_load_dwordx4 v[24:27], v[4:5], off offset:64
	global_load_dwordx4 v[28:31], v[4:5], off offset:96
	global_load_dwordx4 v[32:35], v[4:5], off offset:128
	global_load_dwordx4 v[36:39], v[4:5], off offset:160
	global_load_dwordx4 v[40:43], v[4:5], off offset:192
	global_load_dwordx4 v[44:47], v[4:5], off offset:224
	v_and_b32_e32 v5, 0x3fffffc0, v2
	v_lshl_add_u32 v3, v3, 13, 0
	v_lshlrev_b32_e32 v18, 8, v155
	v_and_b32_e32 v147, 63, v2
	v_lshlrev_b32_e32 v4, 4, v2
	v_bitop3_b32 v16, v154, v2, 15 bitop3:0x78
	v_lshl_add_u32 v156, v5, 2, 0
	v_add_u32_e32 v17, v3, v18
	v_and_b32_e32 v11, 0xf0, v4
	v_cmp_gt_u32_e64 s[38:39], 32, v147
	v_or_b32_e32 v8, 32, v0
	v_or_b32_e32 v6, 64, v0
	v_or_b32_e32 v4, 0x60, v0
	v_or_b32_e32 v10, 0x80, v0
	v_or_b32_e32 v9, 0xa0, v0
	v_or_b32_e32 v7, 0xc0, v0
	v_or_b32_e32 v5, 0xe0, v0
	v_lshl_add_u32 v16, v16, 4, v17
	s_cmp_lt_i32 s40, s2
	v_lshl_add_u32 v157, v155, 2, v156
	v_xad_u32 v19, v8, v11, v17
	v_xad_u32 v48, v6, v11, v17
	v_xad_u32 v49, v4, v11, v17
	v_xad_u32 v50, v10, v11, v17
	v_xad_u32 v51, v9, v11, v17
	v_xad_u32 v52, v7, v11, v17
	v_xad_u32 v11, v5, v11, v17
	s_waitcnt vmcnt(7)
	ds_write_b128 v16, v[12:15] offset:36864
	s_waitcnt vmcnt(6)
	ds_write_b128 v19, v[20:23] offset:36864
	s_waitcnt vmcnt(5)
	ds_write_b128 v48, v[24:27] offset:36864
	s_waitcnt vmcnt(4)
	ds_write_b128 v49, v[28:31] offset:36864
	s_waitcnt vmcnt(3)
	ds_write_b128 v50, v[32:35] offset:36864
	s_waitcnt vmcnt(2)
	ds_write_b128 v51, v[36:39] offset:36864
	s_waitcnt vmcnt(1)
	ds_write_b128 v52, v[40:43] offset:36864
	s_waitcnt vmcnt(0)
	ds_write_b128 v11, v[44:47] offset:36864
	s_cbranch_scc0 .LBB0_444
	s_lshl_b64 s[4:5], s[4:5], 11
	s_add_u32 s6, s91, s4
	s_addc_u32 s7, s92, s5
	s_lshl_b32 s8, s44, 1
	s_add_u32 s6, s6, s8
	s_addc_u32 s7, s7, 0
	s_add_u32 s4, s93, s4
	s_addc_u32 s5, s94, s5
	v_lshlrev_b32_e32 v15, 4, v147
	s_add_u32 s4, s4, s8
	v_lshlrev_b32_e32 v13, 3, v147
	v_and_b32_e32 v15, 0xc0, v15
	v_lshlrev_b32_e32 v16, 1, v147
	s_addc_u32 s5, s5, 0
	v_and_or_b32 v15, v13, 24, v15
	v_and_b32_e32 v16, 32, v16
	v_and_b32_e32 v13, 0x100, v13
	v_ashrrev_i32_e32 v19, 7, v2
	v_ashrrev_i32_e32 v11, 4, v2
	v_or3_b32 v13, v15, v16, v13
	v_add_u32_e32 v15, s41, v19
	s_cmp_lg_u32 s90, -1
	v_max_i32_e32 v15, 4, v15
	s_cselect_b32 s8, s90, 0
	v_add_u32_e32 v24, 32, v11
	v_add_u32_e32 v158, s8, v13
	v_add_u32_e32 v13, -4, v15
	v_lshlrev_b32_e32 v15, 1, v24
	v_and_b32_e32 v16, 0xfffff0, v24
	v_lshlrev_b32_e32 v14, 3, v2
	v_and_or_b32 v15, v15, 8, v16
	v_and_b32_e32 v12, 0x78, v14
	v_lshrrev_b32_e32 v15, 1, v15
	v_bfe_u32 v14, v14, 5, 2
	v_or_b32_e32 v25, v15, v14
	v_lshlrev_b32_e32 v15, 1, v11
	v_and_b32_e32 v16, 0xfffff0, v11
	v_and_or_b32 v15, v15, 8, v16
	v_lshlrev_b32_e32 v12, 1, v12
	v_lshrrev_b32_e32 v15, 1, v15
	v_or_b32_e32 v27, v15, v14
	v_bitop3_b32 v28, v12, v2, s95 bitop3:0x78
	v_lshrrev_b32_e32 v2, 1, v11
	v_and_b32_e32 v14, 3, v11
	v_and_or_b32 v2, v2, 4, v14
	v_lshl_add_u32 v14, s40, 6, v11
	v_ashrrev_i32_e32 v15, 31, v14
	v_lshlrev_b64 v[16:17], 11, v[14:15]
	v_min_u32_e32 v159, s16, v13
	v_mov_b32_e32 v13, v1
	v_lshl_add_u64 v[20:21], s[4:5], 0, v[16:17]
	v_lshl_add_u64 v[20:21], v[20:21], 0, v[12:13]
	v_add_co_u32_e32 v22, vcc, s96, v20
	v_lshl_add_u64 v[16:17], s[6:7], 0, v[16:17]
	v_lshl_add_u64 v[148:149], s[6:7], 0, v[12:13]
	v_lshl_add_u64 v[150:151], s[4:5], 0, v[12:13]
	v_and_b32_e32 v26, 48, v12
	v_addc_co_u32_e32 v23, vcc, 0, v21, vcc
	v_lshl_add_u64 v[12:13], v[16:17], 0, v[12:13]
	v_add_co_u32_e32 v16, vcc, s96, v12
	global_load_dwordx4 v[142:145], v[22:23], off
	global_load_dwordx4 v[134:137], v[20:21], off
	v_addc_co_u32_e32 v17, vcc, 0, v13, vcc
	global_load_dwordx4 v[138:141], v[16:17], off
	global_load_dwordx4 v[130:133], v[12:13], off
	v_lshl_add_u32 v2, v2, 6, 0
	v_lshl_add_u32 v22, v27, 9, v2
	v_lshl_add_u32 v23, v25, 9, v2
	v_lshlrev_b32_e32 v2, 4, v155
	v_bitop3_b32 v162, v0, v2, s95 bitop3:0x78
	v_bitop3_b32 v163, v10, v2, s95 bitop3:0x78
	v_bitop3_b32 v164, v8, v2, s95 bitop3:0x78
	v_bitop3_b32 v165, v9, v2, s95 bitop3:0x78
	v_bitop3_b32 v166, v6, v2, s95 bitop3:0x78
	v_bitop3_b32 v167, v7, v2, s95 bitop3:0x78
	v_bitop3_b32 v168, v4, v2, s95 bitop3:0x78
	v_bitop3_b32 v169, v5, v2, s95 bitop3:0x78
	v_and_b32_e32 v2, 32, v146
; __device__ __forceinline__ int v_st(int k, int c) { const int kk = (k & ~0xC) | ((k & 4) << 1) | ((k & 8) >> 1); return ((kk >> 3) * 4 + (c >> 5)) * 512 + ((kk & 7) * 32 + (c & 31)) * 2; }
; __device__ __forceinline__ int v_rd_base(int lane) { return ((lane & 3) << 3) | (((lane >> 2) & 3) << 6) | (((lane >> 4) & 1) << 5) | (((lane >> 5) & 1) << 8); }
; #define KLOAD(t) do { const bf16* kp_ = Kb + (size_t)((t) * 64 + sr) * 1024 + sc; ks0 = *reinterpret_cast<const bf16x8*>(kp_); ks1 = *reinterpret_cast<const bf16x8*>(kp_ + 32 * 1024); } while (0)
; #define VLOAD(t) do { const bf16* vp_ = Vb + (size_t)((t) * 64 + sr) * 1024 + sc; vs0 = *reinterpret_cast<const bf16x8*>(vp_); vs1 = *reinterpret_cast<const bf16x8*>(vp_ + 32 * 1024); } while (0)
; #define tid ltid()
; template <bool DIFF> ...
;     ...
;   const int sr = tid >> 4, sc = (tid & 15) * 8;
;   const int vst0 = v_st(sr, sc), vst1 = v_st(32 + sr, sc), kst0 = KSWZ(sr, sc * 2), kst1 = KSWZ(32 + sr, sc * 2);
;   const int vb0 = (int)(uintptr_t)V_lds + v_rd_base(lane);
;   int rw = 0, rstart = 0;
;   if (!DIFF) { rw = q0 + (wid >> 1); rstart = rw - 4; rstart = rstart < 0 ? 0 : rstart; rstart = rstart > rows - 8 ? rows - 8 : rstart; }
;   const int qbase = q0 + wid * 32;
;   float m1 = -1e30f, l1 = 0.f, m2 = -1e30f, l2 = 0.f;
;   bf16x8 ks0, ks1, vs0, vs1;
;     ...
;   f32x16 o[4];
; #pragma unroll
;   for (int d = 0; d < 4; ++d) o[d] = f32x16{};
;   KLOAD(t_lo); VLOAD(t_lo);
	v_lshl_add_u32 v21, v24, 8, 0
	v_add_u32_e32 v24, v3, v162
	v_add_u32_e32 v25, v3, v163
	v_add_u32_e32 v27, v3, v164
	v_add_u32_e32 v29, v3, v165
	v_add_u32_e32 v30, v3, v166
	v_add_u32_e32 v31, v3, v167
	v_add_u32_e32 v32, v3, v168
	v_add_u32_e32 v33, v3, v169
	v_or_b32_e32 v3, v2, v155
	v_med3_u32 v3, v3, 8, 56
	v_lshlrev_b32_e32 v5, 2, v154
	v_add_u32_e32 v4, -8, v3
	v_or_b32_e32 v7, 1, v5
	v_cmp_ge_u32_e64 s[6:7], v7, v4
	v_or_b32_e32 v7, 2, v5
	v_cmp_ge_u32_e64 s[8:9], v7, v4
	v_or_b32_e32 v7, 3, v5
	v_cmp_ge_u32_e64 s[10:11], v7, v4
	v_or_b32_e32 v7, 8, v5
	v_cmp_ge_u32_e64 s[12:13], v7, v4
	v_or_b32_e32 v7, 9, v5
	v_cmp_ge_u32_e64 s[14:15], v7, v4
	v_or_b32_e32 v7, 10, v5
	v_cmp_ge_u32_e64 s[16:17], v7, v4
	v_or_b32_e32 v7, 11, v5
	v_add_u32_e32 v6, 8, v3
	v_cmp_ge_u32_e64 s[18:19], v7, v4
	v_or_b32_e32 v7, 16, v5
	v_cmp_ge_u32_e32 vcc, v7, v4
	v_cmp_lt_u32_e64 s[20:21], v7, v6
	v_or_b32_e32 v7, 17, v5
	s_and_b64 s[54:55], vcc, s[20:21]
	v_cmp_ge_u32_e32 vcc, v7, v4
	v_cmp_lt_u32_e64 s[20:21], v7, v6
	v_or_b32_e32 v7, 18, v5
	s_and_b64 s[56:57], vcc, s[20:21]
	v_cmp_ge_u32_e32 vcc, v7, v4
	v_cmp_lt_u32_e64 s[20:21], v7, v6
	v_or_b32_e32 v7, 19, v5
	s_and_b64 s[58:59], vcc, s[20:21]
	v_cmp_ge_u32_e32 vcc, v7, v4
	v_cmp_lt_u32_e64 s[20:21], v7, v6
	v_or_b32_e32 v7, 24, v5
	s_and_b64 s[60:61], vcc, s[20:21]
	v_cmp_ge_u32_e32 vcc, v7, v4
	v_cmp_lt_u32_e64 s[20:21], v7, v6
	v_or_b32_e32 v8, 25, v5
	s_and_b64 s[62:63], vcc, s[20:21]
	v_cmp_ge_u32_e32 vcc, v8, v4
	v_cmp_lt_u32_e64 s[20:21], v8, v6
	v_or_b32_e32 v9, 26, v5
	s_and_b64 s[64:65], vcc, s[20:21]
	v_cmp_ge_u32_e32 vcc, v9, v4
	v_cmp_lt_u32_e64 s[20:21], v9, v6
	v_or_b32_e32 v10, 27, v5
	s_and_b64 s[66:67], vcc, s[20:21]
	v_cmp_ge_u32_e32 vcc, v10, v4
	v_cmp_lt_u32_e64 s[20:21], v10, v6
	v_or_b32_e32 v6, 32, v5
	s_and_b64 s[68:69], vcc, s[20:21]
	v_cmp_ge_u32_e32 vcc, v6, v4
	v_cmp_lt_u32_e64 s[20:21], v7, v3
	v_or_b32_e32 v7, 33, v5
	s_and_b64 s[70:71], vcc, s[20:21]
	v_cmp_ge_u32_e32 vcc, v7, v4
	v_cmp_lt_u32_e64 s[20:21], v8, v3
	v_or_b32_e32 v8, 34, v5
	s_and_b64 s[72:73], vcc, s[20:21]
	v_cmp_ge_u32_e32 vcc, v8, v4
	v_cmp_lt_u32_e64 s[20:21], v9, v3
	v_or_b32_e32 v9, 35, v5
	s_and_b64 s[74:75], vcc, s[20:21]
	v_cmp_ge_u32_e32 vcc, v9, v4
	v_cmp_lt_u32_e64 s[20:21], v10, v3
	v_or_b32_e32 v10, 40, v5
	s_and_b64 s[76:77], vcc, s[20:21]
	v_cmp_ge_u32_e32 vcc, v10, v4
	v_cmp_lt_u32_e64 s[20:21], v6, v3
	v_or_b32_e32 v6, 41, v5
	s_and_b64 s[78:79], vcc, s[20:21]
	v_cmp_ge_u32_e32 vcc, v6, v4
	v_cmp_lt_u32_e64 s[20:21], v7, v3
	v_or_b32_e32 v7, 42, v5
	s_and_b64 s[80:81], vcc, s[20:21]
	v_cmp_ge_u32_e32 vcc, v7, v4
	v_cmp_lt_u32_e64 s[20:21], v8, v3
	v_or_b32_e32 v8, 43, v5
	v_cmp_ge_u32_e64 s[4:5], v5, v4
	s_and_b64 s[82:83], vcc, s[20:21]
	v_cmp_ge_u32_e32 vcc, v8, v4
	v_cmp_lt_u32_e64 s[20:21], v9, v3
	v_or_b32_e32 v4, 48, v5
	v_cmp_lt_u32_e64 s[22:23], v6, v3
	v_or_b32_e32 v6, 49, v5
	v_cmp_lt_u32_e64 s[24:25], v7, v3
	v_or_b32_e32 v7, 50, v5
	v_cmp_lt_u32_e64 s[26:27], v8, v3
	v_or_b32_e32 v8, 51, v5
	s_and_b64 s[84:85], vcc, s[20:21]
	v_cmp_lt_u32_e64 s[20:21], v10, v3
	v_cmp_lt_u32_e64 s[28:29], v4, v3
	v_cmp_lt_u32_e64 s[30:31], v6, v3
	v_cmp_lt_u32_e64 s[34:35], v7, v3
	v_cmp_lt_u32_e64 s[36:37], v8, v3
	v_sub_u32_e32 v3, s40, v19
	v_sub_u32_e32 v4, v5, v155
	v_subrev_u32_e32 v3, s41, v3
	s_movk_i32 s41, 0x7c
	v_sub_u32_e32 v2, v4, v2
	v_lshl_add_u32 v20, v11, 8, 0
	v_mul_lo_u32 v3, v3, s41
	v_lshlrev_b32_e32 v2, 2, v2
	s_add_i32 s41, 0, 0x83a0
	v_mov_b32_e32 v16, v1
	v_mov_b32_e32 v17, v1
	v_add_u32_e32 v161, 0, v18
	v_add3_u32 v170, v3, v2, s41
	v_add_u32_e32 v152, 64, v14
	v_mov_b32_e32 v2, v1
	v_mov_b32_e32 v3, v1
	v_mov_b32_e32 v4, v1
	v_mov_b32_e32 v5, v1
	v_mov_b32_e32 v6, v1
	v_mov_b32_e32 v7, v1
	v_mov_b32_e32 v8, v1
	v_mov_b32_e32 v9, v1
	v_mov_b32_e32 v10, v1
	v_mov_b32_e32 v11, v1
	v_mov_b32_e32 v12, v1
	v_mov_b32_e32 v13, v1
	v_mov_b32_e32 v14, v1
	v_mov_b32_e32 v15, v1
	v_add_u32_e32 v171, v20, v28
	v_add_u32_e32 v172, v21, v28
	v_add_u32_e32 v173, v22, v26
	v_add_u32_e32 v174, v23, v26
	v_add_u32_e32 v175, v24, v18
	v_add_u32_e32 v176, v25, v18
	v_add_u32_e32 v177, v27, v18
	v_add_u32_e32 v178, v29, v18
	v_add_u32_e32 v179, v30, v18
	v_add_u32_e32 v180, v31, v18
	v_add_u32_e32 v181, v32, v18
	v_add_u32_e32 v182, v33, v18
	v_mov_b64_e32 v[32:33], v[16:17]
	v_mov_b64_e32 v[48:49], v[16:17]
	v_mov_b64_e32 v[64:65], v[16:17]
	v_add_u32_e32 v160, 8, v159
	v_mov_b32_e32 v183, 0
	v_mov_b32_e32 v184, 0xf149f2ca
	v_mov_b64_e32 v[30:31], v[14:15]
	v_mov_b64_e32 v[28:29], v[12:13]
	v_mov_b64_e32 v[26:27], v[10:11]
	v_mov_b64_e32 v[24:25], v[8:9]
	v_mov_b64_e32 v[22:23], v[6:7]
	v_mov_b64_e32 v[20:21], v[4:5]
	v_mov_b64_e32 v[18:19], v[2:3]
	v_mov_b64_e32 v[46:47], v[14:15]
	v_mov_b64_e32 v[44:45], v[12:13]
	v_mov_b64_e32 v[42:43], v[10:11]
	v_mov_b64_e32 v[40:41], v[8:9]
	v_mov_b64_e32 v[38:39], v[6:7]
	v_mov_b64_e32 v[36:37], v[4:5]
	v_mov_b64_e32 v[34:35], v[2:3]
	v_mov_b64_e32 v[62:63], v[14:15]
	v_mov_b64_e32 v[60:61], v[12:13]
	v_mov_b64_e32 v[58:59], v[10:11]
	v_mov_b64_e32 v[56:57], v[8:9]
	v_mov_b64_e32 v[54:55], v[6:7]
	v_mov_b64_e32 v[52:53], v[4:5]
	v_mov_b64_e32 v[50:51], v[2:3]

; __device__ __forceinline__ float2 cmul(float2 a, float2 b) { return make_float2(a.x * b.x - a.y * b.y, a.x * b.y + a.y * b.x); }
; #define tid ltid()
; #define G lgrid()
; #define bx lbid()
; template <int LR, bool INV>
; __device__ __forceinline__ void fft_stages(float2 (&x)[1 << LR], const int r, const int s) {
;   constexpr int R = 1 << LR;
; #pragma unroll
;   for (int st = 0; st < LR; ++st) {
;     const int hl = INV ? (1 << st) : (R >> (st + 1));
;     const float fb = (float)r * (0.5f / (float)(hl * s));
;     const float2 wb = make_float2(__builtin_amdgcn_cosf(fb), INV ? __builtin_amdgcn_sinf(fb) : -__builtin_amdgcn_sinf(fb));
; #pragma unroll
;     for (int m = 0; m < R; ++m) {
;       if (m & hl) continue;
;       const int k = m & (hl - 1); const int j = k * (8 / hl);
;       const float2 wc = make_float2(c16(j), INV ? s16(j) : -s16(j));
;       const float2 tw = cmul(wb, wc);
; __global__ void __launch_bounds__(NTHR, 2) mega_fwd(Args a_unused) {
;     ...
;         for (int u = bx; u < 4096; u += G) {
;           const int gsel = u < 2048 ? 1 : 0, c = u & 2047;
;           const int L = gsel ? 4096 : 2048, N = 2 * L;
;           const float* hd = (const float*)(ws + (gsel ? WS_HDN_S : WS_HDN_P));
;           __syncthreads();
;           { const float* frow = (const float*)((const char*)AOUT + 192 * MiB) + (gsel ? (size_t)c * 8192 : (size_t)2048 * 8192 + (size_t)c * 4096);
;             for (int n = tid; n < N; n += NTHR) Hb[PIDX(n)] = make_float2(frow[n], 0.f); }
;           __syncthreads();
.LBB0_645:
	s_cmpk_gt_i32 s5, 0x7ff
	s_cselect_b64 s[10:11], -1, 0
	s_and_b32 s17, s5, 0x7ff
	s_cmpk_lt_i32 s5, 0x800
	s_cselect_b64 s[42:43], -1, 0
	s_and_b64 s[12:13], s[42:43], exec
	s_movk_i32 s12, 0x800
	s_cselect_b32 s16, 0x1000, s12
	s_lshl_b32 s18, s16, 1
	s_mov_b64 s[12:13], s[0:1]
	s_mov_b64 s[14:15], s[0:1]
	v_mov_b32_e32 v0, v208
	s_waitcnt lgkmcnt(0)
	s_barrier
	s_nop 0
	v_cmp_gt_i32_e32 vcc, s18, v0
	s_and_saveexec_b64 s[12:13], vcc
	s_cbranch_execz .LBB0_648
	s_load_dwordx2 s[14:15], s[14:15], 0xe8
	s_lshl_b32 s20, s17, 12
	s_lshl_b32 s19, s17, 13
	s_or_b32 s22, s20, 0x1000000
	s_and_b64 s[20:21], s[42:43], exec
	s_cselect_b32 s19, s19, s22
	s_lshl_b32 s19, s19, 2
	s_waitcnt lgkmcnt(0)
	s_add_u32 s14, s14, s19
	v_ashrrev_i32_e32 v1, 31, v0
	s_addc_u32 s15, s15, 0
	v_lshl_add_u64 v[2:3], v[0:1], 2, s[14:15]
	s_mov_b64 s[14:15], 0xc000000
	v_lshl_add_u64 v[2:3], v[2:3], 0, s[14:15]
	v_lshl_add_u32 v1, v0, 3, s52
	v_ashrrev_i32_e32 v4, 4, v0
	v_lshl_add_u32 v4, v4, 3, v1
	s_mov_b64 s[20:21], 0x1000
	v_mov_b32_e32 v151, 0
	v_mov_b32_e32 v153, 0
	v_mov_b32_e32 v155, 0
	v_mov_b32_e32 v157, 0
	v_mov_b32_e32 v159, 0
	v_mov_b32_e32 v161, 0
	v_mov_b32_e32 v163, 0
	v_mov_b32_e32 v165, 0
	v_mov_b32_e32 v167, 0
	v_mov_b32_e32 v169, 0
	v_mov_b32_e32 v171, 0
	v_mov_b32_e32 v173, 0
	v_mov_b32_e32 v175, 0
	v_mov_b32_e32 v177, 0
	v_mov_b32_e32 v179, 0
	v_mov_b32_e32 v181, 0
	global_load_dword v150, v[2:3], off
	global_load_dword v152, v[2:3], off offset:2048
	v_lshl_add_u64 v[2:3], v[2:3], 0, s[20:21]
	global_load_dword v154, v[2:3], off
	global_load_dword v156, v[2:3], off offset:2048
	v_lshl_add_u64 v[2:3], v[2:3], 0, s[20:21]
	global_load_dword v158, v[2:3], off
	global_load_dword v160, v[2:3], off offset:2048
	v_lshl_add_u64 v[2:3], v[2:3], 0, s[20:21]
	global_load_dword v162, v[2:3], off
	global_load_dword v164, v[2:3], off offset:2048
	v_lshl_add_u64 v[2:3], v[2:3], 0, s[20:21]
	s_cmp_lg_u32 s18, 0x2000
	s_cbranch_scc1 .Lfload_half
	global_load_dword v166, v[2:3], off
	global_load_dword v168, v[2:3], off offset:2048
	v_lshl_add_u64 v[2:3], v[2:3], 0, s[20:21]
	global_load_dword v170, v[2:3], off
	global_load_dword v172, v[2:3], off offset:2048
	v_lshl_add_u64 v[2:3], v[2:3], 0, s[20:21]
	global_load_dword v174, v[2:3], off
	global_load_dword v176, v[2:3], off offset:2048
	v_lshl_add_u64 v[2:3], v[2:3], 0, s[20:21]
	global_load_dword v178, v[2:3], off
	global_load_dword v180, v[2:3], off offset:2048
	s_waitcnt vmcnt(8)
	ds_write_b64 v4, v[150:151] offset:0
	ds_write_b64 v4, v[152:153] offset:4352
	ds_write_b64 v4, v[154:155] offset:8704
	ds_write_b64 v4, v[156:157] offset:13056
	ds_write_b64 v4, v[158:159] offset:17408
	ds_write_b64 v4, v[160:161] offset:21760
	ds_write_b64 v4, v[162:163] offset:26112
	ds_write_b64 v4, v[164:165] offset:30464
	s_waitcnt vmcnt(0)
	ds_write_b64 v4, v[166:167] offset:34816
	ds_write_b64 v4, v[168:169] offset:39168
	ds_write_b64 v4, v[170:171] offset:43520
	ds_write_b64 v4, v[172:173] offset:47872
	ds_write_b64 v4, v[174:175] offset:52224
	ds_write_b64 v4, v[176:177] offset:56576
	ds_write_b64 v4, v[178:179] offset:60928
	ds_write_b64 v4, v[180:181] offset:65280
	s_branch .LBB0_648
.Lfload_half:
	s_waitcnt vmcnt(0)
	ds_write_b64 v4, v[150:151] offset:0
	ds_write_b64 v4, v[152:153] offset:4352
	ds_write_b64 v4, v[154:155] offset:8704
	ds_write_b64 v4, v[156:157] offset:13056
	ds_write_b64 v4, v[158:159] offset:17408
	ds_write_b64 v4, v[160:161] offset:21760
	ds_write_b64 v4, v[162:163] offset:26112
	ds_write_b64 v4, v[164:165] offset:30464
.LBB0_648:
	s_or_b64 exec, exec, s[12:13]
	v_mov_b32_e32 v60, v208
	s_movk_i32 s12, 0x200
	s_waitcnt lgkmcnt(0)
	s_barrier
	s_and_b64 vcc, exec, s[10:11]
	v_cmp_gt_i32_e64 s[40:41], s12, v60
	s_mov_b64 s[12:13], -1
	s_cbranch_vccz .LBB0_653
	s_and_saveexec_b64 s[12:13], s[40:41]
	s_cbranch_execz .LBB0_652
	v_and_b32_e32 v28, 0x1ff, v60
	v_cvt_f32_u32_e32 v14, v28
	s_mov_b32 s90, s75
	s_mov_b32 s14, s71
	s_mov_b32 s15, s70
	v_mul_f32_e32 v0, 0x39800000, v14
	v_sin_f32_e32 v6, v0
	v_cos_f32_e32 v7, v0
	v_mul_f32_e32 v11, 0x3a000000, v14
	v_sin_f32_e32 v10, v11
	v_cos_f32_e32 v11, v11
	v_mul_f32_e32 v15, 0x3a800000, v14
	v_sin_f32_e32 v14, v15
	v_cos_f32_e32 v15, v15
	v_xor_b32_e32 v2, 0x80000000, v6
	v_pk_mov_b32 v[0:1], v[6:7], v[6:7] op_sel:[1,0]
	v_mul_f32_e32 v8, s70, v6
	v_mul_f32_e32 v9, s70, v7
	v_mov_b32_e32 v1, v2
	s_mov_b32 s74, s91
	v_fma_f32 v0, -v6, 0, v0
	v_fma_f32 v1, -v7, 0, v1
	v_fma_f32 v2, v7, s14, v8
	v_fma_f32 v3, v6, s15, v9
	v_fma_f32 v4, v7, s90, -v6
	v_fma_f32 v5, v6, s91, -v7
	v_pk_fma_f32 v[6:7], v[6:7], s[70:71], v[8:9] op_sel:[1,0,0] op_sel_hi:[0,1,1]
	v_xor_b32_e32 v9, 0x80000000, v10
	v_mul_f32_e32 v12, s74, v10
	v_mul_f32_e32 v13, s75, v11
	v_mov_b32_e32 v8, v11
	v_fma_f32 v8, -v10, 0, v8
	v_fma_f32 v9, -v11, 0, v9
	v_sub_f32_e32 v10, v13, v10
	v_sub_f32_e32 v11, v12, v11
	v_xor_b32_e32 v13, 0x80000000, v14
	v_mov_b32_e32 v12, v15
	v_fma_f32 v12, -v14, 0, v12
	v_fma_f32 v13, -v15, 0, v13
	v_pk_mov_b32 v[16:17], v[8:9], v[8:9] op_sel:[1,0]
	v_pk_mov_b32 v[14:15], v[12:13], v[12:13] op_sel:[1,0]
	v_pk_mov_b32 v[18:19], v[10:11], v[10:11] op_sel:[1,0]
	v_pk_mov_b32 v[20:21], v[0:1], v[0:1] op_sel:[1,0]
	v_pk_mov_b32 v[22:23], v[2:3], v[2:3] op_sel:[1,0]
	v_pk_mov_b32 v[24:25], v[4:5], v[4:5] op_sel:[1,0]
	v_pk_mov_b32 v[26:27], v[6:7], v[6:7] op_sel:[1,0]
	v_add_u32_e32 v29, 0xfffffe00, v60
	v_lshlrev_b32_e32 v30, 3, v60
	s_mov_b64 s[14:15], 0
;     static __device__ __forceinline__ float sl(float g, float up) { return g * __builtin_amdgcn_rcpf(1.0f + __builtin_amdgcn_exp2f(-1.4426950408889634f * g)) * up; }
; __device__ __forceinline__ float2 cmul(float2 a, float2 b) { return make_float2(a.x * b.x - a.y * b.y, a.x * b.y + a.y * b.x); }
; #define tid ltid()
; template <int LR, bool INV>
; __device__ __forceinline__ void fft_stages(float2 (&x)[1 << LR], const int r, const int s) {
;   constexpr int R = 1 << LR;
; #pragma unroll
;   for (int st = 0; st < LR; ++st) {
;     const int hl = INV ? (1 << st) : (R >> (st + 1));
;     const float fb = (float)r * (0.5f / (float)(hl * s));
;     const float2 wb = make_float2(__builtin_amdgcn_cosf(fb), INV ? __builtin_amdgcn_sinf(fb) : -__builtin_amdgcn_sinf(fb));
; #pragma unroll
;     for (int m = 0; m < R; ++m) {
;       if (m & hl) continue;
;       const int k = m & (hl - 1); const int j = k * (8 / hl);
;       const float2 wc = make_float2(c16(j), INV ? s16(j) : -s16(j));
;       const float2 tw = cmul(wb, wc);
;       if (!INV) { const float2 p = x[m], q = x[m + hl]; x[m] = make_float2(p.x + q.x, p.y + q.y); x[m + hl] = cmul(make_float2(p.x - q.x, p.y - q.y), tw); }
;       else { const float2 p = x[m], q = cmul(x[m + hl], tw); x[m] = make_float2(p.x + q.x, p.y + q.y); x[m + hl] = make_float2(p.x - q.x, p.y - q.y); }
;     }
;   }
; template <int LR, bool INV>
; __device__ __forceinline__ void fft_pass(float2* X, const int N, const int sl, const int tid) {
;   constexpr int R = 1 << LR;
;   const int s = 1 << sl;
;   for (int g = tid; g < (N >> LR); g += NTHR) {
;     const int r = g & (s - 1);
;     const int i0 = ((g >> sl) << (sl + LR)) + r;
;     float2 x[R];
; #pragma unroll
;     for (int m = 0; m < R; ++m) x[m] = X[PIDX(i0 + (m << sl))];
;     fft_stages<LR, INV>(x, r, s);
; #pragma unroll
;     for (int m = 0; m < R; ++m) X[PIDX(i0 + (m << sl))] = x[m];
;   }
;   __syncthreads();
.LBB0_651:
	v_and_or_b32 v31, v30, s67, v28
	v_ashrrev_i32_e32 v32, 4, v31
	v_lshlrev_b32_e32 v32, 3, v32
	v_lshlrev_b32_e32 v33, 3, v31
	v_add3_u32 v50, s52, v32, v33
	v_or_b32_e32 v32, 0x200, v31
	v_ashrrev_i32_e32 v32, 4, v32
	v_lshlrev_b32_e32 v32, 3, v32
	v_add3_u32 v51, s52, v32, v33
	v_or_b32_e32 v32, 0x400, v31
	v_ashrrev_i32_e32 v32, 4, v32
	v_lshlrev_b32_e32 v32, 3, v32
	v_add3_u32 v52, s52, v32, v33
	v_or_b32_e32 v32, 0x600, v31
	v_ashrrev_i32_e32 v32, 4, v32
	v_lshlrev_b32_e32 v32, 3, v32
	v_add3_u32 v53, s52, v32, v33
	v_or_b32_e32 v32, 0x800, v31
	v_ashrrev_i32_e32 v32, 4, v32
	v_lshlrev_b32_e32 v32, 3, v32
	v_add3_u32 v54, s52, v32, v33
	v_or_b32_e32 v32, 0xa00, v31
	v_ashrrev_i32_e32 v32, 4, v32
	v_lshlrev_b32_e32 v32, 3, v32
	v_add3_u32 v55, s52, v32, v33
	v_or_b32_e32 v32, 0xc00, v31
	v_or_b32_e32 v31, 0xe00, v31
	v_ashrrev_i32_e32 v32, 4, v32
	v_ashrrev_i32_e32 v31, 4, v31
	v_lshlrev_b32_e32 v32, 3, v32
	v_lshlrev_b32_e32 v31, 3, v31
	v_add3_u32 v56, s52, v32, v33
	v_add3_u32 v31, s52, v31, v33
	ds_read_b64 v[32:33], v50
	ds_read_b64 v[34:35], v51 offset:4096
	ds_read_b64 v[36:37], v52 offset:8192
	ds_read_b64 v[38:39], v53 offset:12288
	ds_read_b64 v[40:41], v54 offset:16384
	ds_read_b64 v[42:43], v55 offset:20480
	ds_read_b64 v[44:45], v56 offset:24576
	ds_read_b64 v[46:47], v31 offset:28672
	v_add_u32_e32 v29, 0x200, v29
	s_waitcnt lgkmcnt(3)
	v_add_f32_e32 v48, v32, v40
	v_add_f32_e32 v49, v33, v41
	v_sub_f32_e32 v32, v32, v40
	v_sub_f32_e32 v33, v33, v41
	s_waitcnt lgkmcnt(2)
	v_add_f32_e32 v40, v34, v42
	v_add_f32_e32 v41, v35, v43
	v_sub_f32_e32 v34, v34, v42
	v_sub_f32_e32 v35, v35, v43
	s_waitcnt lgkmcnt(1)
	v_add_f32_e32 v42, v36, v44
	v_add_f32_e32 v43, v37, v45
	v_sub_f32_e32 v36, v36, v44
	v_sub_f32_e32 v37, v37, v45
	s_waitcnt lgkmcnt(0)
	v_add_f32_e32 v44, v38, v46
	v_add_f32_e32 v45, v39, v47
	v_sub_f32_e32 v38, v38, v46
	v_sub_f32_e32 v39, v39, v47
	v_add_f32_e32 v46, v48, v42
	v_add_f32_e32 v47, v49, v43
	v_sub_f32_e32 v42, v48, v42
	v_sub_f32_e32 v43, v49, v43
	v_add_f32_e32 v48, v40, v44
	v_add_f32_e32 v49, v41, v45
	v_sub_f32_e32 v40, v40, v44
	v_sub_f32_e32 v41, v41, v45
	v_add_f32_e32 v44, v46, v48
	v_add_f32_e32 v45, v47, v49
	v_sub_f32_e32 v46, v46, v48
	v_sub_f32_e32 v47, v47, v49
	ds_write_b64 v50, v[44:45]
	v_mul_f32_e32 v44, v14, v47
	v_mul_f32_e32 v45, v15, v47
	v_cmp_lt_i32_e32 vcc, -1, v29
	v_fma_f32 v48, v12, v46, -v44
	v_fma_f32 v45, v13, v46, v45
	v_add_u32_e32 v30, 0x1000, v30
	v_mov_b32_e32 v49, v45
	v_mul_f32_e32 v44, v16, v43
	v_mul_f32_e32 v45, v17, v43
	ds_write_b64 v51, v[48:49] offset:4096
	v_fma_f32 v46, v8, v42, -v44
	v_fma_f32 v43, v9, v42, v45
	s_or_b64 s[14:15], vcc, s[14:15]
	v_mov_b32_e32 v47, v43
	v_mul_f32_e32 v42, v18, v41
	v_mul_f32_e32 v43, v19, v41
	v_fma_f32 v44, v10, v40, -v42
	v_fma_f32 v41, v11, v40, v43
	v_mov_b32_e32 v45, v41
	v_add_f32_e32 v40, v46, v44
	v_add_f32_e32 v41, v47, v45
	v_sub_f32_e32 v42, v46, v44
	v_sub_f32_e32 v43, v47, v45
	ds_write_b64 v52, v[40:41] offset:8192
	v_mul_f32_e32 v40, v14, v43
	v_mul_f32_e32 v41, v15, v43
	v_fma_f32 v44, v12, v42, -v40
	v_fma_f32 v41, v13, v42, v41
	v_mov_b32_e32 v45, v41
	v_mul_f32_e32 v40, v20, v33
	v_mul_f32_e32 v41, v21, v33
	ds_write_b64 v53, v[44:45] offset:12288
	v_fma_f32 v42, v0, v32, -v40
	v_fma_f32 v33, v1, v32, v41
	v_mov_b32_e32 v43, v33
	v_mul_f32_e32 v32, v22, v35
	v_mul_f32_e32 v33, v23, v35
	v_fma_f32 v40, v2, v34, -v32
	v_fma_f32 v33, v3, v34, v33
	v_mov_b32_e32 v41, v33
	v_mul_f32_e32 v32, v24, v37
	v_mul_f32_e32 v33, v25, v37
	v_fma_f32 v34, v4, v36, -v32
	v_fma_f32 v33, v5, v36, v33
	v_mov_b32_e32 v35, v33
	v_mul_f32_e32 v32, v26, v39
	v_mul_f32_e32 v33, v27, v39
	v_fma_f32 v36, v6, v38, -v32
	v_fma_f32 v33, v7, v38, v33
	v_mov_b32_e32 v37, v33
	v_add_f32_e32 v32, v42, v34
	v_add_f32_e32 v33, v43, v35
	v_add_f32_e32 v38, v40, v36
	v_add_f32_e32 v39, v41, v37
	v_sub_f32_e32 v36, v40, v36
	v_sub_f32_e32 v37, v41, v37
	v_add_f32_e32 v40, v32, v38
	v_add_f32_e32 v41, v33, v39
	v_sub_f32_e32 v32, v32, v38
	v_sub_f32_e32 v33, v33, v39
	v_sub_f32_e32 v34, v42, v34
	v_sub_f32_e32 v35, v43, v35
	v_mul_f32_e32 v38, v14, v33
	v_mul_f32_e32 v39, v15, v33
	ds_write_b64 v54, v[40:41] offset:16384
	v_fma_f32 v40, v12, v32, -v38
	v_fma_f32 v33, v13, v32, v39
	v_mov_b32_e32 v41, v33
	v_mul_f32_e32 v32, v16, v35
	v_mul_f32_e32 v33, v17, v35
	ds_write_b64 v55, v[40:41] offset:20480
	v_fma_f32 v38, v8, v34, -v32
	v_fma_f32 v33, v9, v34, v33
	v_mov_b32_e32 v39, v33
	v_mul_f32_e32 v32, v18, v37
	v_mul_f32_e32 v33, v19, v37
	v_fma_f32 v34, v10, v36, -v32
	v_fma_f32 v33, v11, v36, v33
	v_mov_b32_e32 v35, v33
	v_add_f32_e32 v32, v38, v34
	v_add_f32_e32 v33, v39, v35
	v_sub_f32_e32 v34, v38, v34
	v_sub_f32_e32 v35, v39, v35
	ds_write_b64 v56, v[32:33] offset:24576
	v_mul_f32_e32 v32, v14, v35
	v_mul_f32_e32 v33, v15, v35
	v_fma_f32 v36, v12, v34, -v32
	v_fma_f32 v32, v12, v34, v32
	v_fma_f32 v33, v13, v34, v33
	v_mov_b32_e32 v37, v33
	ds_write_b64 v31, v[36:37] offset:28672
	s_andn2_b64 exec, exec, s[14:15]
	s_cbranch_execnz .LBB0_651

;     static __device__ __forceinline__ float sl(float g, float up) { return g * __builtin_amdgcn_rcpf(1.0f + __builtin_amdgcn_exp2f(-1.4426950408889634f * g)) * up; }
; __device__ __forceinline__ float2 cmul(float2 a, float2 b) { return make_float2(a.x * b.x - a.y * b.y, a.x * b.y + a.y * b.x); }
; #define tid ltid()
; template <int LR, bool INV>
; __device__ __forceinline__ void fft_stages(float2 (&x)[1 << LR], const int r, const int s) {
;   constexpr int R = 1 << LR;
; #pragma unroll
;   for (int st = 0; st < LR; ++st) {
;     const int hl = INV ? (1 << st) : (R >> (st + 1));
;     const float fb = (float)r * (0.5f / (float)(hl * s));
;     const float2 wb = make_float2(__builtin_amdgcn_cosf(fb), INV ? __builtin_amdgcn_sinf(fb) : -__builtin_amdgcn_sinf(fb));
; #pragma unroll
;     for (int m = 0; m < R; ++m) {
;       if (m & hl) continue;
;       const int k = m & (hl - 1); const int j = k * (8 / hl);
;       const float2 wc = make_float2(c16(j), INV ? s16(j) : -s16(j));
;       const float2 tw = cmul(wb, wc);
;       if (!INV) { const float2 p = x[m], q = x[m + hl]; x[m] = make_float2(p.x + q.x, p.y + q.y); x[m + hl] = cmul(make_float2(p.x - q.x, p.y - q.y), tw); }
;       else { const float2 p = x[m], q = cmul(x[m + hl], tw); x[m] = make_float2(p.x + q.x, p.y + q.y); x[m + hl] = make_float2(p.x - q.x, p.y - q.y); }
;     }
;   }
; }
; template <int LR, bool INV>
; __device__ __forceinline__ void fft_pass(float2* X, const int N, const int sl, const int tid) {
;   constexpr int R = 1 << LR;
;   const int s = 1 << sl;
;   for (int g = tid; g < (N >> LR); g += NTHR) {
;     const int r = g & (s - 1);
;     const int i0 = ((g >> sl) << (sl + LR)) + r;
;     float2 x[R];
; #pragma unroll
;     for (int m = 0; m < R; ++m) x[m] = X[PIDX(i0 + (m << sl))];
.LBB0_653:
	s_movk_i32 s19, 0x200
	s_and_b64 vcc, exec, s[12:13]
	s_cbranch_vccz .LBB0_658
	s_and_saveexec_b64 s[12:13], s[40:41]
	s_cbranch_execz .LBB0_657
	v_and_b32_e32 v61, 0x1ff, v60
	v_cvt_f32_u32_e32 v30, v61
	s_mov_b32 s14, s73
	s_mov_b32 s90, s75
	s_mov_b32 s95, s92
	v_mul_f32_e32 v0, 0x39000000, v30
	v_sin_f32_e32 v14, v0
	v_cos_f32_e32 v15, v0
	v_mul_f32_e32 v18, 0x39800000, v30
	v_sin_f32_e32 v22, v18
	v_cos_f32_e32 v23, v18
	v_mul_f32_e32 v27, 0x3a000000, v30
	v_xor_b32_e32 v2, 0x80000000, v14
	v_pk_mov_b32 v[0:1], v[14:15], v[14:15] op_sel:[1,0]
	v_mul_f32_e32 v10, s14, v14
	v_mul_f32_e32 v11, s14, v15
	s_mov_b32 s14, s71
	v_sin_f32_e32 v26, v27
	v_cos_f32_e32 v27, v27
	v_mul_f32_e32 v31, 0x3a800000, v30
	v_mul_f32_e32 v16, s92, v14
	v_mul_f32_e32 v17, s92, v15
	v_mov_b32_e32 v1, v2
	s_mov_b32 s93, s94
	v_mul_f32_e32 v12, s14, v14
	v_mul_f32_e32 v13, s14, v15
	s_mov_b32 s20, s71
	s_mov_b32 s21, s70
	s_mov_b32 s22, s73
	s_mov_b32 s23, s72
	v_sin_f32_e32 v30, v31
	v_cos_f32_e32 v31, v31
	v_fma_f32 v0, -v14, 0, v0
	v_fma_f32 v1, -v15, 0, v1
	v_fma_f32 v2, v15, s72, v16
	v_fma_f32 v3, v14, s73, v17
	v_fma_f32 v4, v15, s20, -v12
	v_fma_f32 v5, v14, s21, -v13
	v_fma_f32 v6, v15, s94, v10
	v_fma_f32 v7, v14, s95, v11
	v_fma_f32 v8, v15, s90, -v14
	v_fma_f32 v9, v14, s91, -v15
	v_fma_f32 v10, v15, s92, v10
	v_fma_f32 v11, v14, s93, v11
	v_fma_f32 v12, v15, s70, -v12
	v_fma_f32 v13, v14, s71, -v13
	v_pk_fma_f32 v[14:15], v[14:15], s[22:23], v[16:17] op_sel:[1,0,0] op_sel_hi:[0,1,1]
	v_xor_b32_e32 v18, 0x80000000, v22
	v_pk_mov_b32 v[16:17], v[22:23], v[22:23] op_sel:[1,0]
	v_mul_f32_e32 v24, s14, v22
	v_mul_f32_e32 v25, s14, v23
	v_mov_b32_e32 v17, v18
	s_mov_b32 s74, s91
	v_fma_f32 v16, -v22, 0, v16
	v_fma_f32 v17, -v23, 0, v17
	v_fma_f32 v18, v23, s20, -v24
	v_fma_f32 v19, v22, s21, -v25
	v_fma_f32 v20, v23, s90, -v22
	v_fma_f32 v21, v22, s91, -v23
	v_pk_fma_f32 v[22:23], v[22:23], s[70:71], v[24:25] op_sel:[1,0,0] op_sel_hi:[0,1,1] neg_lo:[0,0,1] neg_hi:[0,0,1]
	v_xor_b32_e32 v25, 0x80000000, v26
	v_mul_f32_e32 v28, s74, v26
	v_mul_f32_e32 v29, s75, v27
	v_mov_b32_e32 v24, v27
	v_fma_f32 v24, -v26, 0, v24
	v_fma_f32 v25, -v27, 0, v25
	v_sub_f32_e32 v26, v29, v26
	v_sub_f32_e32 v27, v28, v27
	v_xor_b32_e32 v29, 0x80000000, v30
	v_mov_b32_e32 v28, v31
	v_fma_f32 v28, -v30, 0, v28
	v_fma_f32 v29, -v31, 0, v29
	v_pk_mov_b32 v[32:33], v[24:25], v[24:25] op_sel:[1,0]
	v_pk_mov_b32 v[30:31], v[28:29], v[28:29] op_sel:[1,0]
	v_pk_mov_b32 v[34:35], v[26:27], v[26:27] op_sel:[1,0]
	v_pk_mov_b32 v[36:37], v[16:17], v[16:17] op_sel:[1,0]
	v_pk_mov_b32 v[38:39], v[18:19], v[18:19] op_sel:[1,0]
	v_pk_mov_b32 v[40:41], v[20:21], v[20:21] op_sel:[1,0]
	v_pk_mov_b32 v[42:43], v[22:23], v[22:23] op_sel:[1,0]
	v_pk_mov_b32 v[44:45], v[0:1], v[0:1] op_sel:[1,0]
	v_pk_mov_b32 v[46:47], v[2:3], v[2:3] op_sel:[1,0]
	v_pk_mov_b32 v[48:49], v[4:5], v[4:5] op_sel:[1,0]
	v_pk_mov_b32 v[50:51], v[6:7], v[6:7] op_sel:[1,0]
	v_pk_mov_b32 v[52:53], v[8:9], v[8:9] op_sel:[1,0]
	v_pk_mov_b32 v[54:55], v[10:11], v[10:11] op_sel:[1,0]
	v_pk_mov_b32 v[56:57], v[12:13], v[12:13] op_sel:[1,0]
	v_pk_mov_b32 v[58:59], v[14:15], v[14:15] op_sel:[1,0]
	v_add_u32_e32 v62, 0xfffffe00, v60
	v_lshlrev_b32_e32 v63, 4, v60
	s_mov_b64 s[14:15], 0
.LBB0_656:
	v_and_or_b32 v64, v63, s2, v61
	v_ashrrev_i32_e32 v65, 4, v64
	v_lshlrev_b32_e32 v66, 3, v64
	v_lshlrev_b32_e32 v65, 3, v65
	v_add3_u32 v98, s52, v66, v65
	v_or_b32_e32 v65, 0x200, v64
	v_ashrrev_i32_e32 v66, 4, v65
	v_lshlrev_b32_e32 v66, 3, v66
	v_lshlrev_b32_e32 v65, 3, v65
	v_add3_u32 v99, s52, v66, v65
	v_or_b32_e32 v65, 0x400, v64
	v_ashrrev_i32_e32 v66, 4, v65
	v_lshlrev_b32_e32 v66, 3, v66
	v_lshlrev_b32_e32 v65, 3, v65
	v_add3_u32 v100, s52, v66, v65
	v_or_b32_e32 v65, 0x600, v64
	v_ashrrev_i32_e32 v66, 4, v65
	v_lshlrev_b32_e32 v66, 3, v66
	v_lshlrev_b32_e32 v65, 3, v65
	v_add3_u32 v101, s52, v66, v65
	v_or_b32_e32 v65, 0x800, v64
	v_ashrrev_i32_e32 v66, 4, v65
	v_lshlrev_b32_e32 v66, 3, v66
	v_lshlrev_b32_e32 v65, 3, v65
	v_add3_u32 v102, s52, v66, v65
	v_or_b32_e32 v65, 0xa00, v64
	v_ashrrev_i32_e32 v66, 4, v65
	v_lshlrev_b32_e32 v66, 3, v66
	v_lshlrev_b32_e32 v65, 3, v65
	v_add3_u32 v103, s52, v66, v65
	v_or_b32_e32 v65, 0xc00, v64
	v_ashrrev_i32_e32 v66, 4, v65
	v_lshlrev_b32_e32 v66, 3, v66
	v_lshlrev_b32_e32 v65, 3, v65
	v_add3_u32 v104, s52, v66, v65
	v_or_b32_e32 v65, 0xe00, v64
	v_ashrrev_i32_e32 v66, 4, v65
	v_lshlrev_b32_e32 v66, 3, v66
	v_lshlrev_b32_e32 v65, 3, v65
	v_add3_u32 v105, s52, v66, v65
	v_or_b32_e32 v65, 0x1000, v64
	v_ashrrev_i32_e32 v66, 4, v65
	v_lshlrev_b32_e32 v66, 3, v66
	v_lshlrev_b32_e32 v65, 3, v65
	v_add3_u32 v106, s52, v66, v65
	v_or_b32_e32 v65, 0x1200, v64
	v_ashrrev_i32_e32 v66, 4, v65
	v_lshlrev_b32_e32 v66, 3, v66
	v_lshlrev_b32_e32 v65, 3, v65
	v_add3_u32 v107, s52, v66, v65
	v_or_b32_e32 v65, 0x1400, v64
	v_ashrrev_i32_e32 v66, 4, v65
	v_lshlrev_b32_e32 v66, 3, v66
	v_lshlrev_b32_e32 v65, 3, v65
	v_add3_u32 v108, s52, v66, v65
	v_or_b32_e32 v65, 0x1600, v64
	v_ashrrev_i32_e32 v66, 4, v65
	v_lshlrev_b32_e32 v66, 3, v66
	v_lshlrev_b32_e32 v65, 3, v65
	v_add3_u32 v109, s52, v66, v65
	v_or_b32_e32 v65, 0x1800, v64
	v_ashrrev_i32_e32 v66, 4, v65
	v_lshlrev_b32_e32 v66, 3, v66
	v_lshlrev_b32_e32 v65, 3, v65
	v_add3_u32 v110, s52, v66, v65
	v_or_b32_e32 v65, 0x1a00, v64
	v_ashrrev_i32_e32 v66, 4, v65
	v_lshlrev_b32_e32 v66, 3, v66
	v_lshlrev_b32_e32 v65, 3, v65
	v_add3_u32 v111, s52, v66, v65
	v_or_b32_e32 v65, 0x1c00, v64
	v_ashrrev_i32_e32 v66, 4, v65
	v_lshlrev_b32_e32 v66, 3, v66
	v_lshlrev_b32_e32 v65, 3, v65
	v_or_b32_e32 v64, 0x1e00, v64
	v_add3_u32 v112, s52, v66, v65
	v_ashrrev_i32_e32 v65, 4, v64
	v_lshlrev_b32_e32 v65, 3, v65
	v_lshlrev_b32_e32 v64, 3, v64
	v_add3_u32 v113, s52, v65, v64
	ds_read_b64 v[64:65], v98
	ds_read_b64 v[66:67], v99
	ds_read_b64 v[68:69], v100
	ds_read_b64 v[70:71], v101
	ds_read_b64 v[72:73], v102
	ds_read_b64 v[74:75], v103
	ds_read_b64 v[76:77], v104
	ds_read_b64 v[78:79], v105
	ds_read_b64 v[80:81], v106
	ds_read_b64 v[82:83], v107
	ds_read_b64 v[84:85], v108
	ds_read_b64 v[86:87], v109
	ds_read_b64 v[88:89], v110
	ds_read_b64 v[90:91], v111
	ds_read_b64 v[92:93], v112
	ds_read_b64 v[94:95], v113
	s_waitcnt lgkmcnt(7)
; __device__ __forceinline__ float2 cmul(float2 a, float2 b) { return make_float2(a.x * b.x - a.y * b.y, a.x * b.y + a.y * b.x); }
; template <int LR, bool INV>
; __device__ __forceinline__ void fft_stages(float2 (&x)[1 << LR], const int r, const int s) {
;   constexpr int R = 1 << LR;
; #pragma unroll
;   for (int st = 0; st < LR; ++st) {
;     const int hl = INV ? (1 << st) : (R >> (st + 1));
;     const float fb = (float)r * (0.5f / (float)(hl * s));
;     const float2 wb = make_float2(__builtin_amdgcn_cosf(fb), INV ? __builtin_amdgcn_sinf(fb) : -__builtin_amdgcn_sinf(fb));
; #pragma unroll
;     for (int m = 0; m < R; ++m) {
;       if (m & hl) continue;
;       const int k = m & (hl - 1); const int j = k * (8 / hl);
;       const float2 wc = make_float2(c16(j), INV ? s16(j) : -s16(j));
;       const float2 tw = cmul(wb, wc);
;       if (!INV) { const float2 p = x[m], q = x[m + hl]; x[m] = make_float2(p.x + q.x, p.y + q.y); x[m + hl] = cmul(make_float2(p.x - q.x, p.y - q.y), tw); }
;       else { const float2 p = x[m], q = cmul(x[m + hl], tw); x[m] = make_float2(p.x + q.x, p.y + q.y); x[m + hl] = make_float2(p.x - q.x, p.y - q.y); }
;     }
;   }
	v_add_f32_e32 v96, v64, v80
	v_add_f32_e32 v97, v65, v81
	v_sub_f32_e32 v64, v64, v80
	v_sub_f32_e32 v65, v65, v81
	s_waitcnt lgkmcnt(6)
	v_add_f32_e32 v80, v66, v82
	v_add_f32_e32 v81, v67, v83
	v_sub_f32_e32 v66, v66, v82
	v_sub_f32_e32 v67, v67, v83
	s_waitcnt lgkmcnt(5)
	v_add_f32_e32 v82, v68, v84
	v_add_f32_e32 v83, v69, v85
	v_sub_f32_e32 v68, v68, v84
	v_sub_f32_e32 v69, v69, v85
	s_waitcnt lgkmcnt(4)
	v_add_f32_e32 v84, v70, v86
	v_add_f32_e32 v85, v71, v87
	v_sub_f32_e32 v70, v70, v86
	v_sub_f32_e32 v71, v71, v87
	s_waitcnt lgkmcnt(3)
	v_add_f32_e32 v86, v72, v88
	v_add_f32_e32 v87, v73, v89
	v_sub_f32_e32 v72, v72, v88
	v_sub_f32_e32 v73, v73, v89
	s_waitcnt lgkmcnt(2)
	v_add_f32_e32 v88, v74, v90
	v_add_f32_e32 v89, v75, v91
	v_sub_f32_e32 v74, v74, v90
	v_sub_f32_e32 v75, v75, v91
	s_waitcnt lgkmcnt(1)
	v_add_f32_e32 v90, v76, v92
	v_add_f32_e32 v91, v77, v93
	v_sub_f32_e32 v76, v76, v92
	v_sub_f32_e32 v77, v77, v93
	s_waitcnt lgkmcnt(0)
	v_add_f32_e32 v92, v78, v94
	v_add_f32_e32 v93, v79, v95
	v_sub_f32_e32 v78, v78, v94
	v_sub_f32_e32 v79, v79, v95
	v_add_f32_e32 v94, v96, v86
	v_add_f32_e32 v95, v97, v87
	v_sub_f32_e32 v86, v96, v86
	v_sub_f32_e32 v87, v97, v87
	v_add_f32_e32 v96, v80, v88
	v_add_f32_e32 v97, v81, v89
	v_sub_f32_e32 v80, v80, v88
	v_sub_f32_e32 v81, v81, v89
	v_add_f32_e32 v88, v82, v90
	v_add_f32_e32 v89, v83, v91
	v_sub_f32_e32 v82, v82, v90
	v_sub_f32_e32 v83, v83, v91
	v_add_f32_e32 v90, v84, v92
	v_add_f32_e32 v91, v85, v93
	v_sub_f32_e32 v84, v84, v92
	v_sub_f32_e32 v85, v85, v93
	v_add_f32_e32 v92, v94, v88
	v_add_f32_e32 v93, v95, v89
	v_sub_f32_e32 v88, v94, v88
	v_sub_f32_e32 v89, v95, v89
	v_add_f32_e32 v94, v96, v90
	v_add_f32_e32 v95, v97, v91
	v_sub_f32_e32 v90, v96, v90
	v_sub_f32_e32 v91, v97, v91
	v_add_f32_e32 v96, v92, v94
	v_add_f32_e32 v97, v93, v95
	v_sub_f32_e32 v92, v92, v94
	v_sub_f32_e32 v93, v93, v95
	ds_write_b64 v98, v[96:97]
	v_mul_f32_e32 v94, v30, v93
	v_mul_f32_e32 v95, v31, v93
	v_add_u32_e32 v62, 0x200, v62
	v_fma_f32 v96, v28, v92, -v94
	v_fma_f32 v93, v29, v92, v95
	v_cmp_lt_i32_e32 vcc, -1, v62
	v_mov_b32_e32 v97, v93
	v_mul_f32_e32 v92, v32, v89
	v_mul_f32_e32 v93, v33, v89
	ds_write_b64 v99, v[96:97]
	v_fma_f32 v94, v24, v88, -v92
	v_fma_f32 v89, v25, v88, v93
	v_add_u32_e32 v63, 0x2000, v63
	v_mov_b32_e32 v95, v89
	v_mul_f32_e32 v88, v34, v91
	v_mul_f32_e32 v89, v35, v91
	s_or_b64 s[14:15], vcc, s[14:15]
	v_fma_f32 v92, v26, v90, -v88
	v_fma_f32 v89, v27, v90, v89
	v_mov_b32_e32 v93, v89
	v_add_f32_e32 v88, v94, v92
	v_add_f32_e32 v89, v95, v93
	v_sub_f32_e32 v90, v94, v92
	v_sub_f32_e32 v91, v95, v93
	ds_write_b64 v100, v[88:89]
	v_mul_f32_e32 v88, v30, v91
	v_mul_f32_e32 v89, v31, v91
	v_fma_f32 v92, v28, v90, -v88
	v_fma_f32 v89, v29, v90, v89
	v_mov_b32_e32 v93, v89
	v_mul_f32_e32 v88, v36, v87
	v_mul_f32_e32 v89, v37, v87
	ds_write_b64 v101, v[92:93]
	v_fma_f32 v90, v16, v86, -v88
	v_fma_f32 v87, v17, v86, v89
	v_mov_b32_e32 v91, v87
	v_mul_f32_e32 v86, v38, v81
	v_mul_f32_e32 v87, v39, v81
	v_fma_f32 v88, v18, v80, -v86
	v_fma_f32 v81, v19, v80, v87
	v_mov_b32_e32 v89, v81
	v_mul_f32_e32 v80, v40, v83
	v_mul_f32_e32 v81, v41, v83
	v_fma_f32 v86, v20, v82, -v80
	v_fma_f32 v81, v21, v82, v81
	v_mov_b32_e32 v87, v81
	v_mul_f32_e32 v80, v42, v85
	v_mul_f32_e32 v81, v43, v85
	v_fma_f32 v82, v22, v84, -v80
	v_fma_f32 v81, v23, v84, v81
	v_sub_f32_e32 v84, v90, v86
	v_sub_f32_e32 v85, v91, v87
	v_mov_b32_e32 v83, v81
	v_add_f32_e32 v80, v90, v86
	v_add_f32_e32 v81, v91, v87
	v_add_f32_e32 v86, v88, v82
	v_add_f32_e32 v87, v89, v83
	v_sub_f32_e32 v82, v88, v82
	v_sub_f32_e32 v83, v89, v83
	v_add_f32_e32 v88, v80, v86
	v_add_f32_e32 v89, v81, v87
	v_sub_f32_e32 v80, v80, v86
	v_sub_f32_e32 v81, v81, v87
	ds_write_b64 v102, v[88:89]
	v_mul_f32_e32 v86, v30, v81
	v_mul_f32_e32 v87, v31, v81
	v_fma_f32 v88, v28, v80, -v86
	v_fma_f32 v81, v29, v80, v87
	v_mov_b32_e32 v89, v81
	v_mul_f32_e32 v80, v32, v85
	v_mul_f32_e32 v81, v33, v85
	ds_write_b64 v103, v[88:89]
	v_fma_f32 v86, v24, v84, -v80
	v_fma_f32 v81, v25, v84, v81
	v_mov_b32_e32 v87, v81
	v_mul_f32_e32 v80, v34, v83
	v_mul_f32_e32 v81, v35, v83
	v_fma_f32 v84, v26, v82, -v80
	v_fma_f32 v81, v27, v82, v81
	v_mov_b32_e32 v85, v81
	v_add_f32_e32 v80, v86, v84
	v_add_f32_e32 v81, v87, v85
	v_sub_f32_e32 v82, v86, v84
	v_sub_f32_e32 v83, v87, v85
	ds_write_b64 v104, v[80:81]
	v_mul_f32_e32 v80, v30, v83
	v_mul_f32_e32 v81, v31, v83
	v_fma_f32 v84, v28, v82, -v80
	v_fma_f32 v81, v29, v82, v81
	v_mov_b32_e32 v85, v81
	v_mul_f32_e32 v80, v44, v65
;     static __device__ __forceinline__ float sl(float g, float up) { return g * __builtin_amdgcn_rcpf(1.0f + __builtin_amdgcn_exp2f(-1.4426950408889634f * g)) * up; }
; __device__ __forceinline__ float2 cmul(float2 a, float2 b) { return make_float2(a.x * b.x - a.y * b.y, a.x * b.y + a.y * b.x); }
; #define tid ltid()
; template <int LR, bool INV>
; __device__ __forceinline__ void fft_stages(float2 (&x)[1 << LR], const int r, const int s) {
;   constexpr int R = 1 << LR;
; #pragma unroll
;   for (int st = 0; st < LR; ++st) {
;     const int hl = INV ? (1 << st) : (R >> (st + 1));
;     const float fb = (float)r * (0.5f / (float)(hl * s));
;     const float2 wb = make_float2(__builtin_amdgcn_cosf(fb), INV ? __builtin_amdgcn_sinf(fb) : -__builtin_amdgcn_sinf(fb));
; #pragma unroll
;     for (int m = 0; m < R; ++m) {
;       if (m & hl) continue;
;       const int k = m & (hl - 1); const int j = k * (8 / hl);
;       const float2 wc = make_float2(c16(j), INV ? s16(j) : -s16(j));
;       const float2 tw = cmul(wb, wc);
;       if (!INV) { const float2 p = x[m], q = x[m + hl]; x[m] = make_float2(p.x + q.x, p.y + q.y); x[m + hl] = cmul(make_float2(p.x - q.x, p.y - q.y), tw); }
;       else { const float2 p = x[m], q = cmul(x[m + hl], tw); x[m] = make_float2(p.x + q.x, p.y + q.y); x[m + hl] = make_float2(p.x - q.x, p.y - q.y); }
;     }
;   }
; }
; template <int LR, bool INV>
; __device__ __forceinline__ void fft_pass(float2* X, const int N, const int sl, const int tid) {
;   constexpr int R = 1 << LR;
;   const int s = 1 << sl;
;   for (int g = tid; g < (N >> LR); g += NTHR) {
;     const int r = g & (s - 1);
;     const int i0 = ((g >> sl) << (sl + LR)) + r;
;     float2 x[R];
; #pragma unroll
;     for (int m = 0; m < R; ++m) x[m] = X[PIDX(i0 + (m << sl))];
;     fft_stages<LR, INV>(x, r, s);
; #pragma unroll
;     for (int m = 0; m < R; ++m) X[PIDX(i0 + (m << sl))] = x[m];
	v_mul_f32_e32 v81, v45, v65
	ds_write_b64 v105, v[84:85]
	v_fma_f32 v82, v0, v64, -v80
	v_fma_f32 v65, v1, v64, v81
	v_mov_b32_e32 v83, v65
	v_mul_f32_e32 v64, v46, v67
	v_mul_f32_e32 v65, v47, v67
	v_fma_f32 v80, v2, v66, -v64
	v_fma_f32 v65, v3, v66, v65
	v_mov_b32_e32 v81, v65
	v_mul_f32_e32 v64, v48, v69
	v_mul_f32_e32 v65, v49, v69
	v_fma_f32 v66, v4, v68, -v64
	v_fma_f32 v65, v5, v68, v65
	v_mov_b32_e32 v67, v65
	v_mul_f32_e32 v64, v50, v71
	v_mul_f32_e32 v65, v51, v71
	v_fma_f32 v68, v6, v70, -v64
	v_fma_f32 v65, v7, v70, v65
	v_mov_b32_e32 v69, v65
	v_mul_f32_e32 v64, v52, v73
	v_mul_f32_e32 v65, v53, v73
	v_fma_f32 v70, v8, v72, -v64
	v_fma_f32 v65, v9, v72, v65
	v_mov_b32_e32 v71, v65
	v_mul_f32_e32 v64, v54, v75
	v_mul_f32_e32 v65, v55, v75
	v_fma_f32 v72, v10, v74, -v64
	v_fma_f32 v65, v11, v74, v65
	v_mov_b32_e32 v73, v65
	v_mul_f32_e32 v64, v56, v77
	v_mul_f32_e32 v65, v57, v77
	v_fma_f32 v74, v12, v76, -v64
	v_fma_f32 v65, v13, v76, v65
	v_mov_b32_e32 v75, v65
	v_mul_f32_e32 v64, v58, v79
	v_mul_f32_e32 v65, v59, v79
	v_fma_f32 v76, v14, v78, -v64
	v_fma_f32 v65, v15, v78, v65
	v_add_f32_e32 v78, v80, v72
	v_add_f32_e32 v79, v81, v73
	v_mov_b32_e32 v77, v65
	v_add_f32_e32 v64, v82, v70
	v_add_f32_e32 v65, v83, v71
	v_sub_f32_e32 v72, v80, v72
	v_sub_f32_e32 v73, v81, v73
	v_add_f32_e32 v80, v66, v74
	v_add_f32_e32 v81, v67, v75
	v_sub_f32_e32 v66, v66, v74
	v_sub_f32_e32 v67, v67, v75
	v_add_f32_e32 v74, v68, v76
	v_add_f32_e32 v75, v69, v77
	v_sub_f32_e32 v68, v68, v76
	v_sub_f32_e32 v69, v69, v77
	v_add_f32_e32 v76, v64, v80
	v_add_f32_e32 v77, v65, v81
	v_sub_f32_e32 v64, v64, v80
	v_sub_f32_e32 v65, v65, v81
	v_add_f32_e32 v80, v78, v74
	v_add_f32_e32 v81, v79, v75
	v_sub_f32_e32 v74, v78, v74
	v_sub_f32_e32 v75, v79, v75
	v_add_f32_e32 v78, v76, v80
	v_add_f32_e32 v79, v77, v81
	v_sub_f32_e32 v76, v76, v80
	v_sub_f32_e32 v77, v77, v81
	ds_write_b64 v106, v[78:79]
	v_mul_f32_e32 v78, v30, v77
	v_mul_f32_e32 v79, v31, v77
	v_sub_f32_e32 v70, v82, v70
	v_sub_f32_e32 v71, v83, v71
	v_fma_f32 v80, v28, v76, -v78
	v_fma_f32 v77, v29, v76, v79
	v_mov_b32_e32 v81, v77
	v_mul_f32_e32 v76, v32, v65
	v_mul_f32_e32 v77, v33, v65
	ds_write_b64 v107, v[80:81]
	v_fma_f32 v78, v24, v64, -v76
	v_fma_f32 v65, v25, v64, v77
	v_mov_b32_e32 v79, v65
	v_mul_f32_e32 v64, v34, v75
	v_mul_f32_e32 v65, v35, v75
	v_fma_f32 v76, v26, v74, -v64
	v_fma_f32 v65, v27, v74, v65
	v_mov_b32_e32 v77, v65
	v_add_f32_e32 v64, v78, v76
	v_add_f32_e32 v65, v79, v77
	v_sub_f32_e32 v74, v78, v76
	v_sub_f32_e32 v75, v79, v77
	ds_write_b64 v108, v[64:65]
	v_mul_f32_e32 v64, v30, v75
	v_mul_f32_e32 v65, v31, v75
	v_fma_f32 v76, v28, v74, -v64
	v_fma_f32 v65, v29, v74, v65
	v_mov_b32_e32 v77, v65
	v_mul_f32_e32 v64, v36, v71
	v_mul_f32_e32 v65, v37, v71
	ds_write_b64 v109, v[76:77]
	v_fma_f32 v74, v16, v70, -v64
	v_fma_f32 v65, v17, v70, v65
	v_mov_b32_e32 v75, v65
	v_mul_f32_e32 v64, v38, v73
	v_mul_f32_e32 v65, v39, v73
	v_fma_f32 v70, v18, v72, -v64
	v_fma_f32 v65, v19, v72, v65
	v_mov_b32_e32 v71, v65
	v_mul_f32_e32 v64, v40, v67
	v_mul_f32_e32 v65, v41, v67
	v_fma_f32 v72, v20, v66, -v64
	v_fma_f32 v65, v21, v66, v65
	v_mov_b32_e32 v73, v65
	v_mul_f32_e32 v64, v42, v69
	v_mul_f32_e32 v65, v43, v69
	v_fma_f32 v66, v22, v68, -v64
	v_fma_f32 v65, v23, v68, v65
	v_sub_f32_e32 v68, v74, v72
	v_sub_f32_e32 v69, v75, v73
	v_mov_b32_e32 v67, v65
	v_add_f32_e32 v64, v74, v72
	v_add_f32_e32 v65, v75, v73
	v_add_f32_e32 v72, v70, v66
	v_add_f32_e32 v73, v71, v67
	v_sub_f32_e32 v66, v70, v66
	v_sub_f32_e32 v67, v71, v67
	v_add_f32_e32 v70, v64, v72
	v_add_f32_e32 v71, v65, v73
	v_sub_f32_e32 v64, v64, v72
	v_sub_f32_e32 v65, v65, v73
	ds_write_b64 v110, v[70:71]
	v_mul_f32_e32 v70, v30, v65
	v_mul_f32_e32 v71, v31, v65
	v_fma_f32 v72, v28, v64, -v70
	v_fma_f32 v65, v29, v64, v71
	v_mov_b32_e32 v73, v65
	v_mul_f32_e32 v64, v32, v69
	v_mul_f32_e32 v65, v33, v69
	ds_write_b64 v111, v[72:73]
	v_fma_f32 v70, v24, v68, -v64
	v_fma_f32 v65, v25, v68, v65
	v_mov_b32_e32 v71, v65
	v_mul_f32_e32 v64, v34, v67
	v_mul_f32_e32 v65, v35, v67
	v_fma_f32 v68, v26, v66, -v64
	v_fma_f32 v65, v27, v66, v65
	v_mov_b32_e32 v69, v65
	v_add_f32_e32 v64, v70, v68
	v_add_f32_e32 v65, v71, v69
	v_sub_f32_e32 v66, v70, v68
	v_sub_f32_e32 v67, v71, v69
	ds_write_b64 v112, v[64:65]
	v_mul_f32_e32 v64, v30, v67
	v_mul_f32_e32 v65, v31, v67
	v_fma_f32 v68, v28, v66, -v64
	v_fma_f32 v65, v29, v66, v65
	v_mov_b32_e32 v69, v65
	ds_write_b64 v113, v[68:69]
	s_andn2_b64 exec, exec, s[14:15]
	s_cbranch_execnz .LBB0_656

;     static __device__ __forceinline__ float sl(float g, float up) { return g * __builtin_amdgcn_rcpf(1.0f + __builtin_amdgcn_exp2f(-1.4426950408889634f * g)) * up; }
; __device__ __forceinline__ float2 cmul(float2 a, float2 b) { return make_float2(a.x * b.x - a.y * b.y, a.x * b.y + a.y * b.x); }
; #define tid ltid()
; template <int LR, bool INV>
; __device__ __forceinline__ void fft_stages(float2 (&x)[1 << LR], const int r, const int s) {
;   constexpr int R = 1 << LR;
; #pragma unroll
;   for (int st = 0; st < LR; ++st) {
;     const int hl = INV ? (1 << st) : (R >> (st + 1));
;     const float fb = (float)r * (0.5f / (float)(hl * s));
;     const float2 wb = make_float2(__builtin_amdgcn_cosf(fb), INV ? __builtin_amdgcn_sinf(fb) : -__builtin_amdgcn_sinf(fb));
; #pragma unroll
;     for (int m = 0; m < R; ++m) {
;       if (m & hl) continue;
;       const int k = m & (hl - 1); const int j = k * (8 / hl);
;       const float2 wc = make_float2(c16(j), INV ? s16(j) : -s16(j));
;       const float2 tw = cmul(wb, wc);
;       if (!INV) { const float2 p = x[m], q = x[m + hl]; x[m] = make_float2(p.x + q.x, p.y + q.y); x[m + hl] = cmul(make_float2(p.x - q.x, p.y - q.y), tw); }
;       else { const float2 p = x[m], q = cmul(x[m + hl], tw); x[m] = make_float2(p.x + q.x, p.y + q.y); x[m + hl] = make_float2(p.x - q.x, p.y - q.y); }
;     }
;   }
; }
; template <int LR, bool INV>
; __device__ __forceinline__ void fft_pass(float2* X, const int N, const int sl, const int tid) {
;   constexpr int R = 1 << LR;
;   const int s = 1 << sl;
;   for (int g = tid; g < (N >> LR); g += NTHR) {
;     const int r = g & (s - 1);
;     const int i0 = ((g >> sl) << (sl + LR)) + r;
;     float2 x[R];
; #pragma unroll
;     for (int m = 0; m < R; ++m) x[m] = X[PIDX(i0 + (m << sl))];
;     fft_stages<LR, INV>(x, r, s);
; #pragma unroll
;     for (int m = 0; m < R; ++m) X[PIDX(i0 + (m << sl))] = x[m];
;   }
;   __syncthreads();
.LBB0_658:
	v_cmp_gt_i32_e32 vcc, s19, v60
	v_lshlrev_b32_e32 v28, 3, v60
	s_and_saveexec_b64 s[12:13], vcc
	s_cbranch_execz .LBB0_661
	v_and_b32_e32 v29, 63, v60
	v_cvt_f32_ubyte0_e32 v14, v29
	v_mul_f32_e32 v0, 0x3b000000, v14
	v_sin_f32_e32 v6, v0
	v_cos_f32_e32 v7, v0
	v_mul_f32_e32 v11, 0x3b800000, v14
	v_sin_f32_e32 v10, v11
	v_cos_f32_e32 v11, v11
	v_mul_f32_e32 v15, 0x3c000000, v14
	v_sin_f32_e32 v14, v15
	v_cos_f32_e32 v15, v15
	v_xor_b32_e32 v2, 0x80000000, v6
	v_pk_mov_b32 v[0:1], v[6:7], v[6:7] op_sel:[1,0]
	s_mov_b32 s90, s75
	v_mov_b32_e32 v1, v2
	v_mul_f32_e32 v8, s70, v6
	v_mul_f32_e32 v9, s70, v7
	s_mov_b32 s14, s71
	s_mov_b32 s15, s70
	s_mov_b32 s74, s91
	v_fma_f32 v0, -v6, 0, v0
	v_fma_f32 v1, -v7, 0, v1
	v_fma_f32 v2, v7, s14, v8
	v_fma_f32 v3, v6, s15, v9
	v_fma_f32 v4, v7, s90, -v6
	v_fma_f32 v5, v6, s91, -v7
	v_pk_fma_f32 v[6:7], v[6:7], s[70:71], v[8:9] op_sel:[1,0,0] op_sel_hi:[0,1,1]
	v_xor_b32_e32 v9, 0x80000000, v10
	v_mul_f32_e32 v12, s74, v10
	v_mul_f32_e32 v13, s75, v11
	v_mov_b32_e32 v8, v11
	v_fma_f32 v8, -v10, 0, v8
	v_fma_f32 v9, -v11, 0, v9
	v_sub_f32_e32 v10, v13, v10
	v_sub_f32_e32 v11, v12, v11
	v_xor_b32_e32 v13, 0x80000000, v14
	v_mov_b32_e32 v12, v15
	v_fma_f32 v12, -v14, 0, v12
	v_fma_f32 v13, -v15, 0, v13
	v_pk_mov_b32 v[16:17], v[8:9], v[8:9] op_sel:[1,0]
	v_pk_mov_b32 v[14:15], v[12:13], v[12:13] op_sel:[1,0]
	v_pk_mov_b32 v[18:19], v[10:11], v[10:11] op_sel:[1,0]
	v_pk_mov_b32 v[20:21], v[0:1], v[0:1] op_sel:[1,0]
	v_pk_mov_b32 v[22:23], v[2:3], v[2:3] op_sel:[1,0]
	v_pk_mov_b32 v[24:25], v[4:5], v[4:5] op_sel:[1,0]
	v_pk_mov_b32 v[26:27], v[6:7], v[6:7] op_sel:[1,0]
	v_lshlrev_b32_e32 v30, 3, v60
	s_mov_b64 s[14:15], 0
	v_mov_b32_e32 v31, v60
.LBB0_660:
	v_and_or_b32 v32, v30, s53, v29
	v_ashrrev_i32_e32 v33, 4, v32
	v_lshlrev_b32_e32 v33, 3, v33
	v_lshlrev_b32_e32 v34, 3, v32
	v_add3_u32 v50, s52, v33, v34
	v_or_b32_e32 v33, 64, v32
	v_ashrrev_i32_e32 v33, 4, v33
	v_lshlrev_b32_e32 v33, 3, v33
	v_add3_u32 v51, s52, v33, v34
	v_or_b32_e32 v33, 0x80, v32
	v_ashrrev_i32_e32 v33, 4, v33
	v_lshlrev_b32_e32 v33, 3, v33
	v_add3_u32 v52, s52, v33, v34
	v_or_b32_e32 v33, 0xc0, v32
	v_ashrrev_i32_e32 v33, 4, v33
	v_lshlrev_b32_e32 v33, 3, v33
	v_add3_u32 v53, s52, v33, v34
	v_or_b32_e32 v33, 0x100, v32
	v_ashrrev_i32_e32 v33, 4, v33
	v_lshlrev_b32_e32 v33, 3, v33
	v_add3_u32 v54, s52, v33, v34
	v_or_b32_e32 v33, 0x140, v32
	v_ashrrev_i32_e32 v33, 4, v33
	v_lshlrev_b32_e32 v33, 3, v33
	v_add3_u32 v55, s52, v33, v34
	v_or_b32_e32 v33, 0x180, v32
	v_or_b32_e32 v32, 0x1c0, v32
	v_ashrrev_i32_e32 v33, 4, v33
	v_ashrrev_i32_e32 v32, 4, v32
	v_lshlrev_b32_e32 v33, 3, v33
	v_lshlrev_b32_e32 v32, 3, v32
	v_add3_u32 v56, s52, v33, v34
	v_add3_u32 v57, s52, v32, v34
	ds_read_b64 v[32:33], v50
	ds_read_b64 v[34:35], v51 offset:512
	ds_read_b64 v[36:37], v52 offset:1024
	ds_read_b64 v[38:39], v53 offset:1536
	ds_read_b64 v[40:41], v54 offset:2048
	ds_read_b64 v[42:43], v55 offset:2560
	ds_read_b64 v[44:45], v56 offset:3072
	ds_read_b64 v[46:47], v57 offset:3584
	v_add_u32_e32 v31, 0x200, v31
	s_waitcnt lgkmcnt(3)
	v_add_f32_e32 v48, v32, v40
	v_add_f32_e32 v49, v33, v41
	v_sub_f32_e32 v32, v32, v40
	v_sub_f32_e32 v33, v33, v41
	s_waitcnt lgkmcnt(2)
	v_add_f32_e32 v40, v34, v42
	v_add_f32_e32 v41, v35, v43
	v_sub_f32_e32 v34, v34, v42
	v_sub_f32_e32 v35, v35, v43
	s_waitcnt lgkmcnt(1)
	v_add_f32_e32 v42, v36, v44
	v_add_f32_e32 v43, v37, v45
	v_sub_f32_e32 v36, v36, v44
	v_sub_f32_e32 v37, v37, v45
	s_waitcnt lgkmcnt(0)
	v_add_f32_e32 v44, v38, v46
	v_add_f32_e32 v45, v39, v47
	v_sub_f32_e32 v38, v38, v46
	v_sub_f32_e32 v39, v39, v47
	v_add_f32_e32 v46, v48, v42
	v_add_f32_e32 v47, v49, v43
	v_sub_f32_e32 v42, v48, v42
	v_sub_f32_e32 v43, v49, v43
	v_add_f32_e32 v48, v40, v44
	v_add_f32_e32 v49, v41, v45
	v_sub_f32_e32 v40, v40, v44
	v_sub_f32_e32 v41, v41, v45
	v_add_f32_e32 v44, v46, v48
	v_add_f32_e32 v45, v47, v49
	v_sub_f32_e32 v46, v46, v48
	v_sub_f32_e32 v47, v47, v49
	ds_write_b64 v50, v[44:45]
	v_mul_f32_e32 v44, v14, v47
	v_mul_f32_e32 v45, v15, v47
	v_cmp_le_i32_e64 s[40:41], s19, v31
	v_fma_f32 v48, v12, v46, -v44
	v_fma_f32 v45, v13, v46, v45
	v_add_u32_e32 v30, 0x1000, v30
	v_mov_b32_e32 v49, v45
	v_mul_f32_e32 v44, v16, v43
	v_mul_f32_e32 v45, v17, v43
	ds_write_b64 v51, v[48:49] offset:512
	v_fma_f32 v46, v8, v42, -v44
	v_fma_f32 v43, v9, v42, v45
	s_or_b64 s[14:15], s[40:41], s[14:15]
	v_mov_b32_e32 v47, v43
	v_mul_f32_e32 v42, v18, v41
	v_mul_f32_e32 v43, v19, v41
	v_fma_f32 v44, v10, v40, -v42
	v_fma_f32 v41, v11, v40, v43
	v_mov_b32_e32 v45, v41
	v_add_f32_e32 v40, v46, v44
	v_add_f32_e32 v41, v47, v45
	v_sub_f32_e32 v42, v46, v44
	v_sub_f32_e32 v43, v47, v45
	ds_write_b64 v52, v[40:41] offset:1024
	v_mul_f32_e32 v40, v14, v43
	v_mul_f32_e32 v41, v15, v43
	v_fma_f32 v44, v12, v42, -v40
	v_fma_f32 v41, v13, v42, v41
	v_mov_b32_e32 v45, v41
	v_mul_f32_e32 v40, v20, v33
	v_mul_f32_e32 v41, v21, v33
	ds_write_b64 v53, v[44:45] offset:1536
	v_fma_f32 v42, v0, v32, -v40
	v_fma_f32 v33, v1, v32, v41
	v_mov_b32_e32 v43, v33
	v_mul_f32_e32 v32, v22, v35
	v_mul_f32_e32 v33, v23, v35
	v_fma_f32 v40, v2, v34, -v32
	v_fma_f32 v33, v3, v34, v33
	v_mov_b32_e32 v41, v33
	v_mul_f32_e32 v32, v24, v37
	v_mul_f32_e32 v33, v25, v37
	v_fma_f32 v34, v4, v36, -v32
	v_fma_f32 v33, v5, v36, v33
	v_mov_b32_e32 v35, v33
	v_mul_f32_e32 v32, v26, v39
	v_mul_f32_e32 v33, v27, v39
	v_fma_f32 v36, v6, v38, -v32
	v_fma_f32 v33, v7, v38, v33
	v_mov_b32_e32 v37, v33
	v_add_f32_e32 v32, v42, v34
	v_add_f32_e32 v33, v43, v35
	v_add_f32_e32 v38, v40, v36
	v_add_f32_e32 v39, v41, v37
	v_sub_f32_e32 v36, v40, v36
	v_sub_f32_e32 v37, v41, v37
	v_add_f32_e32 v40, v32, v38
	v_add_f32_e32 v41, v33, v39
	v_sub_f32_e32 v32, v32, v38
	v_sub_f32_e32 v33, v33, v39
	v_sub_f32_e32 v34, v42, v34
	v_sub_f32_e32 v35, v43, v35
	v_mul_f32_e32 v38, v14, v33
	v_mul_f32_e32 v39, v15, v33
	ds_write_b64 v54, v[40:41] offset:2048
	v_fma_f32 v40, v12, v32, -v38
	v_fma_f32 v33, v13, v32, v39
	v_mov_b32_e32 v41, v33
	v_mul_f32_e32 v32, v16, v35
	v_mul_f32_e32 v33, v17, v35
	ds_write_b64 v55, v[40:41] offset:2560
	v_fma_f32 v38, v8, v34, -v32
	v_fma_f32 v33, v9, v34, v33
	v_mov_b32_e32 v39, v33
	v_mul_f32_e32 v32, v18, v37
	v_mul_f32_e32 v33, v19, v37
	v_fma_f32 v34, v10, v36, -v32
	v_fma_f32 v33, v11, v36, v33
	v_mov_b32_e32 v35, v33
	v_add_f32_e32 v32, v38, v34
	v_add_f32_e32 v33, v39, v35
	v_sub_f32_e32 v34, v38, v34
	v_sub_f32_e32 v35, v39, v35
	ds_write_b64 v56, v[32:33] offset:3072
	v_mul_f32_e32 v32, v14, v35
	v_mul_f32_e32 v33, v15, v35
	v_fma_f32 v36, v12, v34, -v32
	v_fma_f32 v32, v12, v34, v32
	v_fma_f32 v33, v13, v34, v33
	v_mov_b32_e32 v37, v33
	ds_write_b64 v57, v[36:37] offset:3584
	s_andn2_b64 exec, exec, s[14:15]
	s_cbranch_execnz .LBB0_660
;     static __device__ __forceinline__ float sl(float g, float up) { return g * __builtin_amdgcn_rcpf(1.0f + __builtin_amdgcn_exp2f(-1.4426950408889634f * g)) * up; }
; __device__ __forceinline__ float2 cmul(float2 a, float2 b) { return make_float2(a.x * b.x - a.y * b.y, a.x * b.y + a.y * b.x); }
; #define tid ltid()
; template <int LR, bool INV>
; __device__ __forceinline__ void fft_stages(float2 (&x)[1 << LR], const int r, const int s) {
;   constexpr int R = 1 << LR;
; #pragma unroll
;   for (int st = 0; st < LR; ++st) {
;     const int hl = INV ? (1 << st) : (R >> (st + 1));
;     const float fb = (float)r * (0.5f / (float)(hl * s));
;     const float2 wb = make_float2(__builtin_amdgcn_cosf(fb), INV ? __builtin_amdgcn_sinf(fb) : -__builtin_amdgcn_sinf(fb));
; #pragma unroll
;     for (int m = 0; m < R; ++m) {
;       if (m & hl) continue;
;       const int k = m & (hl - 1); const int j = k * (8 / hl);
;       const float2 wc = make_float2(c16(j), INV ? s16(j) : -s16(j));
;       const float2 tw = cmul(wb, wc);
;       if (!INV) { const float2 p = x[m], q = x[m + hl]; x[m] = make_float2(p.x + q.x, p.y + q.y); x[m + hl] = cmul(make_float2(p.x - q.x, p.y - q.y), tw); }
;       else { const float2 p = x[m], q = cmul(x[m + hl], tw); x[m] = make_float2(p.x + q.x, p.y + q.y); x[m + hl] = make_float2(p.x - q.x, p.y - q.y); }
;     }
;   }
; }
; template <int LR, bool INV>
; __device__ __forceinline__ void fft_pass(float2* X, const int N, const int sl, const int tid) {
;   constexpr int R = 1 << LR;
;   const int s = 1 << sl;
;   for (int g = tid; g < (N >> LR); g += NTHR) {
;     const int r = g & (s - 1);
;     const int i0 = ((g >> sl) << (sl + LR)) + r;
;     float2 x[R];
; #pragma unroll
;     for (int m = 0; m < R; ++m) x[m] = X[PIDX(i0 + (m << sl))];
;     fft_stages<LR, INV>(x, r, s);
; #pragma unroll
;     for (int m = 0; m < R; ++m) X[PIDX(i0 + (m << sl))] = x[m];
;   }
;   __syncthreads();
.LBB0_661:
	s_or_b64 exec, exec, s[12:13]
	s_waitcnt lgkmcnt(0)
	s_barrier
	s_and_saveexec_b64 s[12:13], vcc
	s_cbranch_execz .LBB0_664
	v_and_b32_e32 v29, 7, v60
	v_cvt_f32_ubyte0_e32 v14, v29
	v_mul_f32_e32 v0, 0x3c800000, v14
	v_sin_f32_e32 v6, v0
	v_cos_f32_e32 v7, v0
	v_mul_f32_e32 v11, 0x3d000000, v14
	v_sin_f32_e32 v10, v11
	v_cos_f32_e32 v11, v11
	v_mul_f32_e32 v15, 0x3d800000, v14
	v_sin_f32_e32 v14, v15
	v_cos_f32_e32 v15, v15
	v_xor_b32_e32 v2, 0x80000000, v6
	v_pk_mov_b32 v[0:1], v[6:7], v[6:7] op_sel:[1,0]
	s_mov_b32 s90, s75
	v_mov_b32_e32 v1, v2
	v_mul_f32_e32 v8, s70, v6
	v_mul_f32_e32 v9, s70, v7
	s_mov_b32 s14, s71
	s_mov_b32 s15, s70
	s_mov_b32 s74, s91
	v_fma_f32 v0, -v6, 0, v0
	v_fma_f32 v1, -v7, 0, v1
	v_fma_f32 v2, v7, s14, v8
	v_fma_f32 v3, v6, s15, v9
	v_fma_f32 v4, v7, s90, -v6
	v_fma_f32 v5, v6, s91, -v7
	v_pk_fma_f32 v[6:7], v[6:7], s[70:71], v[8:9] op_sel:[1,0,0] op_sel_hi:[0,1,1]
	v_xor_b32_e32 v9, 0x80000000, v10
	v_mul_f32_e32 v12, s74, v10
	v_mul_f32_e32 v13, s75, v11
	v_mov_b32_e32 v8, v11
	v_fma_f32 v8, -v10, 0, v8
	v_fma_f32 v9, -v11, 0, v9
	v_sub_f32_e32 v10, v13, v10
	v_sub_f32_e32 v11, v12, v11
	v_xor_b32_e32 v13, 0x80000000, v14
	v_mov_b32_e32 v12, v15
	v_fma_f32 v12, -v14, 0, v12
	v_fma_f32 v13, -v15, 0, v13
	v_pk_mov_b32 v[16:17], v[8:9], v[8:9] op_sel:[1,0]
	v_pk_mov_b32 v[14:15], v[12:13], v[12:13] op_sel:[1,0]
	v_pk_mov_b32 v[18:19], v[10:11], v[10:11] op_sel:[1,0]
	v_pk_mov_b32 v[20:21], v[0:1], v[0:1] op_sel:[1,0]
	v_pk_mov_b32 v[22:23], v[2:3], v[2:3] op_sel:[1,0]
	v_pk_mov_b32 v[24:25], v[4:5], v[4:5] op_sel:[1,0]
	v_pk_mov_b32 v[26:27], v[6:7], v[6:7] op_sel:[1,0]
	v_lshlrev_b32_e32 v30, 3, v60
	s_mov_b64 s[14:15], 0
	v_mov_b32_e32 v31, v60
.LBB0_663:
	v_and_b32_e32 v32, 0xffffffc0, v30
	v_or_b32_e32 v33, v32, v29
	v_ashrrev_i32_e32 v34, 1, v32
	v_lshlrev_b32_e32 v33, 3, v33
	v_add3_u32 v52, s52, v34, v33
	v_or_b32_e32 v34, 16, v32
	v_ashrrev_i32_e32 v34, 4, v34
	v_lshlrev_b32_e32 v34, 3, v34
	v_add3_u32 v53, s52, v34, v33
	v_or_b32_e32 v34, 32, v32
	v_or_b32_e32 v32, 48, v32
	v_ashrrev_i32_e32 v34, 4, v34
	v_ashrrev_i32_e32 v32, 4, v32
	v_lshlrev_b32_e32 v34, 3, v34
	v_lshlrev_b32_e32 v32, 3, v32
	v_add3_u32 v54, s52, v34, v33
	v_add3_u32 v55, s52, v32, v33
	ds_read2_b64 v[32:35], v52 offset1:8
	ds_read2_b64 v[36:39], v53 offset0:16 offset1:24
	ds_read2_b64 v[40:43], v54 offset0:32 offset1:40
	ds_read2_b64 v[44:47], v55 offset0:48 offset1:56
	v_add_u32_e32 v31, 0x200, v31
	v_cmp_le_i32_e64 s[40:41], s19, v31
	v_add_u32_e32 v30, 0x1000, v30
	s_waitcnt lgkmcnt(1)
	v_add_f32_e32 v48, v32, v40
	v_add_f32_e32 v49, v33, v41
	v_sub_f32_e32 v32, v32, v40
	v_sub_f32_e32 v33, v33, v41
	v_add_f32_e32 v40, v34, v42
	v_add_f32_e32 v41, v35, v43
	v_sub_f32_e32 v34, v34, v42
	v_sub_f32_e32 v35, v35, v43
	s_waitcnt lgkmcnt(0)
	v_add_f32_e32 v42, v36, v44
	v_add_f32_e32 v43, v37, v45
	v_sub_f32_e32 v36, v36, v44
	v_sub_f32_e32 v37, v37, v45
	v_add_f32_e32 v44, v38, v46
	v_add_f32_e32 v45, v39, v47
	v_sub_f32_e32 v38, v38, v46
	v_sub_f32_e32 v39, v39, v47
	v_add_f32_e32 v46, v48, v42
	v_add_f32_e32 v47, v49, v43
	v_sub_f32_e32 v42, v48, v42
	v_sub_f32_e32 v43, v49, v43
	v_add_f32_e32 v48, v40, v44
	v_add_f32_e32 v49, v41, v45
	v_sub_f32_e32 v40, v40, v44
	v_sub_f32_e32 v41, v41, v45
	v_add_f32_e32 v44, v46, v48
	v_add_f32_e32 v45, v47, v49
	v_sub_f32_e32 v46, v46, v48
	v_sub_f32_e32 v47, v47, v49
	s_or_b64 s[14:15], s[40:41], s[14:15]
	v_mul_f32_e32 v48, v14, v47
	v_mul_f32_e32 v49, v15, v47
	v_fma_f32 v50, v12, v46, -v48
	v_fma_f32 v47, v13, v46, v49
	v_mov_b32_e32 v51, v47
	ds_write2_b64 v52, v[44:45], v[50:51] offset1:8
	v_mul_f32_e32 v44, v16, v43
	v_mul_f32_e32 v45, v17, v43
	v_fma_f32 v46, v8, v42, -v44
	v_fma_f32 v43, v9, v42, v45
	v_mov_b32_e32 v47, v43
	v_mul_f32_e32 v42, v18, v41
	v_mul_f32_e32 v43, v19, v41
	v_fma_f32 v44, v10, v40, -v42
	v_fma_f32 v41, v11, v40, v43
	v_mov_b32_e32 v45, v41
	v_sub_f32_e32 v42, v46, v44
	v_sub_f32_e32 v43, v47, v45
	v_add_f32_e32 v40, v46, v44
	v_add_f32_e32 v41, v47, v45
	v_mul_f32_e32 v44, v14, v43
	v_mul_f32_e32 v45, v15, v43
	v_fma_f32 v46, v12, v42, -v44
	v_fma_f32 v43, v13, v42, v45
	v_mov_b32_e32 v47, v43
	ds_write2_b64 v53, v[40:41], v[46:47] offset0:16 offset1:24
	v_mul_f32_e32 v40, v20, v33
	v_mul_f32_e32 v41, v21, v33
	v_fma_f32 v42, v0, v32, -v40
	v_fma_f32 v33, v1, v32, v41
	v_mov_b32_e32 v43, v33
	v_mul_f32_e32 v32, v22, v35
	v_mul_f32_e32 v33, v23, v35
	v_fma_f32 v40, v2, v34, -v32
	v_fma_f32 v33, v3, v34, v33
	v_mov_b32_e32 v41, v33
	v_mul_f32_e32 v32, v24, v37
	v_mul_f32_e32 v33, v25, v37
	v_fma_f32 v34, v4, v36, -v32
	v_fma_f32 v33, v5, v36, v33
	v_mov_b32_e32 v35, v33
	v_mul_f32_e32 v32, v26, v39
	v_mul_f32_e32 v33, v27, v39
	v_fma_f32 v36, v6, v38, -v32
	v_fma_f32 v33, v7, v38, v33
	v_mov_b32_e32 v37, v33
	v_add_f32_e32 v32, v42, v34
	v_add_f32_e32 v33, v43, v35
	v_add_f32_e32 v38, v40, v36
	v_add_f32_e32 v39, v41, v37
	v_sub_f32_e32 v36, v40, v36
	v_sub_f32_e32 v37, v41, v37
	v_add_f32_e32 v40, v32, v38
	v_add_f32_e32 v41, v33, v39
	v_sub_f32_e32 v32, v32, v38
	v_sub_f32_e32 v33, v33, v39
	v_sub_f32_e32 v34, v42, v34
	v_sub_f32_e32 v35, v43, v35
	v_mul_f32_e32 v38, v14, v33
	v_mul_f32_e32 v39, v15, v33
	v_fma_f32 v42, v12, v32, -v38
	v_fma_f32 v33, v13, v32, v39
	v_mov_b32_e32 v43, v33
	v_mul_f32_e32 v32, v16, v35
	v_mul_f32_e32 v33, v17, v35
	ds_write2_b64 v54, v[40:41], v[42:43] offset0:32 offset1:40
	v_fma_f32 v38, v8, v34, -v32
	v_fma_f32 v33, v9, v34, v33
	v_mov_b32_e32 v39, v33
	v_mul_f32_e32 v32, v18, v37
	v_mul_f32_e32 v33, v19, v37
	v_fma_f32 v34, v10, v36, -v32
	v_fma_f32 v33, v11, v36, v33
	v_mov_b32_e32 v35, v33
	v_add_f32_e32 v32, v38, v34
	v_add_f32_e32 v33, v39, v35
	v_sub_f32_e32 v34, v38, v34
	v_sub_f32_e32 v35, v39, v35
	v_mul_f32_e32 v36, v14, v35
	v_mul_f32_e32 v37, v15, v35
	v_fma_f32 v38, v12, v34, -v36
	v_fma_f32 v35, v13, v34, v37
	v_fma_f32 v34, v12, v34, v36
	v_mov_b32_e32 v39, v35
	ds_write2_b64 v55, v[32:33], v[38:39] offset0:48 offset1:56
	s_andn2_b64 exec, exec, s[14:15]
	s_cbranch_execnz .LBB0_663

;     static __device__ __forceinline__ float sl(float g, float up) { return g * __builtin_amdgcn_rcpf(1.0f + __builtin_amdgcn_exp2f(-1.4426950408889634f * g)) * up; }
; __device__ __forceinline__ float2 cmul(float2 a, float2 b) { return make_float2(a.x * b.x - a.y * b.y, a.x * b.y + a.y * b.x); }
; #define tid ltid()
; template <int LR, bool INV>
; __device__ __forceinline__ void fft_stages(float2 (&x)[1 << LR], const int r, const int s) {
;   constexpr int R = 1 << LR;
; #pragma unroll
;   for (int st = 0; st < LR; ++st) {
;     const int hl = INV ? (1 << st) : (R >> (st + 1));
;     const float fb = (float)r * (0.5f / (float)(hl * s));
;     const float2 wb = make_float2(__builtin_amdgcn_cosf(fb), INV ? __builtin_amdgcn_sinf(fb) : -__builtin_amdgcn_sinf(fb));
; #pragma unroll
;     for (int m = 0; m < R; ++m) {
;       if (m & hl) continue;
;       const int k = m & (hl - 1); const int j = k * (8 / hl);
;       const float2 wc = make_float2(c16(j), INV ? s16(j) : -s16(j));
;       const float2 tw = cmul(wb, wc);
;       if (!INV) { const float2 p = x[m], q = x[m + hl]; x[m] = make_float2(p.x + q.x, p.y + q.y); x[m + hl] = cmul(make_float2(p.x - q.x, p.y - q.y), tw); }
;       else { const float2 p = x[m], q = cmul(x[m + hl], tw); x[m] = make_float2(p.x + q.x, p.y + q.y); x[m + hl] = make_float2(p.x - q.x, p.y - q.y); }
;     }
;   }
; }
; template <int LR, bool INV>
; __device__ __forceinline__ void fft_pass(float2* X, const int N, const int sl, const int tid) {
;   constexpr int R = 1 << LR;
;   const int s = 1 << sl;
;   for (int g = tid; g < (N >> LR); g += NTHR) {
;     const int r = g & (s - 1);
;     const int i0 = ((g >> sl) << (sl + LR)) + r;
;     float2 x[R];
; #pragma unroll
;     for (int m = 0; m < R; ++m) x[m] = X[PIDX(i0 + (m << sl))];
;     fft_stages<LR, INV>(x, r, s);
; #pragma unroll
;     for (int m = 0; m < R; ++m) X[PIDX(i0 + (m << sl))] = x[m];
;   }
;   __syncthreads();
.LBB0_666:
	v_ashrrev_i32_e32 v0, 4, v28
	v_lshl_add_u32 v5, v0, 3, v4
	ds_read2_b64 v[6:9], v5 offset1:1
	ds_read2_b64 v[10:13], v5 offset0:2 offset1:3
	ds_read2_b64 v[14:17], v5 offset0:4 offset1:5
	ds_read2_b64 v[18:21], v5 offset0:6 offset1:7
	s_mov_b32 s74, s71
	s_mov_b32 s20, s75
	s_mov_b32 s21, s71
	s_waitcnt lgkmcnt(1)
	v_add_f32_e32 v0, v6, v14
	v_add_f32_e32 v1, v7, v15
	v_add_f32_e32 v2, v8, v16
	v_add_f32_e32 v3, v9, v17
	s_waitcnt lgkmcnt(0)
	v_add_f32_e32 v24, v10, v18
	v_add_f32_e32 v25, v11, v19
	v_add_f32_e32 v26, v12, v20
	v_add_f32_e32 v27, v13, v21
	v_add_f32_e32 v30, v0, v24
	v_add_f32_e32 v31, v1, v25
	v_add_f32_e32 v32, v2, v26
	v_add_f32_e32 v33, v3, v27
	v_sub_f32_e32 v0, v0, v24
	v_sub_f32_e32 v1, v1, v25
	v_add_f32_e32 v34, v30, v32
	v_add_f32_e32 v35, v31, v33
	v_sub_f32_e32 v30, v30, v32
	v_sub_f32_e32 v31, v31, v33
	v_mul_f32_e32 v24, 0, v0
	v_mul_f32_e32 v25, 0, v1
	v_mul_f32_e32 v32, 0, v30
	v_mul_f32_e32 v33, 0, v31
	v_sub_f32_e32 v22, v8, v16
	v_add_f32_e32 v36, v30, v33
	v_sub_f32_e32 v31, v31, v32
	v_mul_f32_e32 v22, 0x3f3504f3, v22
	v_mov_b32_e32 v37, v31
	v_add_f32_e32 v30, v0, v25
	v_sub_f32_e32 v1, v1, v24
	v_add_u32_e32 v60, 0x200, v60
	v_mov_b32_e32 v31, v1
	v_sub_f32_e32 v0, v2, v26
	v_sub_f32_e32 v1, v3, v27
	v_cmp_le_i32_e32 vcc, s19, v60
	v_fma_f32 v2, v0, 0, v1
	v_fma_f32 v1, v1, 0, -v0
	v_add_u32_e32 v4, 0x8000, v4
	v_mov_b32_e32 v3, v1
	v_add_f32_e32 v0, v30, v2
	v_add_f32_e32 v1, v31, v3
	v_sub_f32_e32 v2, v30, v2
	v_sub_f32_e32 v3, v31, v3
	v_add_u32_e32 v28, 0x1000, v28
	v_mul_f32_e32 v24, 0, v2
	v_mul_f32_e32 v25, 0, v3
	s_or_b64 s[14:15], vcc, s[14:15]
	v_add_f32_e32 v26, v2, v25
	v_sub_f32_e32 v3, v3, v24
	ds_write2_b64 v5, v[34:35], v[36:37] offset1:1
	v_mov_b32_e32 v27, v3
	ds_write2_b64 v5, v[0:1], v[26:27] offset0:2 offset1:3
	v_pk_mov_b32 v[0:1], v[8:9], v[6:7] op_sel:[1,0]
	v_pk_mov_b32 v[2:3], v[16:17], v[14:15] op_sel:[1,0]
	v_mov_b32_e32 v8, v10
	v_mov_b32_e32 v16, v18
	v_sub_f32_e32 v0, v0, v2
	v_sub_f32_e32 v1, v1, v3
	v_sub_f32_e32 v2, v8, v16
	v_sub_f32_e32 v3, v9, v17
	v_mov_b32_e32 v6, v7
	v_mov_b32_e32 v7, v13
	v_mov_b32_e32 v8, v15
	v_mov_b32_e32 v9, v21
	v_sub_f32_e32 v6, v6, v8
	v_sub_f32_e32 v7, v7, v9
	v_mov_b32_e32 v13, v11
	v_mov_b32_e32 v21, v19
	v_mov_b32_e32 v23, v6
	v_sub_f32_e32 v10, v12, v20
	v_sub_f32_e32 v11, v13, v21
	v_fma_f32 v8, v0, s74, v22
	v_pk_mov_b32 v[12:13], v[10:11], v[22:23] op_sel:[1,0]
	v_fma_f32 v15, -v1, s75, v23
	v_fma_f32 v16, v2, s20, v12
	v_fma_f32 v13, v3, s21, -v13
	s_mov_b32 s74, s70
	s_mov_b32 s21, s70
	v_mul_f32_e32 v18, s74, v10
	v_mul_f32_e32 v19, s75, v11
	v_mul_f32_e32 v20, s20, v6
	v_mul_f32_e32 v21, s21, v7
	v_pk_mov_b32 v[0:1], v[0:1], v[18:19] op_sel:[1,0]
	v_pk_mov_b32 v[2:3], v[20:21], v[2:3] op_sel:[1,0]
	v_mov_b32_e32 v9, v15
	v_mov_b32_e32 v17, v13
	v_fma_f32 v2, v10, s74, -v2
	v_fma_f32 v3, v11, s75, -v3
	v_fma_f32 v0, v6, s20, v0
	v_fma_f32 v1, v7, s21, v1
	v_add_f32_e32 v6, v8, v2
	v_add_f32_e32 v7, v9, v3
	v_add_f32_e32 v10, v0, v16
	v_add_f32_e32 v11, v1, v17
	v_mov_b32_e32 v21, v7
	v_add_f32_e32 v18, v6, v10
	v_add_f32_e32 v19, v7, v11
	v_mov_b32_e32 v20, v10
	v_mov_b32_e32 v7, v11
	v_sub_f32_e32 v6, v20, v6
	v_sub_f32_e32 v7, v21, v7
	v_mov_b32_e32 v14, v0
	v_mul_f32_e32 v10, 0, v6
	v_mul_f32_e32 v11, 0, v7
	v_mov_b32_e32 v17, v3
	v_add_f32_e32 v20, v6, v11
	v_sub_f32_e32 v7, v7, v10
	v_mov_b32_e32 v9, v13
	v_mov_b32_e32 v21, v7
	v_sub_f32_e32 v6, v14, v16
	v_sub_f32_e32 v7, v15, v17
	v_mov_b32_e32 v3, v1
	v_mul_f32_e32 v10, 0, v6
	v_mul_f32_e32 v11, 0, v7
	v_sub_f32_e32 v0, v8, v2
	v_sub_f32_e32 v1, v9, v3
	v_add_f32_e32 v14, v6, v11
	v_sub_f32_e32 v7, v7, v10
	v_fma_f32 v2, v0, 0, v1
	v_fma_f32 v1, v1, 0, -v0
	v_mov_b32_e32 v15, v7
	v_mov_b32_e32 v3, v1
	v_add_f32_e32 v0, v14, v2
	v_add_f32_e32 v1, v15, v3
	v_sub_f32_e32 v2, v14, v2
	v_sub_f32_e32 v3, v15, v3
	ds_write2_b64 v5, v[18:19], v[20:21] offset0:4 offset1:5
	v_mul_f32_e32 v6, 0, v2
	v_mul_f32_e32 v7, 0, v3
	v_add_f32_e32 v8, v2, v7
	v_sub_f32_e32 v3, v3, v6
	v_mov_b32_e32 v9, v3
	ds_write2_b64 v5, v[0:1], v[8:9] offset0:6 offset1:7
	s_andn2_b64 exec, exec, s[14:15]
	s_cbranch_execnz .LBB0_666

;     static __device__ __forceinline__ float sl(float g, float up) { return g * __builtin_amdgcn_rcpf(1.0f + __builtin_amdgcn_exp2f(-1.4426950408889634f * g)) * up; }
; #define tid ltid()
; template <int LR, bool INV>
; __device__ __forceinline__ void fft_stages(float2 (&x)[1 << LR], const int r, const int s) {
;   constexpr int R = 1 << LR;
; #pragma unroll
;   for (int st = 0; st < LR; ++st) {
;     const int hl = INV ? (1 << st) : (R >> (st + 1));
;     const float fb = (float)r * (0.5f / (float)(hl * s));
;     const float2 wb = make_float2(__builtin_amdgcn_cosf(fb), INV ? __builtin_amdgcn_sinf(fb) : -__builtin_amdgcn_sinf(fb));
; #pragma unroll
;     for (int m = 0; m < R; ++m) {
;       if (m & hl) continue;
;       const int k = m & (hl - 1); const int j = k * (8 / hl);
;       const float2 wc = make_float2(c16(j), INV ? s16(j) : -s16(j));
;       const float2 tw = cmul(wb, wc);
;       if (!INV) { const float2 p = x[m], q = x[m + hl]; x[m] = make_float2(p.x + q.x, p.y + q.y); x[m + hl] = cmul(make_float2(p.x - q.x, p.y - q.y), tw); }
;       else { const float2 p = x[m], q = cmul(x[m + hl], tw); x[m] = make_float2(p.x + q.x, p.y + q.y); x[m + hl] = make_float2(p.x - q.x, p.y - q.y); }
;     }
;   }
; }
; template <int LR, bool INV>
; __device__ __forceinline__ void fft_pass(float2* X, const int N, const int sl, const int tid) {
;   constexpr int R = 1 << LR;
;   const int s = 1 << sl;
;   for (int g = tid; g < (N >> LR); g += NTHR) {
;     const int r = g & (s - 1);
;     const int i0 = ((g >> sl) << (sl + LR)) + r;
;     float2 x[R];
; #pragma unroll
;     for (int m = 0; m < R; ++m) x[m] = X[PIDX(i0 + (m << sl))];
;     fft_stages<LR, INV>(x, r, s);
; #pragma unroll
;     for (int m = 0; m < R; ++m) X[PIDX(i0 + (m << sl))] = x[m];
;   }
;   __syncthreads();
; }
; template <int LR>
; __device__ __forceinline__ void fft_first(float2* X, const bf16* __restrict__ u0, const bf16* __restrict__ u1, const int tid) {
;   constexpr int R = 1 << LR;
;   float2 x[R];
; #pragma unroll
;   for (int m = 0; m < R / 2; ++m) x[m] = make_float2(bfl(u0[tid + 512 * m]), bfl(u1[tid + 512 * m]));
; #pragma unroll
;   for (int m = R / 2; m < R; ++m) x[m] = make_float2(0.f, 0.f);
;   fft_stages<LR, false>(x, tid, 512);
; #pragma unroll
;   for (int m = 0; m < R; ++m) X[PIDX(tid + 512 * m)] = x[m];
;   __syncthreads();
; }
.LBB0_669:
	s_lshl_b32 s12, s18, 1
	s_lshl_b32 s12, s12, s20
	s_lshl_b32 s12, s12, 1
	s_add_u32 s40, s17, s12
	s_addc_u32 s41, s19, 0
	s_add_u32 s42, s40, s16
	s_addc_u32 s43, s41, 0
	s_mov_b64 s[12:13], -1
	s_and_b64 vcc, exec, s[10:11]
	s_cbranch_vccz .LBB0_671
	v_mov_b32_e32 v2, v208
	s_mov_b32 s12, s71
	v_ashrrev_i32_e32 v3, 31, v2
	v_lshlrev_b64 v[4:5], 1, v[2:3]
	v_lshl_add_u64 v[6:7], s[40:41], 0, v[4:5]
	v_lshl_add_u64 v[4:5], s[42:43], 0, v[4:5]
	global_load_ushort v9, v[4:5], off
	global_load_ushort v11, v[6:7], off
	global_load_ushort v13, v[4:5], off offset:1024
	global_load_ushort v15, v[6:7], off offset:1024
	global_load_ushort v22, v[4:5], off offset:2048
	global_load_ushort v24, v[6:7], off offset:2048
	s_nop 0
	global_load_ushort v5, v[4:5], off offset:3072
	s_nop 0
	global_load_ushort v7, v[6:7], off offset:3072
	v_cvt_f32_i32_e32 v8, v2
	v_add_u32_e32 v4, 0x400, v2
	v_add_u32_e32 v3, 0x200, v2
	v_add_u32_e32 v6, 0x600, v2
	v_ashrrev_i32_e32 v10, 4, v2
	v_lshl_add_u32 v12, v2, 3, 0
	v_add_u32_e32 v14, 0x800, v2
	v_add_u32_e32 v16, 0xa00, v2
	v_add_u32_e32 v17, 0xc00, v2
	v_add_u32_e32 v2, 0xe00, v2
	v_ashrrev_i32_e32 v4, 4, v4
	v_lshl_add_u32 v40, v10, 3, v12
	v_ashrrev_i32_e32 v3, 4, v3
	v_ashrrev_i32_e32 v6, 4, v6
	v_ashrrev_i32_e32 v10, 4, v14
	v_ashrrev_i32_e32 v14, 4, v16
	v_ashrrev_i32_e32 v16, 4, v17
	v_ashrrev_i32_e32 v2, 4, v2
	v_lshl_add_u32 v42, v4, 3, v12
	v_mul_f32_e32 v4, 0x3a000000, v8
	v_lshl_add_u32 v41, v3, 3, v12
	v_lshl_add_u32 v43, v6, 3, v12
	v_lshl_add_u32 v44, v10, 3, v12
	v_lshl_add_u32 v45, v14, 3, v12
	v_lshl_add_u32 v46, v16, 3, v12
	v_lshl_add_u32 v47, v2, 3, v12
	v_cos_f32_e32 v10, v4
	v_sin_f32_e32 v12, v4
	v_mul_f32_e32 v6, 0x3a800000, v8
	v_cos_f32_e32 v14, v6
	v_sin_f32_e32 v16, v6
	v_mul_f32_e32 v2, 0x39800000, v8
	v_fmamk_f32 v4, v12, 0x80000000, v10
	v_fma_f32 v6, v10, s91, -v12
	v_fma_f32 v8, v10, 0, -v12
	v_fma_f32 v10, v12, s91, -v10
	v_cos_f32_e32 v3, v2
	v_sin_f32_e32 v2, v2
	v_fmamk_f32 v12, v16, 0x80000000, v14
	v_fma_f32 v14, v14, s91, -v16
	s_mov_b32 s13, s70
	v_xor_b32_e32 v48, 0x80000000, v2
	v_pk_mov_b32 v[16:17], v[2:3], v[2:3] op_sel:[1,0]
	s_mov_b32 s90, s75
	v_mov_b32_e32 v17, v48
	v_fma_f32 v16, -v2, 0, v16
	v_fma_f32 v17, -v3, 0, v17
	s_waitcnt vmcnt(7)
	v_lshlrev_b32_e32 v19, 16, v9
	s_waitcnt vmcnt(6)
	v_lshlrev_b32_e32 v18, 16, v11
	s_waitcnt vmcnt(5)
	v_lshlrev_b32_e32 v21, 16, v13
	s_waitcnt vmcnt(4)
	v_lshlrev_b32_e32 v20, 16, v15
	s_waitcnt vmcnt(3)
	v_lshlrev_b32_e32 v23, 16, v22
	s_waitcnt vmcnt(2)
	v_lshlrev_b32_e32 v22, 16, v24
	s_waitcnt vmcnt(1)
	v_lshlrev_b32_e32 v25, 16, v5
	s_waitcnt vmcnt(0)
	v_lshlrev_b32_e32 v24, 16, v7
	v_add_f32_e32 v26, 0, v18
	v_add_f32_e32 v27, 0, v19
	v_add_f32_e32 v28, 0, v20
	v_add_f32_e32 v29, 0, v21
	v_add_f32_e32 v30, 0, v22
	v_add_f32_e32 v31, 0, v23
	v_add_f32_e32 v32, 0, v24
	v_add_f32_e32 v33, 0, v25
	v_sub_f32_e32 v34, v26, v30
	v_sub_f32_e32 v35, v27, v31
	v_sub_f32_e32 v36, v28, v32
	v_sub_f32_e32 v37, v29, v33
	v_add_f32_e32 v26, v26, v30
	v_add_f32_e32 v27, v27, v31
	v_add_f32_e32 v28, v28, v32
	v_add_f32_e32 v29, v29, v33
	v_mul_f32_e32 v30, v6, v34
	v_mul_f32_e32 v31, v6, v35
	v_mul_f32_e32 v32, v10, v36
	v_mul_f32_e32 v33, v10, v37
	v_sub_f32_e32 v38, v26, v28
	v_sub_f32_e32 v39, v27, v29
	v_add_f32_e32 v26, v26, v28
	v_add_f32_e32 v27, v27, v29
	v_fma_f32 v28, v4, v34, -v31
	v_fma_f32 v31, v4, v35, v30
	v_fma_f32 v34, v8, v36, -v33
	v_fma_f32 v33, v8, v37, v32
	v_mul_f32_e32 v36, v14, v38
	v_mul_f32_e32 v37, v14, v39
	v_mov_b32_e32 v29, v31
	v_mov_b32_e32 v35, v33
	ds_write_b64 v40, v[26:27]
	v_fma_f32 v26, v12, v38, -v37
	v_fma_f32 v31, v12, v39, v36
	v_sub_f32_e32 v32, v28, v34
	v_sub_f32_e32 v33, v29, v35
	v_mov_b32_e32 v27, v31
	v_add_f32_e32 v28, v28, v34
	v_add_f32_e32 v29, v29, v35
	v_mul_f32_e32 v30, v14, v32
	v_mul_f32_e32 v31, v14, v33
	ds_write_b64 v41, v[26:27] offset:4096
	ds_write_b64 v42, v[28:29] offset:8192
	v_fma_f32 v26, v12, v32, -v31
	v_fma_f32 v29, v12, v33, v30
	v_mov_b32_e32 v27, v29
	ds_write_b64 v43, v[26:27] offset:12288
	v_mov_b32_e32 v26, v19
	v_mul_f32_e32 v27, v16, v26
	v_mul_f32_e32 v26, v17, v26
	v_fma_f32 v28, v16, v18, -v26
	v_fma_f32 v17, v17, v18, v27
	v_mov_b32_e32 v26, v21
	v_mov_b32_e32 v29, v17
	v_mul_f32_e32 v16, s70, v2
	v_mul_f32_e32 v17, s70, v3
	v_fma_f32 v18, v3, s12, v16
	v_fma_f32 v19, v2, s13, v17
	v_mul_f32_e32 v27, v18, v26
	v_mul_f32_e32 v26, v19, v26
	v_fma_f32 v30, v18, v20, -v26
	v_fma_f32 v19, v19, v20, v27
	v_mov_b32_e32 v20, v23
	v_mov_b32_e32 v31, v19
	v_fma_f32 v18, v3, s90, -v2
	v_fma_f32 v19, v2, s91, -v3
	v_mul_f32_e32 v21, v18, v20
	v_mul_f32_e32 v20, v19, v20
	v_pk_fma_f32 v[2:3], v[2:3], s[70:71], v[16:17] op_sel:[1,0,0] op_sel_hi:[0,1,1]
	v_mov_b32_e32 v16, v25
	v_fma_f32 v26, v18, v22, -v20
	v_fma_f32 v19, v19, v22, v21
	v_mul_f32_e32 v17, v2, v16
	v_mul_f32_e32 v16, v3, v16
	v_mov_b32_e32 v27, v19
	v_fma_f32 v18, v2, v24, -v16
	v_fma_f32 v3, v3, v24, v17
	s_mov_b64 s[12:13], 0
	v_mov_b32_e32 v19, v3
	v_sub_f32_e32 v2, v28, v26
	v_sub_f32_e32 v3, v29, v27
	v_mul_f32_e32 v7, v6, v3
	v_mul_f32_e32 v6, v6, v2
	v_fma_f32 v16, v4, v2, -v7
	v_fma_f32 v3, v4, v3, v6
	v_mov_b32_e32 v17, v3
	v_sub_f32_e32 v2, v30, v18
	v_sub_f32_e32 v3, v31, v19
	v_mul_f32_e32 v4, v10, v2
	v_mul_f32_e32 v5, v10, v3
	v_fma_f32 v6, v8, v2, -v5
	v_fma_f32 v3, v8, v3, v4
	v_mov_b32_e32 v7, v3
	v_sub_f32_e32 v2, v16, v6
	v_sub_f32_e32 v3, v17, v7
	v_mul_f32_e32 v4, v14, v2
	v_mul_f32_e32 v5, v14, v3
	v_fma_f32 v8, v12, v2, -v5
	v_fma_f32 v3, v12, v3, v4
	v_mov_b32_e32 v9, v3
	v_add_f32_e32 v2, v28, v26
	v_add_f32_e32 v3, v29, v27
	v_add_f32_e32 v4, v30, v18
	v_add_f32_e32 v5, v31, v19
	v_sub_f32_e32 v10, v2, v4
	v_sub_f32_e32 v11, v3, v5
	v_add_f32_e32 v2, v2, v4
	v_add_f32_e32 v3, v3, v5
	v_mul_f32_e32 v15, v14, v11
	v_mul_f32_e32 v14, v14, v10
	v_fma_f32 v18, v12, v10, -v15
	v_fma_f32 v11, v12, v11, v14
	v_mov_b32_e32 v19, v11
	ds_write_b64 v44, v[2:3] offset:16384
	ds_write_b64 v45, v[18:19] offset:20480
	v_add_f32_e32 v2, v16, v6
	v_add_f32_e32 v3, v17, v7
	ds_write_b64 v46, v[2:3] offset:24576
	ds_write_b64 v47, v[8:9] offset:28672
	s_waitcnt lgkmcnt(0)
	s_barrier
; __device__ __forceinline__ float bfl(unsigned w) { return __uint_as_float(w << 16); }
; __device__ __forceinline__ float2 cmul(float2 a, float2 b) { return make_float2(a.x * b.x - a.y * b.y, a.x * b.y + a.y * b.x); }
; #define tid ltid()
; template <int LR, bool INV>
; __device__ __forceinline__ void fft_stages(float2 (&x)[1 << LR], const int r, const int s) {
;   constexpr int R = 1 << LR;
; #pragma unroll
;   for (int st = 0; st < LR; ++st) {
;     const int hl = INV ? (1 << st) : (R >> (st + 1));
;     const float fb = (float)r * (0.5f / (float)(hl * s));
;     const float2 wb = make_float2(__builtin_amdgcn_cosf(fb), INV ? __builtin_amdgcn_sinf(fb) : -__builtin_amdgcn_sinf(fb));
; #pragma unroll
;     for (int m = 0; m < R; ++m) {
;       if (m & hl) continue;
;       const int k = m & (hl - 1); const int j = k * (8 / hl);
;       const float2 wc = make_float2(c16(j), INV ? s16(j) : -s16(j));
;       const float2 tw = cmul(wb, wc);
;       if (!INV) { const float2 p = x[m], q = x[m + hl]; x[m] = make_float2(p.x + q.x, p.y + q.y); x[m + hl] = cmul(make_float2(p.x - q.x, p.y - q.y), tw); }
;       else { const float2 p = x[m], q = cmul(x[m + hl], tw); x[m] = make_float2(p.x + q.x, p.y + q.y); x[m + hl] = make_float2(p.x - q.x, p.y - q.y); }
;     }
;   }
; template <int LR>
; __device__ __forceinline__ void fft_first(float2* X, const bf16* __restrict__ u0, const bf16* __restrict__ u1, const int tid) {
;   constexpr int R = 1 << LR;
;   float2 x[R];
; #pragma unroll
;   for (int m = 0; m < R / 2; ++m) x[m] = make_float2(bfl(u0[tid + 512 * m]), bfl(u1[tid + 512 * m]));
; #pragma unroll
;   for (int m = R / 2; m < R; ++m) x[m] = make_float2(0.f, 0.f);
;   fft_stages<LR, false>(x, tid, 512);
; #pragma unroll
;   for (int m = 0; m < R; ++m) X[PIDX(tid + 512 * m)] = x[m];
;   __syncthreads();
; }
.LBB0_671:
	s_andn2_b64 vcc, exec, s[12:13]
	s_cbranch_vccnz .LBB0_673
	v_mov_b32_e32 v2, v208
	s_mov_b32 s14, s71
	v_ashrrev_i32_e32 v3, 31, v2
	v_lshlrev_b64 v[4:5], 1, v[2:3]
	v_lshl_add_u64 v[6:7], s[40:41], 0, v[4:5]
	v_lshl_add_u64 v[4:5], s[42:43], 0, v[4:5]
	global_load_ushort v3, v[6:7], off
	global_load_ushort v20, v[4:5], off
	global_load_ushort v21, v[6:7], off offset:1024
	global_load_ushort v26, v[4:5], off offset:1024
	global_load_ushort v27, v[6:7], off offset:2048
	global_load_ushort v28, v[4:5], off offset:2048
	global_load_ushort v33, v[4:5], off offset:3072
	global_load_ushort v44, v[6:7], off offset:3072
	v_add_co_u32_e32 v6, vcc, s64, v6
	v_cvt_f32_i32_e32 v64, v2
	s_nop 0
	v_addc_co_u32_e32 v7, vcc, 0, v7, vcc
	v_add_co_u32_e32 v4, vcc, s64, v4
	s_mov_b32 s15, s70
	s_nop 0
	v_addc_co_u32_e32 v5, vcc, 0, v5, vcc
	global_load_ushort v45, v[6:7], off
	global_load_ushort v46, v[4:5], off
	global_load_ushort v47, v[6:7], off offset:1024
	global_load_ushort v48, v[4:5], off offset:1024
	global_load_ushort v49, v[6:7], off offset:2048
	global_load_ushort v50, v[4:5], off offset:2048
	global_load_ushort v51, v[4:5], off offset:3072
	global_load_ushort v52, v[6:7], off offset:3072
	v_mul_f32_e32 v4, 0x39000000, v64
	v_sin_f32_e32 v9, v4
	v_cos_f32_e32 v8, v4
	v_mul_f32_e32 v53, 0x39800000, v64
	s_mov_b32 s90, s75
	v_xor_b32_e32 v5, 0x80000000, v9
	v_mul_f32_e32 v10, 0, v9
	v_mov_b32_e32 v4, v8
	v_mul_f32_e32 v11, 0, v8
	v_mov_b32_e32 v36, v9
	v_mov_b32_e32 v37, v8
	s_mov_b32 s12, s71
	v_cos_f32_e32 v29, v53
	v_mul_f32_e32 v13, 0xbf3504f3, v9
	v_mul_f32_e32 v12, 0x3f3504f3, v8
	v_sub_f32_e32 v22, v4, v10
	v_sub_f32_e32 v23, v5, v11
	v_mul_f32_e32 v4, s14, v36
	v_mul_f32_e32 v5, s15, v37
	v_mul_f32_e32 v10, s94, v36
	v_mul_f32_e32 v11, s94, v37
	v_mul_f32_e32 v38, s72, v36
	v_mul_f32_e32 v39, s73, v37
	v_fma_f32 v6, v8, s90, -v9
	v_fma_f32 v7, v9, s91, -v8
	v_mul_f32_e32 v32, 0xbec3ef15, v8
	v_mul_f32_e32 v18, s72, v8
	v_fma_f32 v14, -v36, s12, v12
	v_fma_f32 v15, -v37, s12, v13
	v_pk_fma_f32 v[4:5], v[36:37], s[12:13], v[4:5] op_sel:[0,0,1] op_sel_hi:[1,0,0] neg_lo:[1,0,0] neg_hi:[1,0,0]
	v_fma_f32 v24, v8, s72, -v10
	v_fma_f32 v25, v9, s73, -v11
	v_pk_mov_b32 v[42:43], v[10:11], v[10:11] op_sel:[1,0]
	v_mov_b32_e32 v41, v18
	v_mov_b32_e32 v40, v38
	v_add_u32_e32 v60, 0x200, v2
	v_add_u32_e32 v61, 0x400, v2
	v_mul_f32_e32 v17, 0xbec3ef15, v9
	v_mov_b32_e32 v16, v42
	v_sub_f32_e32 v16, v16, v40
	v_sub_f32_e32 v17, v17, v41
	v_add_u32_e32 v62, 0x600, v2
	v_add_u32_e32 v63, 0x800, v2
	v_add_u32_e32 v65, 0xa00, v2
	v_add_u32_e32 v67, 0xe00, v2
	v_add_u32_e32 v66, 0xc00, v2
	s_waitcnt vmcnt(15)
	v_lshlrev_b32_e32 v34, 16, v3
	v_mul_f32_e32 v3, 0x3a000000, v64
	s_waitcnt vmcnt(13)
	v_lshlrev_b32_e32 v30, 16, v21
	s_waitcnt vmcnt(12)
	v_lshlrev_b32_e32 v31, 16, v26
	s_waitcnt vmcnt(11)
	v_lshlrev_b32_e32 v26, 16, v27
	s_waitcnt vmcnt(10)
	v_lshlrev_b32_e32 v27, 16, v28
	v_sin_f32_e32 v28, v53
	s_waitcnt vmcnt(9)
	v_lshlrev_b32_e32 v21, 16, v33
	v_mov_b32_e32 v33, v43
	v_lshlrev_b32_e32 v35, 16, v20
	v_sub_f32_e32 v54, v32, v40
	v_sub_f32_e32 v55, v33, v41
	s_waitcnt vmcnt(7)
	v_lshlrev_b32_e32 v18, 16, v45
	s_waitcnt vmcnt(6)
	v_lshlrev_b32_e32 v19, 16, v46
	v_mov_b32_e32 v32, v29
	v_mov_b32_e32 v33, v28
	v_mul_f32_e32 v58, s70, v32
	v_mul_f32_e32 v59, s71, v33
	v_ashrrev_i32_e32 v33, 4, v60
	v_add_f32_e32 v68, 0, v18
	v_add_f32_e32 v69, 0, v19
	s_waitcnt vmcnt(0)
	v_lshlrev_b32_e32 v8, 16, v52
	v_fma_f32 v52, -v36, s94, v39
	v_fma_f32 v53, -v37, s94, v38
	v_cos_f32_e32 v37, v3
	v_sin_f32_e32 v3, v3
	v_lshlrev_b32_e32 v20, 16, v44
	v_lshlrev_b32_e32 v13, 16, v48
	v_lshlrev_b32_e32 v11, 16, v50
	v_fmamk_f32 v36, v3, 0x80000000, v37
	v_fma_f32 v42, v37, s91, -v3
	v_fma_f32 v38, v37, 0, -v3
	v_fma_f32 v40, v3, s91, -v37
	v_ashrrev_i32_e32 v37, 4, v61
	v_add_f32_e32 v60, 0, v34
	v_add_f32_e32 v61, 0, v35
	v_fmamk_f32 v48, v28, 0x80000000, v29
	v_fma_f32 v50, v29, s91, -v28
	v_mul_f32_e32 v56, s70, v28
	v_mul_f32_e32 v57, s71, v29
	v_fma_f32 v44, v29, 0, -v28
	v_fma_f32 v46, v28, s91, -v29
	v_mul_f32_e32 v28, 0x3a800000, v64
	v_sub_f32_e32 v76, v60, v68
	v_sub_f32_e32 v77, v61, v69
	v_lshlrev_b32_e32 v12, 16, v47
	v_cos_f32_e32 v29, v28
	v_sin_f32_e32 v32, v28
	v_mul_f32_e32 v78, v50, v76
	v_mul_f32_e32 v79, v50, v77
	v_ashrrev_i32_e32 v39, 4, v62
	v_ashrrev_i32_e32 v41, 4, v63
	v_add_f32_e32 v62, 0, v30
	v_add_f32_e32 v63, 0, v31
	v_add_f32_e32 v70, 0, v12
	v_add_f32_e32 v71, 0, v13
	v_fma_f32 v80, v48, v76, -v79
	v_fma_f32 v77, v48, v77, v78
	v_mov_b32_e32 v81, v77
	v_sub_f32_e32 v76, v62, v70
	v_sub_f32_e32 v77, v63, v71
	v_sub_f32_e32 v78, v56, v57
	v_sub_f32_e32 v79, v56, v57
	v_lshlrev_b32_e32 v10, 16, v49
	v_mul_f32_e32 v82, v78, v76
	v_mul_f32_e32 v83, v79, v77
	v_sub_f32_e32 v56, v57, v59
	v_fmamk_f32 v28, v32, 0x80000000, v29
	v_fma_f32 v32, v29, s91, -v32
	v_lshl_add_u32 v29, v2, 3, 0
	v_ashrrev_i32_e32 v43, 4, v65
	v_ashrrev_i32_e32 v47, 4, v67
	v_add_f32_e32 v64, 0, v26
	v_add_f32_e32 v65, 0, v27
	v_add_f32_e32 v72, 0, v10
	v_add_f32_e32 v73, 0, v11
	v_fma_f32 v84, v56, v76, -v83
	v_fma_f32 v77, v56, v77, v82
	v_ashrrev_i32_e32 v45, 4, v66
	v_lshl_add_u32 v47, v47, 3, v29
	v_mov_b32_e32 v85, v77
	v_sub_f32_e32 v76, v64, v72
	v_sub_f32_e32 v77, v65, v73
	v_lshlrev_b32_e32 v9, 16, v51
	v_lshl_add_u32 v45, v45, 3, v29
	v_mul_f32_e32 v82, v46, v76
	v_mul_f32_e32 v83, v46, v77
	v_add_f32_e32 v66, 0, v20
	v_add_f32_e32 v67, 0, v21
	v_add_f32_e32 v74, 0, v8
	v_add_f32_e32 v75, 0, v9
	v_fma_f32 v86, v44, v76, -v83
	v_fma_f32 v77, v44, v77, v82
	v_mov_b32_e32 v87, v77
	v_sub_f32_e32 v76, v66, v74
	v_sub_f32_e32 v77, v67, v75
; __device__ __forceinline__ float bfl(unsigned w) { return __uint_as_float(w << 16); }
; __device__ __forceinline__ float2 cmul(float2 a, float2 b) { return make_float2(a.x * b.x - a.y * b.y, a.x * b.y + a.y * b.x); }
; #define tid ltid()
; template <int LR, bool INV>
; __device__ __forceinline__ void fft_stages(float2 (&x)[1 << LR], const int r, const int s) {
;   constexpr int R = 1 << LR;
; #pragma unroll
;   for (int st = 0; st < LR; ++st) {
;     const int hl = INV ? (1 << st) : (R >> (st + 1));
;     const float fb = (float)r * (0.5f / (float)(hl * s));
;     const float2 wb = make_float2(__builtin_amdgcn_cosf(fb), INV ? __builtin_amdgcn_sinf(fb) : -__builtin_amdgcn_sinf(fb));
; #pragma unroll
;     for (int m = 0; m < R; ++m) {
;       if (m & hl) continue;
;       const int k = m & (hl - 1); const int j = k * (8 / hl);
;       const float2 wc = make_float2(c16(j), INV ? s16(j) : -s16(j));
;       const float2 tw = cmul(wb, wc);
;       if (!INV) { const float2 p = x[m], q = x[m + hl]; x[m] = make_float2(p.x + q.x, p.y + q.y); x[m + hl] = cmul(make_float2(p.x - q.x, p.y - q.y), tw); }
;       else { const float2 p = x[m], q = cmul(x[m + hl], tw); x[m] = make_float2(p.x + q.x, p.y + q.y); x[m + hl] = make_float2(p.x - q.x, p.y - q.y); }
;     }
;   }
; template <int LR>
; __device__ __forceinline__ void fft_first(float2* X, const bf16* __restrict__ u0, const bf16* __restrict__ u1, const int tid) {
;   constexpr int R = 1 << LR;
;   float2 x[R];
; #pragma unroll
;   for (int m = 0; m < R / 2; ++m) x[m] = make_float2(bfl(u0[tid + 512 * m]), bfl(u1[tid + 512 * m]));
; #pragma unroll
;   for (int m = R / 2; m < R; ++m) x[m] = make_float2(0.f, 0.f);
;   fft_stages<LR, false>(x, tid, 512);
; #pragma unroll
;   for (int m = 0; m < R; ++m) X[PIDX(tid + 512 * m)] = x[m];
;   __syncthreads();
; }
	v_sub_f32_e32 v82, v59, v57
	v_mul_f32_e32 v88, v82, v76
	v_mul_f32_e32 v89, v82, v77
	v_pk_add_f32 v[58:59], v[58:59], v[58:59] op_sel:[0,1] op_sel_hi:[0,1] neg_lo:[0,1] neg_hi:[0,1]
	v_fma_f32 v90, v58, v76, -v89
	v_fma_f32 v77, v59, v77, v88
	v_lshl_add_u32 v43, v43, 3, v29
	v_mov_b32_e32 v91, v77
	v_sub_f32_e32 v76, v80, v86
	v_sub_f32_e32 v77, v81, v87
	v_add_f32_e32 v60, v60, v68
	v_add_f32_e32 v61, v61, v69
	v_add_f32_e32 v64, v64, v72
	v_add_f32_e32 v65, v65, v73
	v_lshl_add_u32 v37, v37, 3, v29
	v_mul_f32_e32 v88, v42, v76
	v_mul_f32_e32 v89, v42, v77
	v_sub_f32_e32 v68, v60, v64
	v_sub_f32_e32 v69, v61, v65
	v_fma_f32 v92, v36, v76, -v89
	v_fma_f32 v77, v36, v77, v88
	v_add_f32_e32 v62, v62, v70
	v_add_f32_e32 v63, v63, v71
	v_mul_f32_e32 v70, v42, v68
	v_mul_f32_e32 v71, v42, v69
	v_lshl_add_u32 v41, v41, 3, v29
	v_mov_b32_e32 v93, v77
	v_sub_f32_e32 v76, v84, v90
	v_sub_f32_e32 v77, v85, v91
	v_add_f32_e32 v66, v66, v74
	v_add_f32_e32 v67, v67, v75
	v_fma_f32 v72, v36, v68, -v71
	v_fma_f32 v69, v36, v69, v70
	v_lshl_add_u32 v39, v39, 3, v29
	v_mul_f32_e32 v88, v40, v76
	v_mul_f32_e32 v89, v40, v77
	v_mov_b32_e32 v73, v69
	v_sub_f32_e32 v68, v62, v66
	v_sub_f32_e32 v69, v63, v67
	v_fma_f32 v94, v38, v76, -v89
	v_fma_f32 v77, v38, v77, v88
	v_mul_f32_e32 v70, v40, v68
	v_mul_f32_e32 v71, v40, v69
	v_mov_b32_e32 v95, v77
	v_fma_f32 v74, v38, v68, -v71
	v_fma_f32 v69, v38, v69, v70
	v_lshl_add_u32 v33, v33, 3, v29
	v_sub_f32_e32 v76, v92, v94
	v_sub_f32_e32 v77, v93, v95
	v_mov_b32_e32 v75, v69
	v_mul_f32_e32 v88, v32, v76
	v_mul_f32_e32 v89, v32, v77
	v_sub_f32_e32 v68, v72, v74
	v_sub_f32_e32 v69, v73, v75
	v_add_f32_e32 v60, v60, v64
	v_add_f32_e32 v61, v61, v65
	v_add_f32_e32 v62, v62, v66
	v_add_f32_e32 v63, v63, v67
	v_fma_f32 v96, v28, v76, -v89
	v_fma_f32 v77, v28, v77, v88
	v_mul_f32_e32 v70, v32, v68
	v_mul_f32_e32 v71, v32, v69
	v_sub_f32_e32 v64, v60, v62
	v_sub_f32_e32 v65, v61, v63
	v_ashrrev_i32_e32 v3, 4, v2
	v_mov_b32_e32 v97, v77
	v_fma_f32 v76, v28, v68, -v71
	v_fma_f32 v69, v28, v69, v70
	v_mul_f32_e32 v66, v32, v64
	v_mul_f32_e32 v67, v32, v65
	v_lshl_add_u32 v3, v3, 3, v29
	v_mov_b32_e32 v77, v69
	v_fma_f32 v68, v28, v64, -v67
	v_fma_f32 v65, v28, v65, v66
	v_add_f32_e32 v60, v60, v62
	v_add_f32_e32 v61, v61, v63
	v_mov_b32_e32 v69, v65
	ds_write_b64 v3, v[60:61]
	ds_write_b64 v33, v[68:69] offset:4096
	v_add_f32_e32 v60, v72, v74
	v_add_f32_e32 v61, v73, v75
	ds_write_b64 v37, v[60:61] offset:8192
	ds_write_b64 v39, v[76:77] offset:12288
	v_add_f32_e32 v60, v80, v86
	v_add_f32_e32 v61, v81, v87
	v_add_f32_e32 v62, v84, v90
	v_add_f32_e32 v63, v85, v91
	v_add_u32_e32 v3, 0x1000, v2
	v_sub_f32_e32 v64, v60, v62
	v_sub_f32_e32 v65, v61, v63
	v_ashrrev_i32_e32 v3, 4, v3
	v_mul_f32_e32 v66, v32, v64
	v_mul_f32_e32 v67, v32, v65
	v_lshl_add_u32 v33, v3, 3, v29
	v_add_u32_e32 v3, 0x1200, v2
	v_ashrrev_i32_e32 v3, 4, v3
	v_lshl_add_u32 v37, v3, 3, v29
	v_add_u32_e32 v3, 0x1400, v2
	v_ashrrev_i32_e32 v3, 4, v3
	v_lshl_add_u32 v39, v3, 3, v29
	v_add_u32_e32 v3, 0x1600, v2
	v_fma_f32 v68, v28, v64, -v67
	v_fma_f32 v65, v28, v65, v66
	v_add_f32_e32 v60, v60, v62
	v_add_f32_e32 v61, v61, v63
	v_ashrrev_i32_e32 v3, 4, v3
	v_mov_b32_e32 v69, v65
	ds_write_b64 v41, v[60:61] offset:16384
	ds_write_b64 v43, v[68:69] offset:20480
	v_lshl_add_u32 v41, v3, 3, v29
	v_add_u32_e32 v3, 0x1800, v2
	v_ashrrev_i32_e32 v3, 4, v3
	v_lshl_add_u32 v43, v3, 3, v29
	v_add_u32_e32 v3, 0x1a00, v2
	v_add_f32_e32 v60, v92, v94
	v_add_f32_e32 v61, v93, v95
	v_ashrrev_i32_e32 v3, 4, v3
	ds_write_b64 v45, v[60:61] offset:24576
	ds_write_b64 v47, v[96:97] offset:28672
	v_lshl_add_u32 v47, v3, 3, v29
	v_add_u32_e32 v3, 0x1c00, v2
	v_add_u32_e32 v2, 0x1e00, v2
	v_ashrrev_i32_e32 v3, 4, v3
	v_ashrrev_i32_e32 v2, 4, v2
	v_lshl_add_u32 v49, v3, 3, v29
	v_lshl_add_u32 v29, v2, 3, v29
	v_mov_b32_e32 v2, v35
	v_mul_f32_e32 v3, v22, v2
	v_mul_f32_e32 v2, v23, v2
	v_fma_f32 v60, v22, v34, -v2
	v_fma_f32 v3, v23, v34, v3
	v_mov_b32_e32 v2, v31
	v_mov_b32_e32 v61, v3
	v_mul_f32_e32 v3, v24, v2
	v_mul_f32_e32 v2, v25, v2
	v_fma_f32 v22, v24, v30, -v2
	v_fma_f32 v3, v25, v30, v3
	v_mov_b32_e32 v2, v27
	v_mov_b32_e32 v23, v3
	v_mul_f32_e32 v3, v14, v2
	v_mul_f32_e32 v2, v15, v2
	v_fma_f32 v24, v14, v26, -v2
	v_fma_f32 v3, v15, v26, v3
	v_mov_b32_e32 v2, v21
	v_mov_b32_e32 v25, v3
	v_mul_f32_e32 v3, v16, v2
	v_mul_f32_e32 v2, v17, v2
	v_fma_f32 v14, v16, v20, -v2
	v_fma_f32 v3, v17, v20, v3
	v_mov_b32_e32 v2, v19
	v_mov_b32_e32 v15, v3
	v_mul_f32_e32 v3, v6, v2
	v_mul_f32_e32 v2, v7, v2
	v_fma_f32 v16, v6, v18, -v2
	v_fma_f32 v3, v7, v18, v3
	v_mov_b32_e32 v2, v13
	v_mov_b32_e32 v17, v3
	v_mul_f32_e32 v3, v54, v2
	v_mul_f32_e32 v2, v55, v2
	v_fma_f32 v6, v54, v12, -v2
	v_fma_f32 v3, v55, v12, v3
	v_mov_b32_e32 v2, v11
	v_mov_b32_e32 v7, v3
	v_mul_f32_e32 v3, v4, v2
	v_mul_f32_e32 v2, v5, v2
	v_fma_f32 v12, v4, v10, -v2
	v_fma_f32 v3, v5, v10, v3
	v_mov_b32_e32 v2, v9
	v_mov_b32_e32 v13, v3
	v_mul_f32_e32 v3, v52, v2
	v_mul_f32_e32 v2, v53, v2
	v_fma_f32 v4, v52, v8, -v2
	v_fma_f32 v3, v53, v8, v3
	v_mov_b32_e32 v5, v3
	v_sub_f32_e32 v2, v60, v16
	v_sub_f32_e32 v3, v61, v17
	v_mul_f32_e32 v8, v50, v2
	v_mul_f32_e32 v9, v50, v3
	v_fma_f32 v10, v48, v2, -v9
	v_fma_f32 v3, v48, v3, v8
	v_mov_b32_e32 v11, v3
	v_sub_f32_e32 v2, v22, v6
	v_sub_f32_e32 v3, v23, v7
	v_add_f32_e32 v6, v22, v6
	v_add_f32_e32 v7, v23, v7
	v_mul_f32_e32 v8, v78, v2
	v_mul_f32_e32 v9, v79, v3
	v_fma_f32 v18, v56, v2, -v9
	v_fma_f32 v3, v56, v3, v8
	v_mov_b32_e32 v19, v3
	v_sub_f32_e32 v2, v24, v12
	v_sub_f32_e32 v3, v25, v13
	v_mul_f32_e32 v8, v46, v2
	v_mul_f32_e32 v9, v46, v3
;     static __device__ __forceinline__ float sl(float g, float up) { return g * __builtin_amdgcn_rcpf(1.0f + __builtin_amdgcn_exp2f(-1.4426950408889634f * g)) * up; }
; #define tid ltid()
; template <int LR, bool INV>
; __device__ __forceinline__ void fft_stages(float2 (&x)[1 << LR], const int r, const int s) {
;   constexpr int R = 1 << LR;
; #pragma unroll
;   for (int st = 0; st < LR; ++st) {
;     const int hl = INV ? (1 << st) : (R >> (st + 1));
;     const float fb = (float)r * (0.5f / (float)(hl * s));
;     const float2 wb = make_float2(__builtin_amdgcn_cosf(fb), INV ? __builtin_amdgcn_sinf(fb) : -__builtin_amdgcn_sinf(fb));
; #pragma unroll
;     for (int m = 0; m < R; ++m) {
;       if (m & hl) continue;
;       const int k = m & (hl - 1); const int j = k * (8 / hl);
;       const float2 wc = make_float2(c16(j), INV ? s16(j) : -s16(j));
;       const float2 tw = cmul(wb, wc);
;       if (!INV) { const float2 p = x[m], q = x[m + hl]; x[m] = make_float2(p.x + q.x, p.y + q.y); x[m + hl] = cmul(make_float2(p.x - q.x, p.y - q.y), tw); }
;       else { const float2 p = x[m], q = cmul(x[m + hl], tw); x[m] = make_float2(p.x + q.x, p.y + q.y); x[m + hl] = make_float2(p.x - q.x, p.y - q.y); }
;     }
;   }
; }
; template <int LR, bool INV>
; __device__ __forceinline__ void fft_pass(float2* X, const int N, const int sl, const int tid) {
;   constexpr int R = 1 << LR;
;   const int s = 1 << sl;
;   for (int g = tid; g < (N >> LR); g += NTHR) {
;     const int r = g & (s - 1);
;     const int i0 = ((g >> sl) << (sl + LR)) + r;
;     float2 x[R];
; #pragma unroll
;     for (int m = 0; m < R; ++m) x[m] = X[PIDX(i0 + (m << sl))];
;     fft_stages<LR, INV>(x, r, s);
; #pragma unroll
;     for (int m = 0; m < R; ++m) X[PIDX(i0 + (m << sl))] = x[m];
;   }
;   __syncthreads();
; }
; template <int LR>
; __device__ __forceinline__ void fft_first(float2* X, const bf16* __restrict__ u0, const bf16* __restrict__ u1, const int tid) {
;   constexpr int R = 1 << LR;
;   float2 x[R];
; #pragma unroll
;   for (int m = 0; m < R / 2; ++m) x[m] = make_float2(bfl(u0[tid + 512 * m]), bfl(u1[tid + 512 * m]));
; #pragma unroll
;   for (int m = R / 2; m < R; ++m) x[m] = make_float2(0.f, 0.f);
;   fft_stages<LR, false>(x, tid, 512);
; #pragma unroll
;   for (int m = 0; m < R; ++m) X[PIDX(tid + 512 * m)] = x[m];
;   __syncthreads();
; }
	v_fma_f32 v20, v44, v2, -v9
	v_fma_f32 v3, v44, v3, v8
	v_mov_b32_e32 v21, v3
	v_sub_f32_e32 v2, v14, v4
	v_sub_f32_e32 v3, v15, v5
	v_add_f32_e32 v4, v14, v4
	v_add_f32_e32 v5, v15, v5
	v_mul_f32_e32 v8, v82, v2
	v_mul_f32_e32 v9, v82, v3
	v_fma_f32 v26, v58, v2, -v9
	v_fma_f32 v3, v59, v3, v8
	v_mov_b32_e32 v27, v3
	v_sub_f32_e32 v2, v10, v20
	v_sub_f32_e32 v3, v11, v21
	v_mul_f32_e32 v8, v42, v2
	v_mul_f32_e32 v9, v42, v3
	v_fma_f32 v30, v36, v2, -v9
	v_fma_f32 v3, v36, v3, v8
	v_mov_b32_e32 v31, v3
	v_sub_f32_e32 v2, v18, v26
	v_sub_f32_e32 v3, v19, v27
	v_mul_f32_e32 v8, v40, v2
	v_mul_f32_e32 v9, v40, v3
	v_fma_f32 v34, v38, v2, -v9
	v_fma_f32 v3, v38, v3, v8
	v_mov_b32_e32 v35, v3
	v_sub_f32_e32 v2, v30, v34
	v_sub_f32_e32 v3, v31, v35
	v_mul_f32_e32 v8, v32, v2
	v_mul_f32_e32 v9, v32, v3
	v_fma_f32 v44, v28, v2, -v9
	v_fma_f32 v3, v28, v3, v8
	v_mov_b32_e32 v45, v3
	v_add_f32_e32 v2, v60, v16
	v_add_f32_e32 v3, v61, v17
	v_add_f32_e32 v8, v24, v12
	v_add_f32_e32 v9, v25, v13
	v_sub_f32_e32 v12, v2, v8
	v_sub_f32_e32 v13, v3, v9
	v_add_f32_e32 v2, v2, v8
	v_add_f32_e32 v3, v3, v9
	v_mul_f32_e32 v14, v42, v12
	v_mul_f32_e32 v15, v42, v13
	v_fma_f32 v16, v36, v12, -v15
	v_fma_f32 v13, v36, v13, v14
	v_mov_b32_e32 v17, v13
	v_sub_f32_e32 v12, v6, v4
	v_sub_f32_e32 v13, v7, v5
	v_add_f32_e32 v4, v6, v4
	v_add_f32_e32 v5, v7, v5
	v_mul_f32_e32 v14, v40, v12
	v_mul_f32_e32 v15, v40, v13
	v_fma_f32 v22, v38, v12, -v15
	v_fma_f32 v13, v38, v13, v14
	v_mov_b32_e32 v23, v13
	v_sub_f32_e32 v12, v16, v22
	v_sub_f32_e32 v13, v17, v23
	v_sub_f32_e32 v6, v2, v4
	v_sub_f32_e32 v7, v3, v5
	v_mul_f32_e32 v14, v32, v12
	v_mul_f32_e32 v15, v32, v13
	v_fma_f32 v24, v28, v12, -v15
	v_fma_f32 v13, v28, v13, v14
	v_mul_f32_e32 v8, v32, v6
	v_mul_f32_e32 v9, v32, v7
	v_mov_b32_e32 v25, v13
	v_fma_f32 v12, v28, v6, -v9
	v_fma_f32 v7, v28, v7, v8
	v_add_f32_e32 v2, v2, v4
	v_add_f32_e32 v3, v3, v5
	v_mov_b32_e32 v13, v7
	ds_write_b64 v33, v[2:3] offset:32768
	ds_write_b64 v37, v[12:13] offset:36864
	v_add_f32_e32 v2, v16, v22
	v_add_f32_e32 v3, v17, v23
	ds_write_b64 v39, v[2:3] offset:40960
	ds_write_b64 v41, v[24:25] offset:45056
	v_add_f32_e32 v2, v10, v20
	v_add_f32_e32 v3, v11, v21
	v_add_f32_e32 v4, v18, v26
	v_add_f32_e32 v5, v19, v27
	v_sub_f32_e32 v6, v2, v4
	v_sub_f32_e32 v7, v3, v5
	v_add_f32_e32 v2, v2, v4
	v_add_f32_e32 v3, v3, v5
	v_mul_f32_e32 v8, v32, v6
	v_mul_f32_e32 v9, v32, v7
	v_fma_f32 v10, v28, v6, -v9
	v_fma_f32 v7, v28, v7, v8
	v_mov_b32_e32 v11, v7
	ds_write_b64 v43, v[2:3] offset:49152
	ds_write_b64 v47, v[10:11] offset:53248
	v_add_f32_e32 v2, v30, v34
	v_add_f32_e32 v3, v31, v35
	ds_write_b64 v49, v[2:3] offset:57344
	ds_write_b64 v29, v[44:45] offset:61440
	s_waitcnt lgkmcnt(0)
	s_barrier
.LBB0_673:
	v_mov_b32_e32 v30, v208
	s_nop 0
	v_cmp_gt_i32_e32 vcc, s21, v30
	s_and_saveexec_b64 s[12:13], vcc
	s_cbranch_execz .LBB0_676
	v_and_b32_e32 v31, 63, v30
	v_cvt_f32_ubyte0_e32 v16, v31
	v_mul_f32_e32 v2, 0x3b000000, v16
	v_sin_f32_e32 v8, v2
	v_cos_f32_e32 v9, v2
	v_mul_f32_e32 v13, 0x3b800000, v16
	v_sin_f32_e32 v12, v13
	v_cos_f32_e32 v13, v13
	v_mul_f32_e32 v17, 0x3c000000, v16
	v_sin_f32_e32 v16, v17
	v_cos_f32_e32 v17, v17
	v_xor_b32_e32 v4, 0x80000000, v8
	v_pk_mov_b32 v[2:3], v[8:9], v[8:9] op_sel:[1,0]
	s_mov_b32 s90, s75
	v_mov_b32_e32 v3, v4
	v_mul_f32_e32 v10, s70, v8
	v_mul_f32_e32 v11, s70, v9
	s_mov_b32 s14, s71
	s_mov_b32 s15, s70
	s_mov_b32 s74, s91
	v_fma_f32 v2, -v8, 0, v2
	v_fma_f32 v3, -v9, 0, v3
	v_fma_f32 v4, v9, s14, v10
	v_fma_f32 v5, v8, s15, v11
	v_fma_f32 v6, v9, s90, -v8
	v_fma_f32 v7, v8, s91, -v9
	v_pk_fma_f32 v[8:9], v[8:9], s[70:71], v[10:11] op_sel:[1,0,0] op_sel_hi:[0,1,1]
	v_xor_b32_e32 v11, 0x80000000, v12
	v_mul_f32_e32 v14, s74, v12
	v_mul_f32_e32 v15, s75, v13
	v_mov_b32_e32 v10, v13
	v_fma_f32 v10, -v12, 0, v10
	v_fma_f32 v11, -v13, 0, v11
	v_sub_f32_e32 v12, v15, v12
	v_sub_f32_e32 v13, v14, v13
	v_xor_b32_e32 v15, 0x80000000, v16
	v_mov_b32_e32 v14, v17
	v_fma_f32 v14, -v16, 0, v14
	v_fma_f32 v15, -v17, 0, v15
	v_pk_mov_b32 v[18:19], v[10:11], v[10:11] op_sel:[1,0]
	v_pk_mov_b32 v[16:17], v[14:15], v[14:15] op_sel:[1,0]
	v_pk_mov_b32 v[20:21], v[12:13], v[12:13] op_sel:[1,0]
	v_pk_mov_b32 v[22:23], v[2:3], v[2:3] op_sel:[1,0]
	v_pk_mov_b32 v[24:25], v[4:5], v[4:5] op_sel:[1,0]
	v_pk_mov_b32 v[26:27], v[6:7], v[6:7] op_sel:[1,0]
	v_pk_mov_b32 v[28:29], v[8:9], v[8:9] op_sel:[1,0]
	v_lshlrev_b32_e32 v32, 3, v30
	s_mov_b64 s[14:15], 0
;     static __device__ __forceinline__ float sl(float g, float up) { return g * __builtin_amdgcn_rcpf(1.0f + __builtin_amdgcn_exp2f(-1.4426950408889634f * g)) * up; }
; __device__ __forceinline__ float2 cmul(float2 a, float2 b) { return make_float2(a.x * b.x - a.y * b.y, a.x * b.y + a.y * b.x); }
; #define tid ltid()
; template <int LR, bool INV>
; __device__ __forceinline__ void fft_stages(float2 (&x)[1 << LR], const int r, const int s) {
;   constexpr int R = 1 << LR;
; #pragma unroll
;   for (int st = 0; st < LR; ++st) {
;     const int hl = INV ? (1 << st) : (R >> (st + 1));
;     const float fb = (float)r * (0.5f / (float)(hl * s));
;     const float2 wb = make_float2(__builtin_amdgcn_cosf(fb), INV ? __builtin_amdgcn_sinf(fb) : -__builtin_amdgcn_sinf(fb));
; #pragma unroll
;     for (int m = 0; m < R; ++m) {
;       if (m & hl) continue;
;       const int k = m & (hl - 1); const int j = k * (8 / hl);
;       const float2 wc = make_float2(c16(j), INV ? s16(j) : -s16(j));
;       const float2 tw = cmul(wb, wc);
;       if (!INV) { const float2 p = x[m], q = x[m + hl]; x[m] = make_float2(p.x + q.x, p.y + q.y); x[m + hl] = cmul(make_float2(p.x - q.x, p.y - q.y), tw); }
;       else { const float2 p = x[m], q = cmul(x[m + hl], tw); x[m] = make_float2(p.x + q.x, p.y + q.y); x[m + hl] = make_float2(p.x - q.x, p.y - q.y); }
;     }
;   }
; }
; template <int LR, bool INV>
; __device__ __forceinline__ void fft_pass(float2* X, const int N, const int sl, const int tid) {
;   constexpr int R = 1 << LR;
;   const int s = 1 << sl;
;   for (int g = tid; g < (N >> LR); g += NTHR) {
;     const int r = g & (s - 1);
;     const int i0 = ((g >> sl) << (sl + LR)) + r;
;     float2 x[R];
; #pragma unroll
;     for (int m = 0; m < R; ++m) x[m] = X[PIDX(i0 + (m << sl))];
;     fft_stages<LR, INV>(x, r, s);
; #pragma unroll
;     for (int m = 0; m < R; ++m) X[PIDX(i0 + (m << sl))] = x[m];
;   }
;   __syncthreads();
.LBB0_675:
	v_and_or_b32 v33, v32, s53, v31
	v_ashrrev_i32_e32 v34, 4, v33
	v_lshlrev_b32_e32 v34, 3, v34
	v_lshlrev_b32_e32 v35, 3, v33
	v_add3_u32 v52, 0, v34, v35
	v_or_b32_e32 v34, 64, v33
	v_ashrrev_i32_e32 v34, 4, v34
	v_lshlrev_b32_e32 v34, 3, v34
	v_add3_u32 v53, 0, v34, v35
	v_or_b32_e32 v34, 0x80, v33
	v_ashrrev_i32_e32 v34, 4, v34
	v_lshlrev_b32_e32 v34, 3, v34
	v_add3_u32 v54, 0, v34, v35
	v_or_b32_e32 v34, 0xc0, v33
	v_ashrrev_i32_e32 v34, 4, v34
	v_lshlrev_b32_e32 v34, 3, v34
	v_add3_u32 v55, 0, v34, v35
	v_or_b32_e32 v34, 0x100, v33
	v_ashrrev_i32_e32 v34, 4, v34
	v_lshlrev_b32_e32 v34, 3, v34
	v_add3_u32 v56, 0, v34, v35
	v_or_b32_e32 v34, 0x140, v33
	v_ashrrev_i32_e32 v34, 4, v34
	v_lshlrev_b32_e32 v34, 3, v34
	v_add3_u32 v57, 0, v34, v35
	v_or_b32_e32 v34, 0x180, v33
	v_or_b32_e32 v33, 0x1c0, v33
	v_ashrrev_i32_e32 v34, 4, v34
	v_ashrrev_i32_e32 v33, 4, v33
	v_lshlrev_b32_e32 v34, 3, v34
	v_lshlrev_b32_e32 v33, 3, v33
	v_add3_u32 v58, 0, v34, v35
	v_add3_u32 v33, 0, v33, v35
	ds_read_b64 v[34:35], v52
	ds_read_b64 v[36:37], v53 offset:512
	ds_read_b64 v[38:39], v54 offset:1024
	ds_read_b64 v[40:41], v55 offset:1536
	ds_read_b64 v[42:43], v56 offset:2048
	ds_read_b64 v[44:45], v57 offset:2560
	ds_read_b64 v[46:47], v58 offset:3072
	ds_read_b64 v[48:49], v33 offset:3584
	v_add_u32_e32 v30, 0x200, v30
	s_waitcnt lgkmcnt(3)
	v_add_f32_e32 v50, v34, v42
	v_add_f32_e32 v51, v35, v43
	v_sub_f32_e32 v34, v34, v42
	v_sub_f32_e32 v35, v35, v43
	s_waitcnt lgkmcnt(2)
	v_add_f32_e32 v42, v36, v44
	v_add_f32_e32 v43, v37, v45
	v_sub_f32_e32 v36, v36, v44
	v_sub_f32_e32 v37, v37, v45
	s_waitcnt lgkmcnt(1)
	v_add_f32_e32 v44, v38, v46
	v_add_f32_e32 v45, v39, v47
	v_sub_f32_e32 v38, v38, v46
	v_sub_f32_e32 v39, v39, v47
	s_waitcnt lgkmcnt(0)
	v_add_f32_e32 v46, v40, v48
	v_add_f32_e32 v47, v41, v49
	v_sub_f32_e32 v40, v40, v48
	v_sub_f32_e32 v41, v41, v49
	v_add_f32_e32 v48, v50, v44
	v_add_f32_e32 v49, v51, v45
	v_sub_f32_e32 v44, v50, v44
	v_sub_f32_e32 v45, v51, v45
	v_add_f32_e32 v50, v42, v46
	v_add_f32_e32 v51, v43, v47
	v_sub_f32_e32 v42, v42, v46
	v_sub_f32_e32 v43, v43, v47
	v_add_f32_e32 v46, v48, v50
	v_add_f32_e32 v47, v49, v51
	v_sub_f32_e32 v48, v48, v50
	v_sub_f32_e32 v49, v49, v51
	ds_write_b64 v52, v[46:47]
	v_mul_f32_e32 v46, v16, v49
	v_mul_f32_e32 v47, v17, v49
	v_cmp_le_i32_e32 vcc, s21, v30
	v_fma_f32 v50, v14, v48, -v46
	v_fma_f32 v47, v15, v48, v47
	v_add_u32_e32 v32, 0x1000, v32
	v_mov_b32_e32 v51, v47
	v_mul_f32_e32 v46, v18, v45
	v_mul_f32_e32 v47, v19, v45
	ds_write_b64 v53, v[50:51] offset:512
	v_fma_f32 v48, v10, v44, -v46
	v_fma_f32 v45, v11, v44, v47
	s_or_b64 s[14:15], vcc, s[14:15]
	v_mov_b32_e32 v49, v45
	v_mul_f32_e32 v44, v20, v43
	v_mul_f32_e32 v45, v21, v43
	v_fma_f32 v46, v12, v42, -v44
	v_fma_f32 v43, v13, v42, v45
	v_mov_b32_e32 v47, v43
	v_add_f32_e32 v42, v48, v46
	v_add_f32_e32 v43, v49, v47
	v_sub_f32_e32 v44, v48, v46
	v_sub_f32_e32 v45, v49, v47
	ds_write_b64 v54, v[42:43] offset:1024
	v_mul_f32_e32 v42, v16, v45
	v_mul_f32_e32 v43, v17, v45
	v_fma_f32 v46, v14, v44, -v42
	v_fma_f32 v43, v15, v44, v43
	v_mov_b32_e32 v47, v43
	v_mul_f32_e32 v42, v22, v35
	v_mul_f32_e32 v43, v23, v35
	ds_write_b64 v55, v[46:47] offset:1536
	v_fma_f32 v44, v2, v34, -v42
	v_fma_f32 v35, v3, v34, v43
	v_mov_b32_e32 v45, v35
	v_mul_f32_e32 v34, v24, v37
	v_mul_f32_e32 v35, v25, v37
	v_fma_f32 v42, v4, v36, -v34
	v_fma_f32 v35, v5, v36, v35
	v_mov_b32_e32 v43, v35
	v_mul_f32_e32 v34, v26, v39
	v_mul_f32_e32 v35, v27, v39
	v_fma_f32 v36, v6, v38, -v34
	v_fma_f32 v35, v7, v38, v35
	v_mov_b32_e32 v37, v35
	v_mul_f32_e32 v34, v28, v41
	v_mul_f32_e32 v35, v29, v41
	v_fma_f32 v38, v8, v40, -v34
	v_fma_f32 v35, v9, v40, v35
	v_mov_b32_e32 v39, v35
	v_add_f32_e32 v34, v44, v36
	v_add_f32_e32 v35, v45, v37
	v_add_f32_e32 v40, v42, v38
	v_add_f32_e32 v41, v43, v39
	v_sub_f32_e32 v38, v42, v38
	v_sub_f32_e32 v39, v43, v39
	v_add_f32_e32 v42, v34, v40
	v_add_f32_e32 v43, v35, v41
	v_sub_f32_e32 v34, v34, v40
	v_sub_f32_e32 v35, v35, v41
	v_sub_f32_e32 v36, v44, v36
	v_sub_f32_e32 v37, v45, v37
	v_mul_f32_e32 v40, v16, v35
	v_mul_f32_e32 v41, v17, v35
	ds_write_b64 v56, v[42:43] offset:2048
	v_fma_f32 v42, v14, v34, -v40
	v_fma_f32 v35, v15, v34, v41
	v_mov_b32_e32 v43, v35
	v_mul_f32_e32 v34, v18, v37
	v_mul_f32_e32 v35, v19, v37
	ds_write_b64 v57, v[42:43] offset:2560
	v_fma_f32 v40, v10, v36, -v34
	v_fma_f32 v35, v11, v36, v35
	v_mov_b32_e32 v41, v35
	v_mul_f32_e32 v34, v20, v39
	v_mul_f32_e32 v35, v21, v39
	v_fma_f32 v36, v12, v38, -v34
	v_fma_f32 v35, v13, v38, v35
	v_mov_b32_e32 v37, v35
	v_add_f32_e32 v34, v40, v36
	v_add_f32_e32 v35, v41, v37
	v_sub_f32_e32 v36, v40, v36
	v_sub_f32_e32 v37, v41, v37
	ds_write_b64 v58, v[34:35] offset:3072
	v_mul_f32_e32 v34, v16, v37
	v_mul_f32_e32 v35, v17, v37
	v_fma_f32 v38, v14, v36, -v34
	v_fma_f32 v34, v14, v36, v34
	v_fma_f32 v35, v15, v36, v35
	v_mov_b32_e32 v39, v35
	ds_write_b64 v33, v[38:39] offset:3584
	s_andn2_b64 exec, exec, s[14:15]
	s_cbranch_execnz .LBB0_675
;     static __device__ __forceinline__ float sl(float g, float up) { return g * __builtin_amdgcn_rcpf(1.0f + __builtin_amdgcn_exp2f(-1.4426950408889634f * g)) * up; }
; __device__ __forceinline__ float2 cmul(float2 a, float2 b) { return make_float2(a.x * b.x - a.y * b.y, a.x * b.y + a.y * b.x); }
; #define tid ltid()
; template <int LR, bool INV>
; __device__ __forceinline__ void fft_stages(float2 (&x)[1 << LR], const int r, const int s) {
;   constexpr int R = 1 << LR;
; #pragma unroll
;   for (int st = 0; st < LR; ++st) {
;     const int hl = INV ? (1 << st) : (R >> (st + 1));
;     const float fb = (float)r * (0.5f / (float)(hl * s));
;     const float2 wb = make_float2(__builtin_amdgcn_cosf(fb), INV ? __builtin_amdgcn_sinf(fb) : -__builtin_amdgcn_sinf(fb));
; #pragma unroll
;     for (int m = 0; m < R; ++m) {
;       if (m & hl) continue;
;       const int k = m & (hl - 1); const int j = k * (8 / hl);
;       const float2 wc = make_float2(c16(j), INV ? s16(j) : -s16(j));
;       const float2 tw = cmul(wb, wc);
;       if (!INV) { const float2 p = x[m], q = x[m + hl]; x[m] = make_float2(p.x + q.x, p.y + q.y); x[m + hl] = cmul(make_float2(p.x - q.x, p.y - q.y), tw); }
;       else { const float2 p = x[m], q = cmul(x[m + hl], tw); x[m] = make_float2(p.x + q.x, p.y + q.y); x[m + hl] = make_float2(p.x - q.x, p.y - q.y); }
;     }
;   }
; }
; template <int LR, bool INV>
; __device__ __forceinline__ void fft_pass(float2* X, const int N, const int sl, const int tid) {
;   constexpr int R = 1 << LR;
;   const int s = 1 << sl;
;   for (int g = tid; g < (N >> LR); g += NTHR) {
;     const int r = g & (s - 1);
;     const int i0 = ((g >> sl) << (sl + LR)) + r;
;     float2 x[R];
; #pragma unroll
;     for (int m = 0; m < R; ++m) x[m] = X[PIDX(i0 + (m << sl))];
;     fft_stages<LR, INV>(x, r, s);
; #pragma unroll
;     for (int m = 0; m < R; ++m) X[PIDX(i0 + (m << sl))] = x[m];
;   }
;   __syncthreads();
.LBB0_676:
	s_or_b64 exec, exec, s[12:13]
	v_mov_b32_e32 v30, v208
	s_waitcnt lgkmcnt(0)
	s_barrier
	s_nop 0
	v_cmp_gt_i32_e32 vcc, s21, v30
	s_and_saveexec_b64 s[12:13], vcc
	s_cbranch_execz .LBB0_679
	v_and_b32_e32 v31, 7, v30
	v_cvt_f32_ubyte0_e32 v16, v31
	v_mul_f32_e32 v2, 0x3c800000, v16
	v_sin_f32_e32 v8, v2
	v_cos_f32_e32 v9, v2
	v_mul_f32_e32 v13, 0x3d000000, v16
	v_sin_f32_e32 v12, v13
	v_cos_f32_e32 v13, v13
	v_mul_f32_e32 v17, 0x3d800000, v16
	v_sin_f32_e32 v16, v17
	v_cos_f32_e32 v17, v17
	v_xor_b32_e32 v4, 0x80000000, v8
	v_pk_mov_b32 v[2:3], v[8:9], v[8:9] op_sel:[1,0]
	s_mov_b32 s90, s75
	v_mov_b32_e32 v3, v4
	v_mul_f32_e32 v10, s70, v8
	v_mul_f32_e32 v11, s70, v9
	s_mov_b32 s14, s71
	s_mov_b32 s15, s70
	s_mov_b32 s74, s91
	v_fma_f32 v2, -v8, 0, v2
	v_fma_f32 v3, -v9, 0, v3
	v_fma_f32 v4, v9, s14, v10
	v_fma_f32 v5, v8, s15, v11
	v_fma_f32 v6, v9, s90, -v8
	v_fma_f32 v7, v8, s91, -v9
	v_pk_fma_f32 v[8:9], v[8:9], s[70:71], v[10:11] op_sel:[1,0,0] op_sel_hi:[0,1,1]
	v_xor_b32_e32 v11, 0x80000000, v12
	v_mul_f32_e32 v14, s74, v12
	v_mul_f32_e32 v15, s75, v13
	v_mov_b32_e32 v10, v13
	v_fma_f32 v10, -v12, 0, v10
	v_fma_f32 v11, -v13, 0, v11
	v_sub_f32_e32 v12, v15, v12
	v_sub_f32_e32 v13, v14, v13
	v_xor_b32_e32 v15, 0x80000000, v16
	v_mov_b32_e32 v14, v17
	v_fma_f32 v14, -v16, 0, v14
	v_fma_f32 v15, -v17, 0, v15
	v_pk_mov_b32 v[18:19], v[10:11], v[10:11] op_sel:[1,0]
	v_pk_mov_b32 v[16:17], v[14:15], v[14:15] op_sel:[1,0]
	v_pk_mov_b32 v[20:21], v[12:13], v[12:13] op_sel:[1,0]
	v_pk_mov_b32 v[22:23], v[2:3], v[2:3] op_sel:[1,0]
	v_pk_mov_b32 v[24:25], v[4:5], v[4:5] op_sel:[1,0]
	v_pk_mov_b32 v[26:27], v[6:7], v[6:7] op_sel:[1,0]
	v_pk_mov_b32 v[28:29], v[8:9], v[8:9] op_sel:[1,0]
	v_lshlrev_b32_e32 v32, 3, v30
	s_mov_b64 s[14:15], 0
.LBB0_678:
	v_and_b32_e32 v33, 0xffffffc0, v32
	v_or_b32_e32 v34, v33, v31
	v_ashrrev_i32_e32 v35, 1, v33
	v_lshlrev_b32_e32 v34, 3, v34
	v_add3_u32 v54, 0, v35, v34
	v_or_b32_e32 v35, 16, v33
	v_ashrrev_i32_e32 v35, 4, v35
	v_lshlrev_b32_e32 v35, 3, v35
	v_add3_u32 v55, 0, v35, v34
	v_or_b32_e32 v35, 32, v33
	v_or_b32_e32 v33, 48, v33
	v_ashrrev_i32_e32 v35, 4, v35
	v_ashrrev_i32_e32 v33, 4, v33
	v_lshlrev_b32_e32 v35, 3, v35
	v_lshlrev_b32_e32 v33, 3, v33
	v_add3_u32 v56, 0, v35, v34
	v_add3_u32 v33, 0, v33, v34
	ds_read2_b64 v[34:37], v54 offset1:8
	ds_read2_b64 v[38:41], v55 offset0:16 offset1:24
	ds_read2_b64 v[42:45], v56 offset0:32 offset1:40
	ds_read2_b64 v[46:49], v33 offset0:48 offset1:56
	v_add_u32_e32 v30, 0x200, v30
	v_cmp_le_i32_e32 vcc, s21, v30
	v_add_u32_e32 v32, 0x1000, v32
	s_waitcnt lgkmcnt(1)
	v_add_f32_e32 v50, v34, v42
	v_add_f32_e32 v51, v35, v43
	v_sub_f32_e32 v34, v34, v42
	v_sub_f32_e32 v35, v35, v43
	v_add_f32_e32 v42, v36, v44
	v_add_f32_e32 v43, v37, v45
	v_sub_f32_e32 v36, v36, v44
	v_sub_f32_e32 v37, v37, v45
	s_waitcnt lgkmcnt(0)
	v_add_f32_e32 v44, v38, v46
	v_add_f32_e32 v45, v39, v47
	v_sub_f32_e32 v38, v38, v46
	v_sub_f32_e32 v39, v39, v47
	v_add_f32_e32 v46, v40, v48
	v_add_f32_e32 v47, v41, v49
	v_sub_f32_e32 v40, v40, v48
	v_sub_f32_e32 v41, v41, v49
	v_add_f32_e32 v48, v50, v44
	v_add_f32_e32 v49, v51, v45
	v_sub_f32_e32 v44, v50, v44
	v_sub_f32_e32 v45, v51, v45
	v_add_f32_e32 v50, v42, v46
	v_add_f32_e32 v51, v43, v47
	v_sub_f32_e32 v42, v42, v46
	v_sub_f32_e32 v43, v43, v47
	v_add_f32_e32 v46, v48, v50
	v_add_f32_e32 v47, v49, v51
	v_sub_f32_e32 v48, v48, v50
	v_sub_f32_e32 v49, v49, v51
	s_or_b64 s[14:15], vcc, s[14:15]
	v_mul_f32_e32 v50, v16, v49
	v_mul_f32_e32 v51, v17, v49
	v_fma_f32 v52, v14, v48, -v50
	v_fma_f32 v49, v15, v48, v51
	v_mov_b32_e32 v53, v49
	ds_write2_b64 v54, v[46:47], v[52:53] offset1:8
	v_mul_f32_e32 v46, v18, v45
	v_mul_f32_e32 v47, v19, v45
	v_fma_f32 v48, v10, v44, -v46
	v_fma_f32 v45, v11, v44, v47
	v_mov_b32_e32 v49, v45
	v_mul_f32_e32 v44, v20, v43
	v_mul_f32_e32 v45, v21, v43
	v_fma_f32 v46, v12, v42, -v44
	v_fma_f32 v43, v13, v42, v45
	v_mov_b32_e32 v47, v43
	v_sub_f32_e32 v44, v48, v46
	v_sub_f32_e32 v45, v49, v47
	v_add_f32_e32 v42, v48, v46
	v_add_f32_e32 v43, v49, v47
	v_mul_f32_e32 v46, v16, v45
	v_mul_f32_e32 v47, v17, v45
	v_fma_f32 v48, v14, v44, -v46
	v_fma_f32 v45, v15, v44, v47
	v_mov_b32_e32 v49, v45
	ds_write2_b64 v55, v[42:43], v[48:49] offset0:16 offset1:24
	v_mul_f32_e32 v42, v22, v35
	v_mul_f32_e32 v43, v23, v35
	v_fma_f32 v44, v2, v34, -v42
	v_fma_f32 v35, v3, v34, v43
	v_mov_b32_e32 v45, v35
	v_mul_f32_e32 v34, v24, v37
	v_mul_f32_e32 v35, v25, v37
	v_fma_f32 v42, v4, v36, -v34
	v_fma_f32 v35, v5, v36, v35
	v_mov_b32_e32 v43, v35
	v_mul_f32_e32 v34, v26, v39
	v_mul_f32_e32 v35, v27, v39
	v_fma_f32 v36, v6, v38, -v34
	v_fma_f32 v35, v7, v38, v35
	v_mov_b32_e32 v37, v35
	v_mul_f32_e32 v34, v28, v41
	v_mul_f32_e32 v35, v29, v41
	v_fma_f32 v38, v8, v40, -v34
	v_fma_f32 v35, v9, v40, v35
	v_mov_b32_e32 v39, v35
	v_add_f32_e32 v34, v44, v36
	v_add_f32_e32 v35, v45, v37
	v_add_f32_e32 v40, v42, v38
	v_add_f32_e32 v41, v43, v39
	v_sub_f32_e32 v38, v42, v38
	v_sub_f32_e32 v39, v43, v39
	v_add_f32_e32 v42, v34, v40
	v_add_f32_e32 v43, v35, v41
	v_sub_f32_e32 v34, v34, v40
	v_sub_f32_e32 v35, v35, v41
	v_sub_f32_e32 v36, v44, v36
	v_sub_f32_e32 v37, v45, v37
	v_mul_f32_e32 v40, v16, v35
	v_mul_f32_e32 v41, v17, v35
	v_fma_f32 v44, v14, v34, -v40
	v_fma_f32 v35, v15, v34, v41
	v_mov_b32_e32 v45, v35
	v_mul_f32_e32 v34, v18, v37
	v_mul_f32_e32 v35, v19, v37
	ds_write2_b64 v56, v[42:43], v[44:45] offset0:32 offset1:40
	v_fma_f32 v40, v10, v36, -v34
	v_fma_f32 v35, v11, v36, v35
	v_mov_b32_e32 v41, v35
	v_mul_f32_e32 v34, v20, v39
	v_mul_f32_e32 v35, v21, v39
	v_fma_f32 v36, v12, v38, -v34
	v_fma_f32 v35, v13, v38, v35
	v_mov_b32_e32 v37, v35
	v_add_f32_e32 v34, v40, v36
	v_add_f32_e32 v35, v41, v37
	v_sub_f32_e32 v36, v40, v36
	v_sub_f32_e32 v37, v41, v37
	v_mul_f32_e32 v38, v16, v37
	v_mul_f32_e32 v39, v17, v37
	v_fma_f32 v40, v14, v36, -v38
	v_fma_f32 v37, v15, v36, v39
	v_fma_f32 v36, v14, v36, v38
	v_mov_b32_e32 v41, v37
	ds_write2_b64 v33, v[34:35], v[40:41] offset0:48 offset1:56
	s_andn2_b64 exec, exec, s[14:15]
	s_cbranch_execnz .LBB0_678

; __device__ __forceinline__ float2 cmul(float2 a, float2 b) { return make_float2(a.x * b.x - a.y * b.y, a.x * b.y + a.y * b.x); }
; #define tid ltid()
; template <int LR, bool INV>
; __device__ __forceinline__ void fft_stages(float2 (&x)[1 << LR], const int r, const int s) {
;   constexpr int R = 1 << LR;
; #pragma unroll
;   for (int st = 0; st < LR; ++st) {
;     const int hl = INV ? (1 << st) : (R >> (st + 1));
;     const float fb = (float)r * (0.5f / (float)(hl * s));
;     const float2 wb = make_float2(__builtin_amdgcn_cosf(fb), INV ? __builtin_amdgcn_sinf(fb) : -__builtin_amdgcn_sinf(fb));
; #pragma unroll
;     for (int m = 0; m < R; ++m) {
;       if (m & hl) continue;
;       const int k = m & (hl - 1); const int j = k * (8 / hl);
;       const float2 wc = make_float2(c16(j), INV ? s16(j) : -s16(j));
;       const float2 tw = cmul(wb, wc);
;       if (!INV) { const float2 p = x[m], q = x[m + hl]; x[m] = make_float2(p.x + q.x, p.y + q.y); x[m + hl] = cmul(make_float2(p.x - q.x, p.y - q.y), tw); }
;       else { const float2 p = x[m], q = cmul(x[m + hl], tw); x[m] = make_float2(p.x + q.x, p.y + q.y); x[m + hl] = make_float2(p.x - q.x, p.y - q.y); }
;     }
;   }
; __device__ __forceinline__ void fft_mid(float2* X, const float2* Hb, const int N, const float invN, const int tid) {
;   for (int g = tid; g < (N >> 3); g += NTHR) {
;     const int i0 = g << 3; const int p0 = PIDX(i0);
;     float2 x[8];
; #pragma unroll
;     for (int m = 0; m < 8; ++m) x[m] = X[p0 + m];
;     fft_stages<3, false>(x, 0, 1);
; #pragma unroll
;     for (int m = 0; m < 8; ++m) { const float2 h = Hb[p0 + m]; const float2 v = x[m]; x[m] = make_float2((v.x * h.x - v.y * h.y) * invN, (v.x * h.y + v.y * h.x) * invN); }
;     fft_stages<3, true>(x, 0, 1);
; #pragma unroll
;     for (int m = 0; m < 8; ++m) X[p0 + m] = x[m];
;   }
;   __syncthreads();
; }
.LBB0_681:
	v_ashrrev_i32_e32 v4, 4, v3
	v_add_u32_e32 v4, v3, v4
	v_lshl_add_u32 v38, v4, 3, 0
	ds_read2_b64 v[4:7], v38 offset1:1
	ds_read2_b64 v[8:11], v38 offset0:2 offset1:3
	ds_read2_b64 v[12:15], v38 offset0:4 offset1:5
	ds_read2_b64 v[16:19], v38 offset0:6 offset1:7
	v_add_u32_e32 v2, 0x200, v2
	v_cmp_le_i32_e32 vcc, s21, v2
	v_add_u32_e32 v3, 0x1000, v3
	s_waitcnt lgkmcnt(1)
	v_sub_f32_e32 v20, v4, v12
	v_sub_f32_e32 v21, v5, v13
	v_add_f32_e32 v4, v4, v12
	v_add_f32_e32 v5, v5, v13
	v_mul_f32_e32 v22, 0, v20
	v_mul_f32_e32 v23, 0, v21
	s_or_b64 s[14:15], vcc, s[14:15]
	v_sub_f32_e32 v24, v20, v23
	v_sub_f32_e32 v25, v21, v22
	v_add_f32_e32 v20, v20, v23
	v_add_f32_e32 v21, v21, v22
	s_waitcnt lgkmcnt(0)
	v_sub_f32_e32 v22, v8, v16
	v_sub_f32_e32 v23, v9, v17
	v_pk_mov_b32 v[20:21], v[24:25], v[20:21] op_sel:[1,0]
	v_mul_f32_e32 v24, 0, v22
	v_mul_f32_e32 v25, 0, v23
	v_sub_f32_e32 v26, v25, v22
	v_add_f32_e32 v23, v24, v23
	v_mov_b32_e32 v27, v23
	v_sub_f32_e32 v22, v20, v26
	v_sub_f32_e32 v23, v21, v27
	v_mul_f32_e32 v24, 0, v22
	v_mul_f32_e32 v25, 0, v23
	v_sub_f32_e32 v28, v22, v25
	v_add_f32_e32 v23, v23, v24
	v_add_f32_e32 v24, v10, v18
	v_add_f32_e32 v25, v11, v19
	v_mov_b32_e32 v29, v23
	v_add_f32_e32 v22, v6, v14
	v_add_f32_e32 v23, v7, v15
	v_sub_f32_e32 v6, v6, v14
	v_sub_f32_e32 v7, v7, v15
	v_sub_f32_e32 v10, v10, v18
	v_sub_f32_e32 v11, v11, v19
	v_mul_f32_e32 v15, 0x3f3504f3, v6
	v_mul_f32_e32 v6, 0x3f3504f3, v7
	v_mul_f32_e32 v34, 0xbf3504f3, v10
	v_mul_f32_e32 v11, 0xbf3504f3, v11
	v_sub_f32_e32 v14, v6, v15
	v_fmac_f32_e32 v15, 0x3f3504f3, v7
	v_add_f32_e32 v6, v8, v16
	v_add_f32_e32 v7, v9, v17
	v_add_f32_e32 v8, v34, v11
	v_fma_f32 v9, v10, s70, -v11
	v_sub_f32_e32 v10, v4, v6
	v_sub_f32_e32 v11, v5, v7
	v_sub_f32_e32 v18, v22, v24
	v_sub_f32_e32 v19, v23, v25
	v_mul_f32_e32 v12, 0, v10
	v_mul_f32_e32 v13, 0, v11
	v_mul_f32_e32 v30, 0, v18
	v_mul_f32_e32 v31, 0, v19
	v_sub_f32_e32 v16, v10, v13
	v_sub_f32_e32 v17, v11, v12
	v_add_f32_e32 v10, v10, v13
	v_add_f32_e32 v11, v11, v12
	v_sub_f32_e32 v12, v14, v8
	v_sub_f32_e32 v13, v15, v9
	v_pk_mov_b32 v[10:11], v[16:17], v[10:11] op_sel:[1,0]
	v_fma_f32 v16, v12, 0, -v13
	v_fma_f32 v13, v13, 0, v12
	v_sub_f32_e32 v32, v31, v18
	v_add_f32_e32 v19, v30, v19
	v_mov_b32_e32 v17, v13
	v_add_f32_e32 v12, v22, v24
	v_add_f32_e32 v13, v23, v25
	v_add_f32_e32 v4, v4, v6
	v_add_f32_e32 v5, v5, v7
	v_mov_b32_e32 v33, v19
	v_add_f32_e32 v18, v4, v12
	v_add_f32_e32 v19, v5, v13
	v_sub_f32_e32 v12, v4, v12
	v_sub_f32_e32 v13, v5, v13
	v_add_f32_e32 v4, v20, v26
	v_add_f32_e32 v5, v21, v27
	v_add_f32_e32 v26, v28, v16
	v_add_f32_e32 v27, v29, v17
	v_sub_f32_e32 v16, v28, v16
	v_sub_f32_e32 v17, v29, v17
	v_add_f32_e32 v6, v14, v8
	v_add_f32_e32 v7, v15, v9
	v_fma_f32 v28, 0, v16, v17
	v_fmac_f32_e32 v16, 0x80000000, v17
	v_add_u32_e32 v17, 0x11000, v38
	v_add_f32_e32 v8, v4, v6
	v_add_f32_e32 v9, v5, v7
	v_sub_f32_e32 v14, v4, v6
	v_sub_f32_e32 v15, v5, v7
	ds_read2_b64 v[4:7], v17 offset1:1
	v_fma_f32 v22, 0, v13, v12
	v_fmac_f32_e32 v13, 0x80000000, v12
	v_add_f32_e32 v24, v10, v32
	v_add_f32_e32 v25, v11, v33
	v_sub_f32_e32 v10, v10, v32
	v_sub_f32_e32 v11, v11, v33
	s_waitcnt lgkmcnt(0)
	v_mul_f32_e32 v30, v5, v19
	v_mul_f32_e32 v31, v4, v19
	v_fma_f32 v32, v4, v18, -v30
	v_fma_f32 v5, v5, v18, v31
	v_fma_f32 v12, 0, v10, v11
	v_mov_b32_e32 v4, v13
	v_mov_b32_e32 v33, v5
	v_mul_f32_e32 v5, v6, v4
	v_mul_f32_e32 v4, v7, v4
	v_fma_f32 v18, v6, v22, -v4
	v_fma_f32 v5, v7, v22, v5
	v_fmac_f32_e32 v10, 0x80000000, v11
	v_mov_b32_e32 v19, v5
	ds_read2_b64 v[4:7], v17 offset0:2 offset1:3
	v_fma_f32 v20, 0, v14, v15
	v_fmac_f32_e32 v14, 0x80000000, v15
	v_mul_f32_e32 v22, v0, v18
	v_mul_f32_e32 v23, v1, v19
	s_waitcnt lgkmcnt(0)
	v_mul_f32_e32 v30, v24, v5
	v_mul_f32_e32 v31, v24, v4
	v_fma_f32 v34, v25, v4, -v30
	v_fma_f32 v5, v25, v5, v31
	v_mov_b32_e32 v35, v5
	v_mul_f32_e32 v4, v10, v7
	v_mul_f32_e32 v5, v10, v6
	v_fma_f32 v10, v6, v12, -v4
	v_fma_f32 v5, v7, v12, v5
	v_mov_b32_e32 v11, v5
	ds_read2_b64 v[4:7], v17 offset0:4 offset1:5
	v_mul_f32_e32 v12, v0, v10
	v_mul_f32_e32 v13, v1, v11
	s_waitcnt lgkmcnt(0)
	v_mul_f32_e32 v24, v8, v5
	v_mul_f32_e32 v25, v8, v4
	v_fma_f32 v30, v9, v4, -v24
	v_fma_f32 v31, v9, v5, -v25
	v_fma_f32 v9, v9, v5, v25
	v_mul_f32_e32 v4, v14, v7
	v_mul_f32_e32 v5, v14, v6
	v_fma_f32 v14, v20, v6, -v4
	v_fma_f32 v5, v20, v7, v5
	v_mov_b32_e32 v15, v5
	ds_read2_b64 v[4:7], v17 offset0:6 offset1:7
	v_mov_b32_e32 v8, v30
	v_mul_f32_e32 v24, v0, v30
	v_mul_f32_e32 v20, v0, v14
	v_mul_f32_e32 v21, v1, v15
	v_mul_f32_e32 v12, 0, v12
	v_mul_f32_e32 v13, 0, v13
	s_waitcnt lgkmcnt(0)
; __device__ __forceinline__ float2 cmul(float2 a, float2 b) { return make_float2(a.x * b.x - a.y * b.y, a.x * b.y + a.y * b.x); }
; #define tid ltid()
; template <int LR, bool INV>
; __device__ __forceinline__ void fft_stages(float2 (&x)[1 << LR], const int r, const int s) {
;   constexpr int R = 1 << LR;
; #pragma unroll
;   for (int st = 0; st < LR; ++st) {
;     const int hl = INV ? (1 << st) : (R >> (st + 1));
;     const float fb = (float)r * (0.5f / (float)(hl * s));
;     const float2 wb = make_float2(__builtin_amdgcn_cosf(fb), INV ? __builtin_amdgcn_sinf(fb) : -__builtin_amdgcn_sinf(fb));
; #pragma unroll
;     for (int m = 0; m < R; ++m) {
;       if (m & hl) continue;
;       const int k = m & (hl - 1); const int j = k * (8 / hl);
;       const float2 wc = make_float2(c16(j), INV ? s16(j) : -s16(j));
;       const float2 tw = cmul(wb, wc);
;       if (!INV) { const float2 p = x[m], q = x[m + hl]; x[m] = make_float2(p.x + q.x, p.y + q.y); x[m + hl] = cmul(make_float2(p.x - q.x, p.y - q.y), tw); }
;       else { const float2 p = x[m], q = cmul(x[m + hl], tw); x[m] = make_float2(p.x + q.x, p.y + q.y); x[m + hl] = make_float2(p.x - q.x, p.y - q.y); }
;     }
;   }
; __device__ __forceinline__ void fft_mid(float2* X, const float2* Hb, const int N, const float invN, const int tid) {
;   for (int g = tid; g < (N >> 3); g += NTHR) {
;     const int i0 = g << 3; const int p0 = PIDX(i0);
;     float2 x[8];
; #pragma unroll
;     for (int m = 0; m < 8; ++m) x[m] = X[p0 + m];
;     fft_stages<3, false>(x, 0, 1);
; #pragma unroll
;     for (int m = 0; m < 8; ++m) { const float2 h = Hb[p0 + m]; const float2 v = x[m]; x[m] = make_float2((v.x * h.x - v.y * h.y) * invN, (v.x * h.y + v.y * h.x) * invN); }
;     fft_stages<3, true>(x, 0, 1);
; #pragma unroll
;     for (int m = 0; m < 8; ++m) X[p0 + m] = x[m];
;   }
;   __syncthreads();
; }
	v_mul_f32_e32 v30, v26, v5
	v_mul_f32_e32 v31, v26, v4
	v_fma_f32 v36, v27, v4, -v30
	v_fma_f32 v5, v27, v5, v31
	v_mov_b32_e32 v37, v5
	v_mul_f32_e32 v4, v16, v7
	v_mul_f32_e32 v5, v16, v6
	v_fma_f32 v16, v28, v6, -v4
	v_fma_f32 v5, v28, v7, v5
	v_mul_f32_e32 v6, 0, v22
	v_mul_f32_e32 v7, 0, v23
	v_mov_b32_e32 v17, v5
	v_fma_f32 v22, v0, v18, -v7
	v_fma_f32 v7, v1, v19, v6
	v_fma_f32 v18, v0, v10, -v13
	v_fma_f32 v11, v1, v11, v12
	v_mul_f32_e32 v12, 0, v20
	v_mul_f32_e32 v13, 0, v21
	v_mul_f32_e32 v4, v0, v16
	v_mul_f32_e32 v5, v1, v17
	v_fma_f32 v20, v0, v14, -v13
	v_pk_fma_f32 v[12:13], v[0:1], v[14:15], v[12:13] op_sel:[0,0,1] op_sel_hi:[1,1,0]
	v_mul_f32_e32 v4, 0, v4
	v_mul_f32_e32 v5, 0, v5
	v_mov_b32_e32 v21, v13
	v_mov_b32_e32 v19, v11
	v_fma_f32 v14, v0, v8, v20
	v_fma_f32 v15, v1, v9, v21
	v_fma_f32 v9, v1, v9, -v13
	v_fma_f32 v12, v0, v16, -v5
	v_fma_f32 v5, v1, v17, v4
	v_fma_f32 v10, v0, v34, v18
	v_fma_f32 v11, v1, v35, v19
	v_mov_b32_e32 v13, v5
	v_fma_f32 v4, v0, v36, v12
	v_fma_f32 v5, v1, v37, v13
	v_mul_f32_e32 v16, 0, v10
	v_mul_f32_e32 v17, 0, v11
	v_fma_f32 v12, v0, v36, -v12
	v_fma_f32 v13, v1, v37, -v13
	v_sub_f32_e32 v26, v10, v17
	v_add_f32_e32 v11, v11, v16
	v_mul_f32_e32 v16, 0, v4
	v_mul_f32_e32 v17, 0, v5
	v_mul_f32_e32 v25, 0, v12
	v_sub_f32_e32 v28, v4, v17
	v_add_f32_e32 v5, v5, v16
	v_mov_b32_e32 v21, v13
	v_mov_b32_e32 v29, v5
	v_add_f32_e32 v4, v14, v28
	v_add_f32_e32 v5, v15, v29
	v_fmac_f32_e32 v12, 0, v13
	v_sub_f32_e32 v16, v24, v20
	v_sub_f32_e32 v17, v25, v21
	v_add_f32_e32 v20, v9, v12
	v_sub_f32_e32 v24, v9, v12
	v_mul_f32_e32 v8, 0, v4
	v_mul_f32_e32 v9, 0, v5
	v_fma_f32 v18, v0, v34, -v18
	v_fma_f32 v19, v1, v35, -v19
	v_mov_b32_e32 v23, v7
	v_add_f32_e32 v21, v16, v17
	v_sub_f32_e32 v12, v4, v9
	v_add_f32_e32 v5, v5, v8
	v_mul_f32_e32 v9, 0x3f3504f3, v20
	v_mul_f32_e32 v20, 0x3f3504f3, v24
	v_fma_f32 v24, v18, 0, -v19
	v_fma_f32 v19, v19, 0, v18
	v_fma_f32 v6, v0, v32, v22
	v_fma_f32 v7, v1, v33, v23
	v_mov_b32_e32 v27, v11
	v_mul_f32_e32 v8, 0x3f3504f3, v21
	v_fma_f32 v22, v0, v32, -v22
	v_fma_f32 v23, v1, v33, -v23
	v_mov_b32_e32 v25, v19
	v_add_f32_e32 v10, v6, v26
	v_add_f32_e32 v11, v7, v27
	v_mov_b32_e32 v13, v5
	v_add_f32_e32 v18, v22, v24
	v_add_f32_e32 v19, v23, v25
	v_sub_f32_e32 v8, v8, v9
	v_fmac_f32_e32 v9, 0x3f3504f3, v21
	v_add_f32_e32 v4, v10, v12
	v_add_f32_e32 v5, v11, v13
	v_add_f32_e32 v30, v18, v8
	v_add_f32_e32 v31, v19, v9
	ds_write2_b64 v38, v[4:5], v[30:31] offset1:1
	v_sub_f32_e32 v4, v6, v26
	v_sub_f32_e32 v5, v7, v27
	v_sub_f32_e32 v6, v14, v28
	v_sub_f32_e32 v7, v15, v29
	v_pk_add_f32 v[16:17], v[16:17], v[16:17] op_sel:[0,1] op_sel_hi:[0,1] neg_lo:[0,1] neg_hi:[0,1]
	v_fma_f32 v14, v6, 0, -v7
	v_fma_f32 v7, v7, 0, v6
	v_fma_f32 v16, v16, s70, -v20
	v_fma_f32 v17, v17, s71, -v20
	v_mov_b32_e32 v15, v7
	v_sub_f32_e32 v20, v22, v24
	v_sub_f32_e32 v21, v23, v25
	v_add_f32_e32 v6, v4, v14
	v_add_f32_e32 v7, v5, v15
	v_add_f32_e32 v22, v20, v16
	v_add_f32_e32 v23, v21, v17
	ds_write2_b64 v38, v[6:7], v[22:23] offset0:2 offset1:3
	v_sub_f32_e32 v6, v10, v12
	v_sub_f32_e32 v7, v11, v13
	v_sub_f32_e32 v8, v18, v8
	v_sub_f32_e32 v9, v19, v9
	ds_write2_b64 v38, v[6:7], v[8:9] offset0:4 offset1:5
	v_sub_f32_e32 v4, v4, v14
	v_sub_f32_e32 v5, v5, v15
	v_sub_f32_e32 v6, v20, v16
	v_sub_f32_e32 v7, v21, v17
	ds_write2_b64 v38, v[4:5], v[6:7] offset0:6 offset1:7
	s_andn2_b64 exec, exec, s[14:15]
	s_cbranch_execnz .LBB0_681
.LBB0_682:
	s_or_b64 exec, exec, s[12:13]
	v_mov_b32_e32 v30, v208
	s_waitcnt lgkmcnt(0)
	s_barrier
	s_nop 0
	v_cmp_gt_i32_e32 vcc, s21, v30
	s_and_saveexec_b64 s[12:13], vcc
	s_cbranch_execz .LBB0_685
	v_and_b32_e32 v31, 7, v30
	v_cvt_f32_ubyte0_e32 v3, v31
	v_mul_f32_e32 v2, 0x3d800000, v3
	v_mul_f32_e32 v6, 0x3d000000, v3
	v_mul_f32_e32 v3, 0x3c800000, v3
	v_cos_f32_e32 v24, v3
	v_sin_f32_e32 v3, v3
	v_cos_f32_e32 v5, v2
	v_sin_f32_e32 v2, v2
	v_cos_f32_e32 v4, v6
	v_sin_f32_e32 v7, v6
	v_mul_f32_e32 v26, 0x3f3504f3, v3
	v_mul_f32_e32 v22, 0x3f3504f3, v24
	v_fmamk_f32 v6, v2, 0x80000000, v5
	v_fmac_f32_e32 v2, 0, v5
	v_fmamk_f32 v8, v7, 0x80000000, v4
	v_fma_f32 v10, 0, v4, v7
	v_fma_f32 v12, v4, 0, -v7
	v_fmac_f32_e32 v4, 0, v7
	v_fmamk_f32 v14, v3, 0x80000000, v24
	v_fma_f32 v16, 0, v24, v3
	v_fma_f32 v18, v24, 0, -v3
	v_fma_f32 v20, 0, v3, v24
	v_fmac_f32_e32 v22, 0x3f3504f3, v3
	v_fma_f32 v25, v24, s71, -v26
	v_fma_f32 v24, v24, s70, -v26
	v_mov_b32_e32 v7, v6
	v_mov_b32_e32 v3, v2
	v_mov_b32_e32 v13, v12
	v_mov_b32_e32 v5, v4
	v_mov_b32_e32 v19, v18
	v_mov_b32_e32 v9, v8
	v_mov_b32_e32 v11, v10
	v_mov_b32_e32 v15, v14
	v_mov_b32_e32 v26, v25
	v_mov_b32_e32 v27, v25
	v_mov_b32_e32 v21, v20
	v_mov_b32_e32 v17, v16
	v_mov_b32_e32 v23, v22
	v_pk_mov_b32 v[28:29], v[24:25], v[24:25] op_sel:[1,0]
	v_lshlrev_b32_e32 v32, 3, v30
	s_mov_b64 s[14:15], 0
;     static __device__ __forceinline__ float sl(float g, float up) { return g * __builtin_amdgcn_rcpf(1.0f + __builtin_amdgcn_exp2f(-1.4426950408889634f * g)) * up; }
; __device__ __forceinline__ float2 cmul(float2 a, float2 b) { return make_float2(a.x * b.x - a.y * b.y, a.x * b.y + a.y * b.x); }
; #define tid ltid()
; template <int LR, bool INV>
; __device__ __forceinline__ void fft_stages(float2 (&x)[1 << LR], const int r, const int s) {
;   constexpr int R = 1 << LR;
; #pragma unroll
;   for (int st = 0; st < LR; ++st) {
;     const int hl = INV ? (1 << st) : (R >> (st + 1));
;     const float fb = (float)r * (0.5f / (float)(hl * s));
;     const float2 wb = make_float2(__builtin_amdgcn_cosf(fb), INV ? __builtin_amdgcn_sinf(fb) : -__builtin_amdgcn_sinf(fb));
; #pragma unroll
;     for (int m = 0; m < R; ++m) {
;       if (m & hl) continue;
;       const int k = m & (hl - 1); const int j = k * (8 / hl);
;       const float2 wc = make_float2(c16(j), INV ? s16(j) : -s16(j));
;       const float2 tw = cmul(wb, wc);
;       if (!INV) { const float2 p = x[m], q = x[m + hl]; x[m] = make_float2(p.x + q.x, p.y + q.y); x[m + hl] = cmul(make_float2(p.x - q.x, p.y - q.y), tw); }
;       else { const float2 p = x[m], q = cmul(x[m + hl], tw); x[m] = make_float2(p.x + q.x, p.y + q.y); x[m + hl] = make_float2(p.x - q.x, p.y - q.y); }
;     }
;   }
; }
; template <int LR, bool INV>
; __device__ __forceinline__ void fft_pass(float2* X, const int N, const int sl, const int tid) {
;   constexpr int R = 1 << LR;
;   const int s = 1 << sl;
;   for (int g = tid; g < (N >> LR); g += NTHR) {
;     const int r = g & (s - 1);
;     const int i0 = ((g >> sl) << (sl + LR)) + r;
;     float2 x[R];
; #pragma unroll
;     for (int m = 0; m < R; ++m) x[m] = X[PIDX(i0 + (m << sl))];
;     fft_stages<LR, INV>(x, r, s);
; #pragma unroll
;     for (int m = 0; m < R; ++m) X[PIDX(i0 + (m << sl))] = x[m];
;   }
;   __syncthreads();
.LBB0_684:
	v_and_b32_e32 v33, 0xffffffc0, v32
	v_or_b32_e32 v34, v33, v31
	v_ashrrev_i32_e32 v35, 1, v33
	v_or_b32_e32 v36, 16, v33
	v_or_b32_e32 v37, 32, v33
	v_or_b32_e32 v33, 48, v33
	v_lshl_add_u32 v34, v34, 3, 0
	v_ashrrev_i32_e32 v36, 4, v36
	v_ashrrev_i32_e32 v37, 4, v37
	v_ashrrev_i32_e32 v33, 4, v33
	v_add_u32_e32 v60, v34, v35
	v_lshl_add_u32 v61, v36, 3, v34
	v_lshl_add_u32 v62, v37, 3, v34
	v_lshl_add_u32 v33, v33, 3, v34
	ds_read2_b64 v[34:37], v60 offset1:8
	ds_read2_b64 v[38:41], v61 offset0:16 offset1:24
	ds_read2_b64 v[42:45], v62 offset0:32 offset1:40
	ds_read2_b64 v[46:49], v33 offset0:48 offset1:56
	v_add_u32_e32 v30, 0x200, v30
	s_waitcnt lgkmcnt(3)
	v_mul_f32_e32 v50, v36, v2
	v_mul_f32_e32 v51, v37, v3
	s_waitcnt lgkmcnt(2)
	v_mul_f32_e32 v52, v2, v40
	v_mul_f32_e32 v53, v3, v41
	s_waitcnt lgkmcnt(1)
	v_mul_f32_e32 v54, v2, v44
	v_mul_f32_e32 v55, v3, v45
	s_waitcnt lgkmcnt(0)
	v_mul_f32_e32 v56, v2, v48
	v_mul_f32_e32 v57, v3, v49
	v_fma_f32 v58, v36, v6, -v51
	v_fma_f32 v37, v37, v7, v50
	v_fma_f32 v50, v6, v40, -v53
	v_fma_f32 v41, v7, v41, v52
	v_fma_f32 v52, v6, v44, -v55
	v_fma_f32 v45, v7, v45, v54
	v_fma_f32 v54, v6, v48, -v57
	v_fma_f32 v49, v7, v49, v56
	v_mov_b32_e32 v51, v41
	v_mov_b32_e32 v55, v49
	v_mov_b32_e32 v53, v45
	v_sub_f32_e32 v40, v38, v50
	v_sub_f32_e32 v41, v39, v51
	v_add_f32_e32 v48, v46, v54
	v_add_f32_e32 v49, v47, v55
	v_add_f32_e32 v38, v38, v50
	v_add_f32_e32 v39, v39, v51
	v_sub_f32_e32 v46, v46, v54
	v_sub_f32_e32 v47, v47, v55
	v_mov_b32_e32 v59, v37
	v_add_f32_e32 v44, v42, v52
	v_add_f32_e32 v45, v43, v53
	v_sub_f32_e32 v42, v42, v52
	v_sub_f32_e32 v43, v43, v53
	v_mul_f32_e32 v50, v4, v40
	v_mul_f32_e32 v51, v5, v41
	v_mul_f32_e32 v52, v10, v48
	v_mul_f32_e32 v53, v11, v49
	v_mul_f32_e32 v54, v10, v38
	v_mul_f32_e32 v55, v11, v39
	v_mul_f32_e32 v56, v4, v46
	v_mul_f32_e32 v57, v5, v47
	v_sub_f32_e32 v36, v34, v58
	v_sub_f32_e32 v37, v35, v59
	v_add_f32_e32 v34, v34, v58
	v_add_f32_e32 v35, v35, v59
	v_fma_f32 v58, v12, v40, -v51
	v_fma_f32 v41, v13, v41, v50
	v_fma_f32 v50, v8, v48, -v53
	v_fma_f32 v49, v9, v49, v52
	v_fma_f32 v52, v8, v38, -v55
	v_fma_f32 v39, v9, v39, v54
	v_fma_f32 v54, v12, v46, -v57
	v_fma_f32 v47, v13, v47, v56
	v_mov_b32_e32 v51, v49
	v_mov_b32_e32 v55, v47
	v_mov_b32_e32 v59, v41
	v_mov_b32_e32 v53, v39
	v_sub_f32_e32 v40, v44, v50
	v_sub_f32_e32 v41, v45, v51
	v_add_f32_e32 v44, v44, v50
	v_add_f32_e32 v45, v45, v51
	v_add_f32_e32 v48, v42, v54
	v_add_f32_e32 v49, v43, v55
	v_sub_f32_e32 v46, v34, v52
	v_sub_f32_e32 v47, v35, v53
	v_add_f32_e32 v34, v34, v52
	v_add_f32_e32 v35, v35, v53
	v_sub_f32_e32 v42, v42, v54
	v_sub_f32_e32 v43, v43, v55
	v_mul_f32_e32 v50, v20, v41
	v_mul_f32_e32 v51, v21, v40
	v_mul_f32_e32 v52, v16, v45
	v_mul_f32_e32 v53, v17, v44
	v_mul_f32_e32 v54, v22, v49
	v_mul_f32_e32 v55, v23, v48
	v_sub_f32_e32 v38, v36, v58
	v_sub_f32_e32 v39, v37, v59
	v_add_f32_e32 v36, v36, v58
	v_add_f32_e32 v37, v37, v59
	v_mul_f32_e32 v56, v28, v43
	v_mul_f32_e32 v57, v29, v43
	v_fma_f32 v58, v18, v40, -v50
	v_fma_f32 v41, v19, v41, v51
	v_fma_f32 v50, v14, v44, -v52
	v_fma_f32 v45, v15, v45, v53
	v_fma_f32 v52, v26, v48, -v54
	v_fma_f32 v49, v27, v49, v55
	v_cmp_le_i32_e32 vcc, s21, v30
	v_fma_f32 v54, v24, v42, -v56
	v_fma_f32 v43, v25, v42, v57
	v_mov_b32_e32 v51, v45
	v_mov_b32_e32 v53, v49
	v_add_u32_e32 v32, 0x1000, v32
	s_or_b64 s[14:15], vcc, s[14:15]
	v_mov_b32_e32 v59, v41
	v_mov_b32_e32 v55, v43
	v_add_f32_e32 v42, v34, v50
	v_add_f32_e32 v43, v35, v51
	v_add_f32_e32 v44, v36, v52
	v_add_f32_e32 v45, v37, v53
	v_add_f32_e32 v40, v46, v58
	v_add_f32_e32 v41, v47, v59
	v_add_f32_e32 v48, v38, v54
	v_add_f32_e32 v49, v39, v55
	v_sub_f32_e32 v34, v34, v50
	v_sub_f32_e32 v35, v35, v51
	v_sub_f32_e32 v36, v36, v52
	v_sub_f32_e32 v37, v37, v53
	v_sub_f32_e32 v46, v46, v58
	v_sub_f32_e32 v47, v47, v59
	v_sub_f32_e32 v38, v38, v54
	v_sub_f32_e32 v39, v39, v55
	ds_write2_b64 v60, v[42:43], v[44:45] offset1:8
	ds_write2_b64 v61, v[40:41], v[48:49] offset0:16 offset1:24
	ds_write2_b64 v62, v[34:35], v[36:37] offset0:32 offset1:40
	ds_write2_b64 v33, v[46:47], v[38:39] offset0:48 offset1:56
	s_andn2_b64 exec, exec, s[14:15]
	s_cbranch_execnz .LBB0_684
.LBB0_685:
	s_or_b64 exec, exec, s[12:13]
	v_mov_b32_e32 v30, v208
	s_waitcnt lgkmcnt(0)
	s_barrier
	s_nop 0
	v_cmp_gt_i32_e32 vcc, s21, v30
	s_and_saveexec_b64 s[12:13], vcc
	s_cbranch_execz .LBB0_688
	v_and_b32_e32 v31, 63, v30
	v_cvt_f32_ubyte0_e32 v3, v31
	v_mul_f32_e32 v2, 0x3c000000, v3
	v_mul_f32_e32 v6, 0x3b800000, v3
	v_mul_f32_e32 v3, 0x3b000000, v3
	v_cos_f32_e32 v24, v3
	v_sin_f32_e32 v3, v3
	v_cos_f32_e32 v5, v2
	v_sin_f32_e32 v2, v2
	v_cos_f32_e32 v4, v6
	v_sin_f32_e32 v7, v6
	v_mul_f32_e32 v26, 0x3f3504f3, v3
	v_mul_f32_e32 v22, 0x3f3504f3, v24
	v_fmamk_f32 v6, v2, 0x80000000, v5
	v_fmac_f32_e32 v2, 0, v5
	v_fmamk_f32 v8, v7, 0x80000000, v4
	v_fma_f32 v10, 0, v4, v7
	v_fma_f32 v12, v4, 0, -v7
	v_fmac_f32_e32 v4, 0, v7
	v_fmamk_f32 v14, v3, 0x80000000, v24
	v_fma_f32 v16, 0, v24, v3
	v_fma_f32 v18, v24, 0, -v3
	v_fma_f32 v20, 0, v3, v24
	v_fmac_f32_e32 v22, 0x3f3504f3, v3
	v_fma_f32 v25, v24, s71, -v26
	v_fma_f32 v24, v24, s70, -v26
	v_mov_b32_e32 v7, v6
	v_mov_b32_e32 v3, v2
	v_mov_b32_e32 v13, v12
	v_mov_b32_e32 v5, v4
	v_mov_b32_e32 v19, v18
	v_mov_b32_e32 v9, v8
	v_mov_b32_e32 v11, v10
	v_mov_b32_e32 v26, v25
	v_mov_b32_e32 v27, v25
	v_mov_b32_e32 v15, v14
	v_mov_b32_e32 v21, v20
	v_mov_b32_e32 v17, v16
	v_mov_b32_e32 v23, v22
	v_pk_mov_b32 v[28:29], v[24:25], v[24:25] op_sel:[1,0]
	v_lshlrev_b32_e32 v32, 3, v30
	s_mov_b64 s[14:15], 0
;     static __device__ __forceinline__ float sl(float g, float up) { return g * __builtin_amdgcn_rcpf(1.0f + __builtin_amdgcn_exp2f(-1.4426950408889634f * g)) * up; }
; __device__ __forceinline__ float2 cmul(float2 a, float2 b) { return make_float2(a.x * b.x - a.y * b.y, a.x * b.y + a.y * b.x); }
; #define tid ltid()
; template <int LR, bool INV>
; __device__ __forceinline__ void fft_stages(float2 (&x)[1 << LR], const int r, const int s) {
;   constexpr int R = 1 << LR;
; #pragma unroll
;   for (int st = 0; st < LR; ++st) {
;     const int hl = INV ? (1 << st) : (R >> (st + 1));
;     const float fb = (float)r * (0.5f / (float)(hl * s));
;     const float2 wb = make_float2(__builtin_amdgcn_cosf(fb), INV ? __builtin_amdgcn_sinf(fb) : -__builtin_amdgcn_sinf(fb));
; #pragma unroll
;     for (int m = 0; m < R; ++m) {
;       if (m & hl) continue;
;       const int k = m & (hl - 1); const int j = k * (8 / hl);
;       const float2 wc = make_float2(c16(j), INV ? s16(j) : -s16(j));
;       const float2 tw = cmul(wb, wc);
;       if (!INV) { const float2 p = x[m], q = x[m + hl]; x[m] = make_float2(p.x + q.x, p.y + q.y); x[m + hl] = cmul(make_float2(p.x - q.x, p.y - q.y), tw); }
;       else { const float2 p = x[m], q = cmul(x[m + hl], tw); x[m] = make_float2(p.x + q.x, p.y + q.y); x[m + hl] = make_float2(p.x - q.x, p.y - q.y); }
;     }
;   }
; }
; template <int LR, bool INV>
; __device__ __forceinline__ void fft_pass(float2* X, const int N, const int sl, const int tid) {
;   constexpr int R = 1 << LR;
;   const int s = 1 << sl;
;   for (int g = tid; g < (N >> LR); g += NTHR) {
;     const int r = g & (s - 1);
;     const int i0 = ((g >> sl) << (sl + LR)) + r;
;     float2 x[R];
; #pragma unroll
;     for (int m = 0; m < R; ++m) x[m] = X[PIDX(i0 + (m << sl))];
;     fft_stages<LR, INV>(x, r, s);
; #pragma unroll
;     for (int m = 0; m < R; ++m) X[PIDX(i0 + (m << sl))] = x[m];
;   }
.LBB0_687:
	v_and_or_b32 v33, v32, s53, v31
	v_ashrrev_i32_e32 v34, 4, v33
	v_lshl_add_u32 v35, v33, 3, 0
	v_or_b32_e32 v36, 64, v33
	v_or_b32_e32 v37, 0x80, v33
	v_or_b32_e32 v38, 0xc0, v33
	v_or_b32_e32 v39, 0x100, v33
	v_or_b32_e32 v40, 0x140, v33
	v_or_b32_e32 v41, 0x180, v33
	v_or_b32_e32 v33, 0x1c0, v33
	v_lshl_add_u32 v60, v34, 3, v35
	v_ashrrev_i32_e32 v34, 4, v36
	v_ashrrev_i32_e32 v36, 4, v37
	v_ashrrev_i32_e32 v37, 4, v38
	v_ashrrev_i32_e32 v38, 4, v39
	v_ashrrev_i32_e32 v39, 4, v40
	v_ashrrev_i32_e32 v40, 4, v41
	v_ashrrev_i32_e32 v33, 4, v33
	v_lshl_add_u32 v61, v34, 3, v35
	v_lshl_add_u32 v62, v36, 3, v35
	v_lshl_add_u32 v63, v37, 3, v35
	v_lshl_add_u32 v64, v38, 3, v35
	v_lshl_add_u32 v65, v39, 3, v35
	v_lshl_add_u32 v66, v40, 3, v35
	v_lshl_add_u32 v33, v33, 3, v35
	ds_read_b64 v[34:35], v60
	ds_read_b64 v[36:37], v61 offset:512
	ds_read_b64 v[38:39], v62 offset:1024
	ds_read_b64 v[40:41], v63 offset:1536
	ds_read_b64 v[42:43], v64 offset:2048
	ds_read_b64 v[44:45], v65 offset:2560
	ds_read_b64 v[46:47], v33 offset:3584
	ds_read_b64 v[48:49], v66 offset:3072
	s_waitcnt lgkmcnt(6)
	v_mul_f32_e32 v50, v36, v2
	v_mul_f32_e32 v51, v37, v3
	s_waitcnt lgkmcnt(4)
	v_mul_f32_e32 v52, v2, v40
	v_mul_f32_e32 v53, v3, v41
	s_waitcnt lgkmcnt(2)
	v_mul_f32_e32 v54, v2, v44
	v_mul_f32_e32 v55, v3, v45
	s_waitcnt lgkmcnt(1)
	v_mul_f32_e32 v56, v2, v46
	v_mul_f32_e32 v57, v3, v47
	v_fma_f32 v58, v36, v6, -v51
	v_fma_f32 v37, v37, v7, v50
	v_fma_f32 v50, v6, v40, -v53
	v_fma_f32 v41, v7, v41, v52
	v_fma_f32 v52, v6, v44, -v55
	v_fma_f32 v45, v7, v45, v54
	v_fma_f32 v54, v6, v46, -v57
	v_fma_f32 v47, v7, v47, v56
	v_mov_b32_e32 v51, v41
	v_mov_b32_e32 v55, v47
	v_mov_b32_e32 v53, v45
	v_sub_f32_e32 v40, v38, v50
	v_sub_f32_e32 v41, v39, v51
	s_waitcnt lgkmcnt(0)
	v_add_f32_e32 v46, v48, v54
	v_add_f32_e32 v47, v49, v55
	v_mov_b32_e32 v59, v37
	v_add_f32_e32 v44, v42, v52
	v_add_f32_e32 v45, v43, v53
	v_add_f32_e32 v38, v38, v50
	v_add_f32_e32 v39, v39, v51
	v_sub_f32_e32 v42, v42, v52
	v_sub_f32_e32 v43, v43, v53
	v_sub_f32_e32 v48, v48, v54
	v_sub_f32_e32 v49, v49, v55
	v_mul_f32_e32 v50, v4, v40
	v_mul_f32_e32 v51, v5, v41
	v_mul_f32_e32 v52, v10, v46
	v_mul_f32_e32 v53, v11, v47
	v_sub_f32_e32 v36, v34, v58
	v_sub_f32_e32 v37, v35, v59
	v_add_f32_e32 v34, v34, v58
	v_add_f32_e32 v35, v35, v59
	v_mul_f32_e32 v54, v10, v38
	v_mul_f32_e32 v55, v11, v39
	v_mul_f32_e32 v56, v4, v48
	v_mul_f32_e32 v57, v5, v49
	v_fma_f32 v58, v12, v40, -v51
	v_fma_f32 v41, v13, v41, v50
	v_fma_f32 v50, v8, v46, -v53
	v_fma_f32 v47, v9, v47, v52
	v_fma_f32 v52, v8, v38, -v55
	v_fma_f32 v39, v9, v39, v54
	v_fma_f32 v54, v12, v48, -v57
	v_fma_f32 v49, v13, v49, v56
	v_mov_b32_e32 v51, v47
	v_mov_b32_e32 v59, v41
	v_mov_b32_e32 v53, v39
	v_mov_b32_e32 v55, v49
	v_sub_f32_e32 v40, v44, v50
	v_sub_f32_e32 v41, v45, v51
	v_add_f32_e32 v44, v44, v50
	v_add_f32_e32 v45, v45, v51
	v_sub_f32_e32 v46, v34, v52
	v_sub_f32_e32 v47, v35, v53
	v_add_f32_e32 v34, v34, v52
	v_add_f32_e32 v35, v35, v53
	v_add_f32_e32 v48, v42, v54
	v_add_f32_e32 v49, v43, v55
	v_sub_f32_e32 v42, v42, v54
	v_sub_f32_e32 v43, v43, v55
	v_mul_f32_e32 v50, v20, v41
	v_mul_f32_e32 v51, v21, v40
	v_mul_f32_e32 v52, v16, v45
	v_mul_f32_e32 v53, v17, v44
	v_add_u32_e32 v30, 0x200, v30
	v_sub_f32_e32 v38, v36, v58
	v_sub_f32_e32 v39, v37, v59
	v_add_f32_e32 v36, v36, v58
	v_add_f32_e32 v37, v37, v59
	v_mul_f32_e32 v54, v22, v49
	v_mul_f32_e32 v55, v23, v48
	v_mul_f32_e32 v56, v28, v43
	v_mul_f32_e32 v57, v29, v43
	v_fma_f32 v58, v18, v40, -v50
	v_fma_f32 v41, v19, v41, v51
	v_fma_f32 v50, v14, v44, -v52
	v_fma_f32 v45, v15, v45, v53
	v_cmp_le_i32_e32 vcc, s21, v30
	v_fma_f32 v52, v26, v48, -v54
	v_fma_f32 v49, v27, v49, v55
	v_fma_f32 v54, v24, v42, -v56
	v_fma_f32 v43, v25, v42, v57
	v_mov_b32_e32 v51, v45
	v_add_u32_e32 v32, 0x1000, v32
	s_or_b64 s[14:15], vcc, s[14:15]
	v_mov_b32_e32 v59, v41
	v_mov_b32_e32 v53, v49
	v_mov_b32_e32 v55, v43
	v_add_f32_e32 v42, v34, v50
	v_add_f32_e32 v43, v35, v51
	v_add_f32_e32 v40, v46, v58
	v_add_f32_e32 v41, v47, v59
	v_add_f32_e32 v44, v36, v52
	v_add_f32_e32 v45, v37, v53
	v_add_f32_e32 v48, v38, v54
	v_add_f32_e32 v49, v39, v55
	v_sub_f32_e32 v34, v34, v50
	v_sub_f32_e32 v35, v35, v51
	v_sub_f32_e32 v36, v36, v52
	v_sub_f32_e32 v37, v37, v53
	v_sub_f32_e32 v46, v46, v58
	v_sub_f32_e32 v47, v47, v59
	v_sub_f32_e32 v38, v38, v54
	v_sub_f32_e32 v39, v39, v55
	ds_write_b64 v60, v[42:43]
	ds_write_b64 v61, v[44:45] offset:512
	ds_write_b64 v62, v[40:41] offset:1024
	ds_write_b64 v63, v[48:49] offset:1536
	ds_write_b64 v64, v[34:35] offset:2048
	ds_write_b64 v65, v[36:37] offset:2560
	ds_write_b64 v66, v[46:47] offset:3072
	ds_write_b64 v33, v[38:39] offset:3584
	s_andn2_b64 exec, exec, s[14:15]
	s_cbranch_execnz .LBB0_687
